# first K-tile pair of every GEMM tile peeled with C=0 MFMAs; separate accumulator clearing removed
# baseline (speedup 1.0000x reference)
; #define PG8_STAGE(bufoff, gbase, voff) do { _Pragma("unroll") for (int _i = 0; _i < 2; ++_i) \
;         __builtin_amdgcn_global_load_lds((const unsigned*)((const char*)(gbase) + (voff)[_i]), (PG8_LAS unsigned*)(lds + (bufoff) + ldsw + _i * 8192), 16, 0, 0); } while (0)
; #define PG8_LDA(dst, b, h) do { _Pragma("unroll") for (int m = 0; m < 4; ++m) _Pragma("unroll") for (int k = 0; k < 2; ++k) dst[m][k] = *(const PG8_LAS bf16x8*)(lds + PG8_SA(b, h) + aoff + m * 2048 + k * 1024); } while (0)
; #define PG8_LDB(dst, b, h) do { _Pragma("unroll") for (int n = 0; n < 2; ++n) _Pragma("unroll") for (int k = 0; k < 2; ++k) dst[n][k] = *(const PG8_LAS bf16x8*)(lds + PG8_SB(b, h) + boff + n * 2048 + k * 1024); } while (0)
; #define PG8_MMA(ai, bj, At, Bt) do { __builtin_amdgcn_s_setprio(1); _Pragma("unroll") for (int m = 0; m < 4; ++m) _Pragma("unroll") for (int n = 0; n < 2; ++n) _Pragma("unroll") for (int k = 0; k < 2; ++k) \
;         acc[ai][bj][m][n] = __builtin_amdgcn_mfma_f32_16x16x32_bf16(Bt[n][k], At[m][k], acc[ai][bj][m][n], 0, 0, 0); __builtin_amdgcn_s_setprio(0); } while (0)
; #define PG8_WAIT_V(n) asm volatile("s_waitcnt vmcnt(" #n ")" ::: "memory")
; #define PG8_BAR __builtin_amdgcn_s_barrier()
; template <class Epi, class Sched, bool ALIGN_EPI = false, bool SP2 = false>
; __device__ __forceinline__ void gemm_phase(PG8_LAS unsigned char* lds, const Gemm g, const Sched& S, const Epi& E) {
;     ...
;         for (int t = 0; t < nt; t += 2) {
;             const bool last = (t == nt - 2);
;             const char* a1 = cA + (size_t)(t + 1) * kstep;
;             const char* a2 = last ? nA : cA + (size_t)(t + 2) * kstep; const char* b2 = last ? nB : cB + (size_t)(t + 2) * kstep;
;             const char* a3 = a2 + kstep; const char* b3 = b2 + kstep;
;             if (last && has_next) S.a_ready(nxt);
;             if constexpr (SP2) {
;             PG8_LDB(B0, 0, 0); PG8_LDB(B1, 0, 1); PG8_SCHED; PG8_LDA(At, 0, 0); PG8_STAGE(PG8_SA(1, 1), a1 + hstep, voffA);
;             PG8_WAIT_V(8); PG8_WAIT_L(0); PG8_BAR; PG8_MMA(0, 0, At, B0); PG8_MMA(0, 1, At, B1); PG8_BAR; PG8_SCHED;
;             PG8_LDA(At, 0, 1); PG8_STAGE(PG8_SB(0, 0), b2, voffB); PG8_STAGE(PG8_SB(0, 1), b2 + hstep, voffB); PG8_STAGE(PG8_SA(0, 0), a2, voffA);
;             PG8_WAIT_V(8); PG8_WAIT_L(0); PG8_BAR; PG8_MMA(1, 0, At, B0); PG8_MMA(1, 1, At, B1); PG8_BAR; PG8_SCHED;
.LBB0_128:
	s_ashr_i32 s25, s24, 31
	s_lshl_b64 s[28:29], s[24:25], 20
	v_readlane_b32 s30, v254, 51
	v_readlane_b32 s31, v254, 52
	s_add_u32 s28, s30, s28
	s_addc_u32 s29, s31, s29
	s_and_b64 s[30:31], s[26:27], exec
	s_cselect_b32 s25, s29, s9
	s_cselect_b32 s35, s28, s8
	s_ashr_i32 s23, s22, 31
	s_lshl_b64 s[30:31], s[22:23], 20
	s_add_u32 s30, s94, s30
	s_addc_u32 s31, s95, s31
	s_and_b64 s[46:47], s[26:27], exec
	s_cselect_b32 s23, s31, s45
	s_cselect_b32 s43, s30, s44
	s_add_u32 s8, s8, 0x80080
	s_addc_u32 s9, s9, 0
	s_add_u32 s48, s44, 0x100
	s_addc_u32 s49, s45, 0
	s_mov_b32 s54, -2
	s_waitcnt lgkmcnt(0)
	ds_read_b128 v[96:99], v173
	ds_read_b128 v[100:103], v173 offset:1024
	ds_read_b128 v[104:107], v173 offset:2048
	ds_read_b128 v[112:115], v173 offset:3072
	ds_read_b128 v[178:181], v175
	ds_read_b128 v[182:185], v175 offset:1024
	ds_read_b128 v[186:189], v175 offset:2048
	ds_read_b128 v[190:193], v175 offset:3072
	s_add_u32 s44, s8, 0xfff80080
	s_addc_u32 s45, s9, -1
	s_cmp_eq_u32 s54, 28
	s_cselect_b32 s47, s25, s45
	s_cselect_b32 s46, s35, s44
	s_cselect_b32 s45, s23, s49
	s_cselect_b32 s44, s43, s48
	v_lshl_add_u64 v[160:161], s[8:9], 0, v[154:155]
	s_add_i32 m0, s63, 0xc000
	ds_read_b128 v[198:201], v177
	ds_read_b128 v[202:205], v177 offset:1024
	ds_read_b128 v[206:209], v177 offset:2048
	ds_read_b128 v[210:213], v177 offset:3072
	ds_read_b128 v[214:217], v177 offset:4096
	ds_read_b128 v[218:221], v177 offset:5120
	ds_read_b128 v[222:225], v177 offset:6144
	ds_read_b128 v[226:229], v177 offset:7168
	global_load_lds_dwordx4 v[160:161], off
	v_lshl_add_u64 v[160:161], s[8:9], 0, v[156:157]
	s_add_i32 m0, s63, 0xe000
	s_nop 0
	global_load_lds_dwordx4 v[160:161], off
	s_waitcnt vmcnt(8)
	s_waitcnt lgkmcnt(0)
	s_barrier
	s_setprio 1
	s_waitcnt lgkmcnt(0)
	v_mfma_f32_16x16x32_bf16 v[140:143], v[96:99], v[198:201], 0
	v_mfma_f32_16x16x32_bf16 v[132:135], v[104:107], v[198:201], 0
	v_mfma_f32_16x16x32_bf16 v[116:119], v[96:99], v[206:209], 0
	v_mfma_f32_16x16x32_bf16 v[124:127], v[104:107], v[206:209], 0
	v_mfma_f32_16x16x32_bf16 v[84:87], v[96:99], v[214:217], 0
	v_mfma_f32_16x16x32_bf16 v[92:95], v[104:107], v[214:217], 0
	v_mfma_f32_16x16x32_bf16 v[68:71], v[96:99], v[222:225], 0
	v_mfma_f32_16x16x32_bf16 v[76:79], v[104:107], v[222:225], 0
	v_mfma_f32_16x16x32_bf16 v[140:143], v[100:103], v[202:205], v[140:143]
	v_mfma_f32_16x16x32_bf16 v[132:135], v[112:115], v[202:205], v[132:135]
	v_mfma_f32_16x16x32_bf16 v[116:119], v[100:103], v[210:213], v[116:119]
	v_mfma_f32_16x16x32_bf16 v[124:127], v[112:115], v[210:213], v[124:127]
	v_mfma_f32_16x16x32_bf16 v[84:87], v[100:103], v[218:221], v[84:87]
	v_mfma_f32_16x16x32_bf16 v[92:95], v[112:115], v[218:221], v[92:95]
	v_mfma_f32_16x16x32_bf16 v[68:71], v[100:103], v[226:229], v[68:71]
	v_mfma_f32_16x16x32_bf16 v[76:79], v[112:115], v[226:229], v[76:79]
	s_setprio 0
	s_setprio 1
	v_mfma_f32_16x16x32_bf16 v[128:131], v[178:181], v[198:201], 0
	v_mfma_f32_16x16x32_bf16 v[136:139], v[186:189], v[198:201], 0
	v_mfma_f32_16x16x32_bf16 v[120:123], v[178:181], v[206:209], 0
	v_mfma_f32_16x16x32_bf16 v[108:111], v[186:189], v[206:209], 0
	v_mfma_f32_16x16x32_bf16 v[88:91], v[178:181], v[214:217], 0
	v_mfma_f32_16x16x32_bf16 v[80:83], v[186:189], v[214:217], 0
	v_mfma_f32_16x16x32_bf16 v[72:75], v[178:181], v[222:225], 0
	v_mfma_f32_16x16x32_bf16 v[64:67], v[186:189], v[222:225], 0
	v_mfma_f32_16x16x32_bf16 v[128:131], v[182:185], v[202:205], v[128:131]
	v_mfma_f32_16x16x32_bf16 v[136:139], v[190:193], v[202:205], v[136:139]
	v_mfma_f32_16x16x32_bf16 v[120:123], v[182:185], v[210:213], v[120:123]
	v_mfma_f32_16x16x32_bf16 v[108:111], v[190:193], v[210:213], v[108:111]
	v_mfma_f32_16x16x32_bf16 v[88:91], v[182:185], v[218:221], v[88:91]
	v_mfma_f32_16x16x32_bf16 v[80:83], v[190:193], v[218:221], v[80:83]
	v_mfma_f32_16x16x32_bf16 v[72:75], v[182:185], v[226:229], v[72:75]
	v_mfma_f32_16x16x32_bf16 v[64:67], v[190:193], v[226:229], v[64:67]
	s_setprio 0
	s_barrier
	s_add_i32 s55, s52, s62
	v_lshl_add_u64 v[160:161], s[44:45], 0, v[144:145]
	s_mov_b32 m0, s55
	ds_read_b128 v[198:201], v177 offset:16384
	ds_read_b128 v[202:205], v177 offset:17408
	ds_read_b128 v[206:209], v177 offset:18432
	ds_read_b128 v[210:213], v177 offset:19456
	ds_read_b128 v[214:217], v177 offset:20480
	ds_read_b128 v[218:221], v177 offset:21504
	ds_read_b128 v[222:225], v177 offset:22528
	ds_read_b128 v[226:229], v177 offset:23552
	global_load_lds_dwordx4 v[160:161], off
	s_add_i32 m0, s55, 0x2000
	s_add_u32 s56, s44, 0x80000
	v_lshl_add_u64 v[164:165], s[44:45], 0, v[146:147]
	s_addc_u32 s57, s45, 0
	s_add_i32 s55, s53, s62
	global_load_lds_dwordx4 v[164:165], off
	v_lshl_add_u64 v[170:171], s[56:57], 0, v[144:145]
	s_mov_b32 m0, s55
	v_lshl_add_u64 v[194:195], s[46:47], 0, v[146:147]
	global_load_lds_dwordx4 v[170:171], off
	v_lshl_add_u64 v[170:171], s[56:57], 0, v[146:147]
	s_add_i32 m0, s55, 0x2000
	s_nop 0
	global_load_lds_dwordx4 v[170:171], off
	v_lshl_add_u64 v[170:171], s[46:47], 0, v[144:145]
	s_mov_b32 m0, s63
	s_nop 0
	global_load_lds_dwordx4 v[170:171], off
	s_mov_b32 m0, s64
	s_nop 0
	global_load_lds_dwordx4 v[194:195], off
	s_waitcnt vmcnt(8)
	s_waitcnt lgkmcnt(0)
	s_barrier
; #define PG8_STAGE(bufoff, gbase, voff) do { _Pragma("unroll") for (int _i = 0; _i < 2; ++_i) \
;         __builtin_amdgcn_global_load_lds((const unsigned*)((const char*)(gbase) + (voff)[_i]), (PG8_LAS unsigned*)(lds + (bufoff) + ldsw + _i * 8192), 16, 0, 0); } while (0)
; #define PG8_LDA(dst, b, h) do { _Pragma("unroll") for (int m = 0; m < 4; ++m) _Pragma("unroll") for (int k = 0; k < 2; ++k) dst[m][k] = *(const PG8_LAS bf16x8*)(lds + PG8_SA(b, h) + aoff + m * 2048 + k * 1024); } while (0)
; #define PG8_LDB(dst, b, h) do { _Pragma("unroll") for (int n = 0; n < 2; ++n) _Pragma("unroll") for (int k = 0; k < 2; ++k) dst[n][k] = *(const PG8_LAS bf16x8*)(lds + PG8_SB(b, h) + boff + n * 2048 + k * 1024); } while (0)
; #define PG8_MMA(ai, bj, At, Bt) do { __builtin_amdgcn_s_setprio(1); _Pragma("unroll") for (int m = 0; m < 4; ++m) _Pragma("unroll") for (int n = 0; n < 2; ++n) _Pragma("unroll") for (int k = 0; k < 2; ++k) \
;         acc[ai][bj][m][n] = __builtin_amdgcn_mfma_f32_16x16x32_bf16(Bt[n][k], At[m][k], acc[ai][bj][m][n], 0, 0, 0); __builtin_amdgcn_s_setprio(0); } while (0)
; #define PG8_WAIT_V(n) asm volatile("s_waitcnt vmcnt(" #n ")" ::: "memory")
; #define PG8_WAIT_L(n) asm volatile("s_waitcnt lgkmcnt(" #n ")" ::: "memory")
; #define PG8_BAR __builtin_amdgcn_s_barrier()
; #define PG8_SCHED __builtin_amdgcn_sched_barrier(0)
; template <class Epi, class Sched, bool ALIGN_EPI = false, bool SP2 = false>
; __device__ __forceinline__ void gemm_phase(PG8_LAS unsigned char* lds, const Gemm g, const Sched& S, const Epi& E) {
;     ...
;             PG8_WAIT_V(8); PG8_WAIT_L(0); PG8_BAR; PG8_MMA(1, 0, At, B0); PG8_MMA(1, 1, At, B1); PG8_BAR; PG8_SCHED;
;             PG8_LDB(B0, 1, 0); PG8_LDB(B1, 1, 1); PG8_SCHED; PG8_LDA(At, 1, 0); PG8_STAGE(PG8_SA(0, 1), a2 + hstep, voffA);
;             PG8_WAIT_V(8); PG8_WAIT_L(0); PG8_BAR; PG8_MMA(0, 0, At, B0); PG8_MMA(0, 1, At, B1); PG8_BAR; PG8_SCHED;
	s_setprio 1
	s_waitcnt lgkmcnt(0)
	v_mfma_f32_16x16x32_bf16 v[60:63], v[96:99], v[198:201], 0
	v_mfma_f32_16x16x32_bf16 v[52:55], v[104:107], v[198:201], 0
	v_mfma_f32_16x16x32_bf16 v[36:39], v[96:99], v[206:209], 0
	v_mfma_f32_16x16x32_bf16 v[44:47], v[104:107], v[206:209], 0
	v_mfma_f32_16x16x32_bf16 v[20:23], v[96:99], v[214:217], 0
	v_mfma_f32_16x16x32_bf16 v[28:31], v[104:107], v[214:217], 0
	v_mfma_f32_16x16x32_bf16 v[4:7], v[96:99], v[222:225], 0
	v_mfma_f32_16x16x32_bf16 v[12:15], v[104:107], v[222:225], 0
	v_mfma_f32_16x16x32_bf16 v[60:63], v[100:103], v[202:205], v[60:63]
	v_mfma_f32_16x16x32_bf16 v[52:55], v[112:115], v[202:205], v[52:55]
	v_mfma_f32_16x16x32_bf16 v[36:39], v[100:103], v[210:213], v[36:39]
	v_mfma_f32_16x16x32_bf16 v[44:47], v[112:115], v[210:213], v[44:47]
	v_mfma_f32_16x16x32_bf16 v[20:23], v[100:103], v[218:221], v[20:23]
	v_mfma_f32_16x16x32_bf16 v[28:31], v[112:115], v[218:221], v[28:31]
	v_mfma_f32_16x16x32_bf16 v[4:7], v[100:103], v[226:229], v[4:7]
	v_mfma_f32_16x16x32_bf16 v[12:15], v[112:115], v[226:229], v[12:15]
	s_setprio 0
	s_setprio 1
	v_mfma_f32_16x16x32_bf16 v[48:51], v[178:181], v[198:201], 0
	v_mfma_f32_16x16x32_bf16 v[56:59], v[186:189], v[198:201], 0
	v_mfma_f32_16x16x32_bf16 v[40:43], v[178:181], v[206:209], 0
	v_mfma_f32_16x16x32_bf16 v[32:35], v[186:189], v[206:209], 0
	v_mfma_f32_16x16x32_bf16 v[24:27], v[178:181], v[214:217], 0
	v_mfma_f32_16x16x32_bf16 v[16:19], v[186:189], v[214:217], 0
	v_mfma_f32_16x16x32_bf16 v[8:11], v[178:181], v[222:225], 0
	v_mfma_f32_16x16x32_bf16 v[0:3], v[186:189], v[222:225], 0
	v_mfma_f32_16x16x32_bf16 v[48:51], v[182:185], v[202:205], v[48:51]
	v_mfma_f32_16x16x32_bf16 v[56:59], v[190:193], v[202:205], v[56:59]
	v_mfma_f32_16x16x32_bf16 v[40:43], v[182:185], v[210:213], v[40:43]
	v_mfma_f32_16x16x32_bf16 v[32:35], v[190:193], v[210:213], v[32:35]
	v_mfma_f32_16x16x32_bf16 v[24:27], v[182:185], v[218:221], v[24:27]
	v_mfma_f32_16x16x32_bf16 v[16:19], v[190:193], v[218:221], v[16:19]
	v_mfma_f32_16x16x32_bf16 v[8:11], v[182:185], v[226:229], v[8:11]
	v_mfma_f32_16x16x32_bf16 v[0:3], v[190:193], v[226:229], v[0:3]
	s_setprio 0
	s_barrier
	s_add_i32 s55, 0, 0x18000
	s_add_i32 s56, 0, 0x1c000
	v_add_u32_e32 v112, s55, v167
	v_add_u32_e32 v162, s56, v167
	ds_read_b128 v[96:99], v112
	ds_read_b128 v[100:103], v112 offset:1024
	ds_read_b128 v[104:107], v112 offset:2048
	ds_read_b128 v[112:115], v112 offset:3072
	ds_read_b128 v[178:181], v162
	ds_read_b128 v[182:185], v162 offset:1024
	ds_read_b128 v[186:189], v162 offset:2048
	ds_read_b128 v[190:193], v162 offset:3072
	s_add_u32 s46, s46, 0x80000
	s_addc_u32 s47, s47, 0
	s_mov_b32 m0, s65
	v_lshl_add_u64 v[230:231], s[46:47], 0, v[144:145]
	ds_read_b128 v[198:201], v177 offset:32768
	ds_read_b128 v[202:205], v177 offset:33792
	ds_read_b128 v[206:209], v177 offset:34816
	ds_read_b128 v[210:213], v177 offset:35840
	ds_read_b128 v[214:217], v177 offset:36864
	ds_read_b128 v[218:221], v177 offset:37888
	ds_read_b128 v[222:225], v177 offset:38912
	ds_read_b128 v[226:229], v177 offset:39936
	global_load_lds_dwordx4 v[230:231], off
	v_lshl_add_u64 v[230:231], s[46:47], 0, v[146:147]
	s_mov_b32 m0, s66
	s_nop 0
	global_load_lds_dwordx4 v[230:231], off
	s_waitcnt vmcnt(8)
	s_waitcnt lgkmcnt(0)
	s_barrier
	s_setprio 1
	s_waitcnt lgkmcnt(0)
	v_mfma_f32_16x16x32_bf16 v[140:143], v[96:99], v[198:201], v[140:143]
	v_mfma_f32_16x16x32_bf16 v[132:135], v[104:107], v[198:201], v[132:135]
	v_mfma_f32_16x16x32_bf16 v[116:119], v[96:99], v[206:209], v[116:119]
	v_mfma_f32_16x16x32_bf16 v[124:127], v[104:107], v[206:209], v[124:127]
	v_mfma_f32_16x16x32_bf16 v[84:87], v[96:99], v[214:217], v[84:87]
	v_mfma_f32_16x16x32_bf16 v[92:95], v[104:107], v[214:217], v[92:95]
	v_mfma_f32_16x16x32_bf16 v[68:71], v[96:99], v[222:225], v[68:71]
	v_mfma_f32_16x16x32_bf16 v[76:79], v[104:107], v[222:225], v[76:79]
	v_mfma_f32_16x16x32_bf16 v[140:143], v[100:103], v[202:205], v[140:143]
	v_mfma_f32_16x16x32_bf16 v[132:135], v[112:115], v[202:205], v[132:135]
	v_mfma_f32_16x16x32_bf16 v[116:119], v[100:103], v[210:213], v[116:119]
	v_mfma_f32_16x16x32_bf16 v[124:127], v[112:115], v[210:213], v[124:127]
	v_mfma_f32_16x16x32_bf16 v[84:87], v[100:103], v[218:221], v[84:87]
	v_mfma_f32_16x16x32_bf16 v[92:95], v[112:115], v[218:221], v[92:95]
	v_mfma_f32_16x16x32_bf16 v[68:71], v[100:103], v[226:229], v[68:71]
	v_mfma_f32_16x16x32_bf16 v[76:79], v[112:115], v[226:229], v[76:79]
	s_setprio 0
	s_setprio 1
	v_mfma_f32_16x16x32_bf16 v[128:131], v[178:181], v[198:201], v[128:131]
	v_mfma_f32_16x16x32_bf16 v[136:139], v[186:189], v[198:201], v[136:139]
	v_mfma_f32_16x16x32_bf16 v[120:123], v[178:181], v[206:209], v[120:123]
	v_mfma_f32_16x16x32_bf16 v[108:111], v[186:189], v[206:209], v[108:111]
	v_mfma_f32_16x16x32_bf16 v[88:91], v[178:181], v[214:217], v[88:91]
	v_mfma_f32_16x16x32_bf16 v[80:83], v[186:189], v[214:217], v[80:83]
	v_mfma_f32_16x16x32_bf16 v[72:75], v[178:181], v[222:225], v[72:75]
	v_mfma_f32_16x16x32_bf16 v[64:67], v[186:189], v[222:225], v[64:67]
	v_mfma_f32_16x16x32_bf16 v[128:131], v[182:185], v[202:205], v[128:131]
	v_mfma_f32_16x16x32_bf16 v[136:139], v[190:193], v[202:205], v[136:139]
	v_mfma_f32_16x16x32_bf16 v[120:123], v[182:185], v[210:213], v[120:123]
	v_mfma_f32_16x16x32_bf16 v[108:111], v[190:193], v[210:213], v[108:111]
	v_mfma_f32_16x16x32_bf16 v[88:91], v[182:185], v[218:221], v[88:91]
	v_mfma_f32_16x16x32_bf16 v[80:83], v[190:193], v[218:221], v[80:83]
	v_mfma_f32_16x16x32_bf16 v[72:75], v[182:185], v[226:229], v[72:75]
	v_mfma_f32_16x16x32_bf16 v[64:67], v[190:193], v[226:229], v[64:67]
	s_setprio 0
	s_barrier
; #define PG8_STAGE(bufoff, gbase, voff) do { _Pragma("unroll") for (int _i = 0; _i < 2; ++_i) \
;         __builtin_amdgcn_global_load_lds((const unsigned*)((const char*)(gbase) + (voff)[_i]), (PG8_LAS unsigned*)(lds + (bufoff) + ldsw + _i * 8192), 16, 0, 0); } while (0)
; #define PG8_LDA(dst, b, h) do { _Pragma("unroll") for (int m = 0; m < 4; ++m) _Pragma("unroll") for (int k = 0; k < 2; ++k) dst[m][k] = *(const PG8_LAS bf16x8*)(lds + PG8_SA(b, h) + aoff + m * 2048 + k * 1024); } while (0)
; #define PG8_MMA(ai, bj, At, Bt) do { __builtin_amdgcn_s_setprio(1); _Pragma("unroll") for (int m = 0; m < 4; ++m) _Pragma("unroll") for (int n = 0; n < 2; ++n) _Pragma("unroll") for (int k = 0; k < 2; ++k) \
;         acc[ai][bj][m][n] = __builtin_amdgcn_mfma_f32_16x16x32_bf16(Bt[n][k], At[m][k], acc[ai][bj][m][n], 0, 0, 0); __builtin_amdgcn_s_setprio(0); } while (0)
; #define PG8_WAIT_V(n) asm volatile("s_waitcnt vmcnt(" #n ")" ::: "memory")
; #define PG8_WAIT_L(n) asm volatile("s_waitcnt lgkmcnt(" #n ")" ::: "memory")
; #define PG8_BAR __builtin_amdgcn_s_barrier()
; #define PG8_SCHED __builtin_amdgcn_sched_barrier(0)
; template <class Epi, class Sched, bool ALIGN_EPI = false, bool SP2 = false>
; __device__ __forceinline__ void gemm_phase(PG8_LAS unsigned char* lds, const Gemm g, const Sched& S, const Epi& E) {
;     ...
;             PG8_LDA(At, 1, 1); PG8_STAGE(PG8_SB(1, 0), b3, voffB); PG8_STAGE(PG8_SB(1, 1), b3 + hstep, voffB); PG8_STAGE(PG8_SA(1, 0), a3, voffA);
;             PG8_WAIT_V(8); PG8_WAIT_L(0); PG8_BAR; PG8_MMA(1, 0, At, B0); PG8_MMA(1, 1, At, B1); PG8_BAR; PG8_SCHED;
	s_add_i32 s46, s55, s62
	v_lshl_add_u64 v[160:161], v[160:161], 0, s[12:13]
	s_mov_b32 m0, s46
	ds_read_b128 v[198:201], v177 offset:49152
	ds_read_b128 v[202:205], v177 offset:50176
	ds_read_b128 v[206:209], v177 offset:51200
	ds_read_b128 v[210:213], v177 offset:52224
	ds_read_b128 v[214:217], v177 offset:53248
	ds_read_b128 v[218:221], v177 offset:54272
	ds_read_b128 v[222:225], v177 offset:55296
	ds_read_b128 v[226:229], v177 offset:56320
	global_load_lds_dwordx4 v[160:161], off
	s_add_i32 m0, s46, 0x2000
	s_add_u32 s44, s44, 0x80080
	v_lshl_add_u64 v[160:161], v[164:165], 0, s[12:13]
	s_addc_u32 s45, s45, 0
	s_add_i32 s46, s56, s62
	global_load_lds_dwordx4 v[160:161], off
	v_lshl_add_u64 v[160:161], s[44:45], 0, v[144:145]
	s_mov_b32 m0, s46
	s_nop 0
	global_load_lds_dwordx4 v[160:161], off
	v_lshl_add_u64 v[160:161], s[44:45], 0, v[146:147]
	s_add_i32 m0, s46, 0x2000
	s_nop 0
	global_load_lds_dwordx4 v[160:161], off
	v_lshl_add_u64 v[160:161], v[170:171], 0, s[12:13]
	s_mov_b32 m0, s68
	s_nop 0
	global_load_lds_dwordx4 v[160:161], off
	v_lshl_add_u64 v[160:161], v[194:195], 0, s[12:13]
	s_mov_b32 m0, s69
	s_nop 0
	global_load_lds_dwordx4 v[160:161], off
	s_waitcnt vmcnt(8)
	s_waitcnt lgkmcnt(0)
	s_barrier
	s_setprio 1
	s_waitcnt lgkmcnt(0)
	v_mfma_f32_16x16x32_bf16 v[60:63], v[96:99], v[198:201], v[60:63]
	v_mfma_f32_16x16x32_bf16 v[52:55], v[104:107], v[198:201], v[52:55]
	v_mfma_f32_16x16x32_bf16 v[36:39], v[96:99], v[206:209], v[36:39]
	v_mfma_f32_16x16x32_bf16 v[44:47], v[104:107], v[206:209], v[44:47]
	v_mfma_f32_16x16x32_bf16 v[20:23], v[96:99], v[214:217], v[20:23]
	v_mfma_f32_16x16x32_bf16 v[28:31], v[104:107], v[214:217], v[28:31]
	v_mfma_f32_16x16x32_bf16 v[4:7], v[96:99], v[222:225], v[4:7]
	v_mfma_f32_16x16x32_bf16 v[12:15], v[104:107], v[222:225], v[12:15]
	v_mfma_f32_16x16x32_bf16 v[60:63], v[100:103], v[202:205], v[60:63]
	v_mfma_f32_16x16x32_bf16 v[52:55], v[112:115], v[202:205], v[52:55]
	v_mfma_f32_16x16x32_bf16 v[36:39], v[100:103], v[210:213], v[36:39]
	v_mfma_f32_16x16x32_bf16 v[44:47], v[112:115], v[210:213], v[44:47]
	v_mfma_f32_16x16x32_bf16 v[20:23], v[100:103], v[218:221], v[20:23]
	v_mfma_f32_16x16x32_bf16 v[28:31], v[112:115], v[218:221], v[28:31]
	v_mfma_f32_16x16x32_bf16 v[4:7], v[100:103], v[226:229], v[4:7]
	v_mfma_f32_16x16x32_bf16 v[12:15], v[112:115], v[226:229], v[12:15]
	s_setprio 0
	s_setprio 1
	v_mfma_f32_16x16x32_bf16 v[48:51], v[178:181], v[198:201], v[48:51]
	v_mfma_f32_16x16x32_bf16 v[56:59], v[186:189], v[198:201], v[56:59]
	v_mfma_f32_16x16x32_bf16 v[40:43], v[178:181], v[206:209], v[40:43]
	v_mfma_f32_16x16x32_bf16 v[32:35], v[186:189], v[206:209], v[32:35]
	v_mfma_f32_16x16x32_bf16 v[24:27], v[178:181], v[214:217], v[24:27]
	v_mfma_f32_16x16x32_bf16 v[16:19], v[186:189], v[214:217], v[16:19]
	v_mfma_f32_16x16x32_bf16 v[8:11], v[178:181], v[222:225], v[8:11]
	v_mfma_f32_16x16x32_bf16 v[0:3], v[186:189], v[222:225], v[0:3]
	v_mfma_f32_16x16x32_bf16 v[48:51], v[182:185], v[202:205], v[48:51]
	v_mfma_f32_16x16x32_bf16 v[56:59], v[190:193], v[202:205], v[56:59]
	v_mfma_f32_16x16x32_bf16 v[40:43], v[182:185], v[210:213], v[40:43]
	v_mfma_f32_16x16x32_bf16 v[32:35], v[190:193], v[210:213], v[32:35]
	v_mfma_f32_16x16x32_bf16 v[24:27], v[182:185], v[218:221], v[24:27]
	v_mfma_f32_16x16x32_bf16 v[16:19], v[190:193], v[218:221], v[16:19]
	v_mfma_f32_16x16x32_bf16 v[8:11], v[182:185], v[226:229], v[8:11]
	v_mfma_f32_16x16x32_bf16 v[0:3], v[190:193], v[226:229], v[0:3]
	s_setprio 0
	s_barrier
	s_add_i32 s54, s54, 2
	s_add_u32 s8, s8, 0x100
	s_addc_u32 s9, s9, 0
	s_add_u32 s48, s48, 0x100
	s_addc_u32 s49, s49, 0

; #define PG8_STAGE(bufoff, gbase, voff) do { _Pragma("unroll") for (int _i = 0; _i < 2; ++_i) \
;         __builtin_amdgcn_global_load_lds((const unsigned*)((const char*)(gbase) + (voff)[_i]), (PG8_LAS unsigned*)(lds + (bufoff) + ldsw + _i * 8192), 16, 0, 0); } while (0)
; #define PG8_LDA(dst, b, h) do { _Pragma("unroll") for (int m = 0; m < 4; ++m) _Pragma("unroll") for (int k = 0; k < 2; ++k) dst[m][k] = *(const PG8_LAS bf16x8*)(lds + PG8_SA(b, h) + aoff + m * 2048 + k * 1024); } while (0)
; #define PG8_LDB(dst, b, h) do { _Pragma("unroll") for (int n = 0; n < 2; ++n) _Pragma("unroll") for (int k = 0; k < 2; ++k) dst[n][k] = *(const PG8_LAS bf16x8*)(lds + PG8_SB(b, h) + boff + n * 2048 + k * 1024); } while (0)
; #define PG8_MMA(ai, bj, At, Bt) do { __builtin_amdgcn_s_setprio(1); _Pragma("unroll") for (int m = 0; m < 4; ++m) _Pragma("unroll") for (int n = 0; n < 2; ++n) _Pragma("unroll") for (int k = 0; k < 2; ++k) \
;         acc[ai][bj][m][n] = __builtin_amdgcn_mfma_f32_16x16x32_bf16(Bt[n][k], At[m][k], acc[ai][bj][m][n], 0, 0, 0); __builtin_amdgcn_s_setprio(0); } while (0)
; #define PG8_WAIT_V(n) asm volatile("s_waitcnt vmcnt(" #n ")" ::: "memory")
; #define PG8_BAR __builtin_amdgcn_s_barrier()
; template <class Epi, class Sched, bool ALIGN_EPI = false, bool SP2 = false>
; __device__ __forceinline__ void gemm_phase(PG8_LAS unsigned char* lds, const Gemm g, const Sched& S, const Epi& E) {
;     ...
;         for (int t = 0; t < nt; t += 2) {
;             const bool last = (t == nt - 2);
;             const char* a1 = cA + (size_t)(t + 1) * kstep;
;             const char* a2 = last ? nA : cA + (size_t)(t + 2) * kstep; const char* b2 = last ? nB : cB + (size_t)(t + 2) * kstep;
;             const char* a3 = a2 + kstep; const char* b3 = b2 + kstep;
;             if (last && has_next) S.a_ready(nxt);
;             if constexpr (SP2) {
;             PG8_LDB(B0, 0, 0); PG8_LDB(B1, 0, 1); PG8_SCHED; PG8_LDA(At, 0, 0); PG8_STAGE(PG8_SA(1, 1), a1 + hstep, voffA);
;             PG8_WAIT_V(8); PG8_WAIT_L(0); PG8_BAR; PG8_MMA(0, 0, At, B0); PG8_MMA(0, 1, At, B1); PG8_BAR; PG8_SCHED;
;             PG8_LDA(At, 0, 1); PG8_STAGE(PG8_SB(0, 0), b2, voffB); PG8_STAGE(PG8_SB(0, 1), b2 + hstep, voffB); PG8_STAGE(PG8_SA(0, 0), a2, voffA);
;             PG8_WAIT_V(8); PG8_WAIT_L(0); PG8_BAR; PG8_MMA(1, 0, At, B0); PG8_MMA(1, 1, At, B1); PG8_BAR; PG8_SCHED;
.LBB0_306:
	s_ashr_i32 s21, s20, 31
	s_lshl_b64 s[22:23], s[20:21], 20
	s_add_u32 s22, s60, s22
	s_addc_u32 s23, s61, s23
	s_and_b64 s[24:25], s[4:5], exec
	s_cselect_b32 s7, s23, s27
	s_cselect_b32 s21, s22, s26
	s_ashr_i32 s19, s18, 31
	s_lshl_b64 s[24:25], s[18:19], 20
	s_add_u32 s24, s68, s24
	s_addc_u32 s25, s69, s25
	s_and_b64 s[30:31], s[4:5], exec
	s_cselect_b32 s19, s25, s29
	s_cselect_b32 s33, s24, s28
	s_add_u32 s26, s26, 0x80080
	s_addc_u32 s27, s27, 0
	s_add_u32 s48, s28, 0x100
	s_addc_u32 s49, s29, 0
	s_mov_b32 s50, -2
	s_waitcnt lgkmcnt(0)
	s_waitcnt lgkmcnt(0)
	ds_read_b128 v[128:131], v181
	ds_read_b128 v[132:135], v181 offset:1024
	ds_read_b128 v[136:139], v181 offset:2048
	ds_read_b128 v[140:143], v181 offset:3072
	ds_read_b128 v[144:147], v182
	ds_read_b128 v[148:151], v182 offset:1024
	ds_read_b128 v[168:171], v182 offset:2048
	ds_read_b128 v[172:175], v182 offset:3072
	s_add_u32 s28, s26, 0xfff80080
	s_addc_u32 s29, s27, -1
	s_cmp_eq_u32 s50, 28
	s_cselect_b32 s31, s7, s29
	s_cselect_b32 s30, s21, s28
	s_cselect_b32 s29, s19, s49
	s_cselect_b32 s28, s33, s48
	v_lshl_add_u64 v[176:177], s[26:27], 0, v[160:161]
	s_add_i32 m0, s35, 0xc000
	ds_read_b128 v[186:189], v183
	ds_read_b128 v[190:193], v183 offset:1024
	ds_read_b128 v[198:201], v183 offset:2048
	ds_read_b128 v[202:205], v183 offset:3072
	ds_read_b128 v[206:209], v183 offset:4096
	ds_read_b128 v[210:213], v183 offset:5120
	ds_read_b128 v[214:217], v183 offset:6144
	ds_read_b128 v[218:221], v183 offset:7168
	global_load_lds_dwordx4 v[176:177], off
	v_lshl_add_u64 v[176:177], s[26:27], 0, v[162:163]
	s_add_i32 m0, s35, 0xe000
	s_nop 0
	global_load_lds_dwordx4 v[176:177], off
	s_waitcnt vmcnt(8)
	s_waitcnt lgkmcnt(0)
	s_barrier
	s_setprio 1
	s_waitcnt lgkmcnt(0)
	v_mfma_f32_16x16x32_bf16 v[124:127], v[128:131], v[186:189], 0
	v_mfma_f32_16x16x32_bf16 v[120:123], v[136:139], v[186:189], 0
	v_mfma_f32_16x16x32_bf16 v[104:107], v[128:131], v[198:201], 0
	v_mfma_f32_16x16x32_bf16 v[108:111], v[136:139], v[198:201], 0
	v_mfma_f32_16x16x32_bf16 v[88:91], v[128:131], v[206:209], 0
	v_mfma_f32_16x16x32_bf16 v[92:95], v[136:139], v[206:209], 0
	v_mfma_f32_16x16x32_bf16 v[72:75], v[128:131], v[214:217], 0
	v_mfma_f32_16x16x32_bf16 v[76:79], v[136:139], v[214:217], 0
	v_mfma_f32_16x16x32_bf16 v[124:127], v[132:135], v[190:193], v[124:127]
	v_mfma_f32_16x16x32_bf16 v[120:123], v[140:143], v[190:193], v[120:123]
	v_mfma_f32_16x16x32_bf16 v[104:107], v[132:135], v[202:205], v[104:107]
	v_mfma_f32_16x16x32_bf16 v[108:111], v[140:143], v[202:205], v[108:111]
	v_mfma_f32_16x16x32_bf16 v[88:91], v[132:135], v[210:213], v[88:91]
	v_mfma_f32_16x16x32_bf16 v[92:95], v[140:143], v[210:213], v[92:95]
	v_mfma_f32_16x16x32_bf16 v[72:75], v[132:135], v[218:221], v[72:75]
	v_mfma_f32_16x16x32_bf16 v[76:79], v[140:143], v[218:221], v[76:79]
	s_setprio 0
	s_setprio 1
	v_mfma_f32_16x16x32_bf16 v[116:119], v[144:147], v[186:189], 0
	v_mfma_f32_16x16x32_bf16 v[112:115], v[168:171], v[186:189], 0
	v_mfma_f32_16x16x32_bf16 v[100:103], v[144:147], v[198:201], 0
	v_mfma_f32_16x16x32_bf16 v[96:99], v[168:171], v[198:201], 0
	v_mfma_f32_16x16x32_bf16 v[84:87], v[144:147], v[206:209], 0
	v_mfma_f32_16x16x32_bf16 v[80:83], v[168:171], v[206:209], 0
	v_mfma_f32_16x16x32_bf16 v[68:71], v[144:147], v[214:217], 0
	v_mfma_f32_16x16x32_bf16 v[64:67], v[168:171], v[214:217], 0
	v_mfma_f32_16x16x32_bf16 v[116:119], v[148:151], v[190:193], v[116:119]
	v_mfma_f32_16x16x32_bf16 v[112:115], v[172:175], v[190:193], v[112:115]
	v_mfma_f32_16x16x32_bf16 v[100:103], v[148:151], v[202:205], v[100:103]
	v_mfma_f32_16x16x32_bf16 v[96:99], v[172:175], v[202:205], v[96:99]
	v_mfma_f32_16x16x32_bf16 v[84:87], v[148:151], v[210:213], v[84:87]
	v_mfma_f32_16x16x32_bf16 v[80:83], v[172:175], v[210:213], v[80:83]
	v_mfma_f32_16x16x32_bf16 v[68:71], v[148:151], v[218:221], v[68:71]
	v_mfma_f32_16x16x32_bf16 v[64:67], v[172:175], v[218:221], v[64:67]
	s_setprio 0
	s_barrier
	s_add_i32 s51, s62, s34
	v_lshl_add_u64 v[176:177], s[28:29], 0, v[154:155]
	s_mov_b32 m0, s51
	ds_read_b128 v[186:189], v183 offset:16384
	ds_read_b128 v[190:193], v183 offset:17408
	ds_read_b128 v[198:201], v183 offset:18432
	ds_read_b128 v[202:205], v183 offset:19456
	ds_read_b128 v[206:209], v183 offset:20480
	ds_read_b128 v[210:213], v183 offset:21504
	ds_read_b128 v[214:217], v183 offset:22528
	ds_read_b128 v[218:221], v183 offset:23552
	global_load_lds_dwordx4 v[176:177], off
	s_add_i32 m0, s51, 0x2000
	s_add_u32 s52, s28, 0x80000
	v_lshl_add_u64 v[194:195], s[28:29], 0, v[158:159]
	s_addc_u32 s53, s29, 0
	s_add_i32 s51, s63, s34
	global_load_lds_dwordx4 v[194:195], off
	v_lshl_add_u64 v[222:223], s[52:53], 0, v[154:155]
	s_mov_b32 m0, s51
	v_lshl_add_u64 v[224:225], s[30:31], 0, v[156:157]
	global_load_lds_dwordx4 v[222:223], off
	v_lshl_add_u64 v[222:223], s[52:53], 0, v[158:159]
	s_add_i32 m0, s51, 0x2000
	s_nop 0
	global_load_lds_dwordx4 v[222:223], off
	v_lshl_add_u64 v[222:223], s[30:31], 0, v[152:153]
	s_mov_b32 m0, s35
	s_nop 0
	global_load_lds_dwordx4 v[222:223], off
	s_mov_b32 m0, s37
	s_nop 0
	global_load_lds_dwordx4 v[224:225], off
	s_waitcnt vmcnt(8)
	s_waitcnt lgkmcnt(0)
	s_barrier
; #define PG8_STAGE(bufoff, gbase, voff) do { _Pragma("unroll") for (int _i = 0; _i < 2; ++_i) \
;         __builtin_amdgcn_global_load_lds((const unsigned*)((const char*)(gbase) + (voff)[_i]), (PG8_LAS unsigned*)(lds + (bufoff) + ldsw + _i * 8192), 16, 0, 0); } while (0)
; #define PG8_LDA(dst, b, h) do { _Pragma("unroll") for (int m = 0; m < 4; ++m) _Pragma("unroll") for (int k = 0; k < 2; ++k) dst[m][k] = *(const PG8_LAS bf16x8*)(lds + PG8_SA(b, h) + aoff + m * 2048 + k * 1024); } while (0)
; #define PG8_LDB(dst, b, h) do { _Pragma("unroll") for (int n = 0; n < 2; ++n) _Pragma("unroll") for (int k = 0; k < 2; ++k) dst[n][k] = *(const PG8_LAS bf16x8*)(lds + PG8_SB(b, h) + boff + n * 2048 + k * 1024); } while (0)
; #define PG8_MMA(ai, bj, At, Bt) do { __builtin_amdgcn_s_setprio(1); _Pragma("unroll") for (int m = 0; m < 4; ++m) _Pragma("unroll") for (int n = 0; n < 2; ++n) _Pragma("unroll") for (int k = 0; k < 2; ++k) \
;         acc[ai][bj][m][n] = __builtin_amdgcn_mfma_f32_16x16x32_bf16(Bt[n][k], At[m][k], acc[ai][bj][m][n], 0, 0, 0); __builtin_amdgcn_s_setprio(0); } while (0)
; #define PG8_WAIT_V(n) asm volatile("s_waitcnt vmcnt(" #n ")" ::: "memory")
; #define PG8_WAIT_L(n) asm volatile("s_waitcnt lgkmcnt(" #n ")" ::: "memory")
; #define PG8_BAR __builtin_amdgcn_s_barrier()
; #define PG8_SCHED __builtin_amdgcn_sched_barrier(0)
; template <class Epi, class Sched, bool ALIGN_EPI = false, bool SP2 = false>
; __device__ __forceinline__ void gemm_phase(PG8_LAS unsigned char* lds, const Gemm g, const Sched& S, const Epi& E) {
;     ...
;             PG8_WAIT_V(8); PG8_WAIT_L(0); PG8_BAR; PG8_MMA(1, 0, At, B0); PG8_MMA(1, 1, At, B1); PG8_BAR; PG8_SCHED;
;             PG8_LDB(B0, 1, 0); PG8_LDB(B1, 1, 1); PG8_SCHED; PG8_LDA(At, 1, 0); PG8_STAGE(PG8_SA(0, 1), a2 + hstep, voffA);
;             PG8_WAIT_V(8); PG8_WAIT_L(0); PG8_BAR; PG8_MMA(0, 0, At, B0); PG8_MMA(0, 1, At, B1); PG8_BAR; PG8_SCHED;
	s_setprio 1
	s_waitcnt lgkmcnt(0)
	v_mfma_f32_16x16x32_bf16 v[56:59], v[128:131], v[186:189], 0
	v_mfma_f32_16x16x32_bf16 v[60:63], v[136:139], v[186:189], 0
	v_mfma_f32_16x16x32_bf16 v[40:43], v[128:131], v[198:201], 0
	v_mfma_f32_16x16x32_bf16 v[44:47], v[136:139], v[198:201], 0
	v_mfma_f32_16x16x32_bf16 v[24:27], v[128:131], v[206:209], 0
	v_mfma_f32_16x16x32_bf16 v[28:31], v[136:139], v[206:209], 0
	v_mfma_f32_16x16x32_bf16 v[8:11], v[128:131], v[214:217], 0
	v_mfma_f32_16x16x32_bf16 v[12:15], v[136:139], v[214:217], 0
	v_mfma_f32_16x16x32_bf16 v[56:59], v[132:135], v[190:193], v[56:59]
	v_mfma_f32_16x16x32_bf16 v[60:63], v[140:143], v[190:193], v[60:63]
	v_mfma_f32_16x16x32_bf16 v[40:43], v[132:135], v[202:205], v[40:43]
	v_mfma_f32_16x16x32_bf16 v[44:47], v[140:143], v[202:205], v[44:47]
	v_mfma_f32_16x16x32_bf16 v[24:27], v[132:135], v[210:213], v[24:27]
	v_mfma_f32_16x16x32_bf16 v[28:31], v[140:143], v[210:213], v[28:31]
	v_mfma_f32_16x16x32_bf16 v[8:11], v[132:135], v[218:221], v[8:11]
	v_mfma_f32_16x16x32_bf16 v[12:15], v[140:143], v[218:221], v[12:15]
	s_setprio 0
	s_setprio 1
	v_mfma_f32_16x16x32_bf16 v[52:55], v[144:147], v[186:189], 0
	v_mfma_f32_16x16x32_bf16 v[48:51], v[168:171], v[186:189], 0
	v_mfma_f32_16x16x32_bf16 v[36:39], v[144:147], v[198:201], 0
	v_mfma_f32_16x16x32_bf16 v[32:35], v[168:171], v[198:201], 0
	v_mfma_f32_16x16x32_bf16 v[20:23], v[144:147], v[206:209], 0
	v_mfma_f32_16x16x32_bf16 v[16:19], v[168:171], v[206:209], 0
	v_mfma_f32_16x16x32_bf16 v[4:7], v[144:147], v[214:217], 0
	v_mfma_f32_16x16x32_bf16 v[0:3], v[168:171], v[214:217], 0
	v_mfma_f32_16x16x32_bf16 v[52:55], v[148:151], v[190:193], v[52:55]
	v_mfma_f32_16x16x32_bf16 v[48:51], v[172:175], v[190:193], v[48:51]
	v_mfma_f32_16x16x32_bf16 v[36:39], v[148:151], v[202:205], v[36:39]
	v_mfma_f32_16x16x32_bf16 v[32:35], v[172:175], v[202:205], v[32:35]
	v_mfma_f32_16x16x32_bf16 v[20:23], v[148:151], v[210:213], v[20:23]
	v_mfma_f32_16x16x32_bf16 v[16:19], v[172:175], v[210:213], v[16:19]
	v_mfma_f32_16x16x32_bf16 v[4:7], v[148:151], v[218:221], v[4:7]
	v_mfma_f32_16x16x32_bf16 v[0:3], v[172:175], v[218:221], v[0:3]
	s_setprio 0
	s_barrier
	s_add_i32 s51, 0, 0x18000
	s_add_i32 s52, 0, 0x1c000
	v_add_u32_e32 v140, s51, v179
	v_add_u32_e32 v172, s52, v179
	ds_read_b128 v[128:131], v140
	ds_read_b128 v[132:135], v140 offset:1024
	ds_read_b128 v[136:139], v140 offset:2048
	ds_read_b128 v[140:143], v140 offset:3072
	ds_read_b128 v[144:147], v172
	ds_read_b128 v[148:151], v172 offset:1024
	ds_read_b128 v[168:171], v172 offset:2048
	ds_read_b128 v[172:175], v172 offset:3072
	s_add_u32 s30, s30, 0x80000
	s_addc_u32 s31, s31, 0
	s_mov_b32 m0, s39
	v_lshl_add_u64 v[226:227], s[30:31], 0, v[152:153]
	ds_read_b128 v[186:189], v183 offset:32768
	ds_read_b128 v[190:193], v183 offset:33792
	ds_read_b128 v[198:201], v183 offset:34816
	ds_read_b128 v[202:205], v183 offset:35840
	ds_read_b128 v[206:209], v183 offset:36864
	ds_read_b128 v[210:213], v183 offset:37888
	ds_read_b128 v[214:217], v183 offset:38912
	ds_read_b128 v[218:221], v183 offset:39936
	global_load_lds_dwordx4 v[226:227], off
	v_lshl_add_u64 v[226:227], s[30:31], 0, v[156:157]
	s_mov_b32 m0, s42
	s_nop 0
	global_load_lds_dwordx4 v[226:227], off
	s_waitcnt vmcnt(8)
	s_waitcnt lgkmcnt(0)
	s_barrier
	s_setprio 1
	s_waitcnt lgkmcnt(0)
	v_mfma_f32_16x16x32_bf16 v[124:127], v[128:131], v[186:189], v[124:127]
	v_mfma_f32_16x16x32_bf16 v[120:123], v[136:139], v[186:189], v[120:123]
	v_mfma_f32_16x16x32_bf16 v[104:107], v[128:131], v[198:201], v[104:107]
	v_mfma_f32_16x16x32_bf16 v[108:111], v[136:139], v[198:201], v[108:111]
	v_mfma_f32_16x16x32_bf16 v[88:91], v[128:131], v[206:209], v[88:91]
	v_mfma_f32_16x16x32_bf16 v[92:95], v[136:139], v[206:209], v[92:95]
	v_mfma_f32_16x16x32_bf16 v[72:75], v[128:131], v[214:217], v[72:75]
	v_mfma_f32_16x16x32_bf16 v[76:79], v[136:139], v[214:217], v[76:79]
	v_mfma_f32_16x16x32_bf16 v[124:127], v[132:135], v[190:193], v[124:127]
	v_mfma_f32_16x16x32_bf16 v[120:123], v[140:143], v[190:193], v[120:123]
	v_mfma_f32_16x16x32_bf16 v[104:107], v[132:135], v[202:205], v[104:107]
	v_mfma_f32_16x16x32_bf16 v[108:111], v[140:143], v[202:205], v[108:111]
	v_mfma_f32_16x16x32_bf16 v[88:91], v[132:135], v[210:213], v[88:91]
	v_mfma_f32_16x16x32_bf16 v[92:95], v[140:143], v[210:213], v[92:95]
	v_mfma_f32_16x16x32_bf16 v[72:75], v[132:135], v[218:221], v[72:75]
	v_mfma_f32_16x16x32_bf16 v[76:79], v[140:143], v[218:221], v[76:79]
	s_setprio 0
	s_setprio 1
	v_mfma_f32_16x16x32_bf16 v[116:119], v[144:147], v[186:189], v[116:119]
	v_mfma_f32_16x16x32_bf16 v[112:115], v[168:171], v[186:189], v[112:115]
	v_mfma_f32_16x16x32_bf16 v[100:103], v[144:147], v[198:201], v[100:103]
	v_mfma_f32_16x16x32_bf16 v[96:99], v[168:171], v[198:201], v[96:99]
	v_mfma_f32_16x16x32_bf16 v[84:87], v[144:147], v[206:209], v[84:87]
	v_mfma_f32_16x16x32_bf16 v[80:83], v[168:171], v[206:209], v[80:83]
	v_mfma_f32_16x16x32_bf16 v[68:71], v[144:147], v[214:217], v[68:71]
	v_mfma_f32_16x16x32_bf16 v[64:67], v[168:171], v[214:217], v[64:67]
	v_mfma_f32_16x16x32_bf16 v[116:119], v[148:151], v[190:193], v[116:119]
	v_mfma_f32_16x16x32_bf16 v[112:115], v[172:175], v[190:193], v[112:115]
	v_mfma_f32_16x16x32_bf16 v[100:103], v[148:151], v[202:205], v[100:103]
	v_mfma_f32_16x16x32_bf16 v[96:99], v[172:175], v[202:205], v[96:99]
	v_mfma_f32_16x16x32_bf16 v[84:87], v[148:151], v[210:213], v[84:87]
	v_mfma_f32_16x16x32_bf16 v[80:83], v[172:175], v[210:213], v[80:83]
	v_mfma_f32_16x16x32_bf16 v[68:71], v[148:151], v[218:221], v[68:71]
	v_mfma_f32_16x16x32_bf16 v[64:67], v[172:175], v[218:221], v[64:67]
	s_setprio 0
	s_barrier
; #define PG8_STAGE(bufoff, gbase, voff) do { _Pragma("unroll") for (int _i = 0; _i < 2; ++_i) \
;         __builtin_amdgcn_global_load_lds((const unsigned*)((const char*)(gbase) + (voff)[_i]), (PG8_LAS unsigned*)(lds + (bufoff) + ldsw + _i * 8192), 16, 0, 0); } while (0)
; #define PG8_LDA(dst, b, h) do { _Pragma("unroll") for (int m = 0; m < 4; ++m) _Pragma("unroll") for (int k = 0; k < 2; ++k) dst[m][k] = *(const PG8_LAS bf16x8*)(lds + PG8_SA(b, h) + aoff + m * 2048 + k * 1024); } while (0)
; #define PG8_MMA(ai, bj, At, Bt) do { __builtin_amdgcn_s_setprio(1); _Pragma("unroll") for (int m = 0; m < 4; ++m) _Pragma("unroll") for (int n = 0; n < 2; ++n) _Pragma("unroll") for (int k = 0; k < 2; ++k) \
;         acc[ai][bj][m][n] = __builtin_amdgcn_mfma_f32_16x16x32_bf16(Bt[n][k], At[m][k], acc[ai][bj][m][n], 0, 0, 0); __builtin_amdgcn_s_setprio(0); } while (0)
; #define PG8_WAIT_V(n) asm volatile("s_waitcnt vmcnt(" #n ")" ::: "memory")
; #define PG8_WAIT_L(n) asm volatile("s_waitcnt lgkmcnt(" #n ")" ::: "memory")
; #define PG8_BAR __builtin_amdgcn_s_barrier()
; #define PG8_SCHED __builtin_amdgcn_sched_barrier(0)
; template <class Epi, class Sched, bool ALIGN_EPI = false, bool SP2 = false>
; __device__ __forceinline__ void gemm_phase(PG8_LAS unsigned char* lds, const Gemm g, const Sched& S, const Epi& E) {
;     ...
;             PG8_LDA(At, 1, 1); PG8_STAGE(PG8_SB(1, 0), b3, voffB); PG8_STAGE(PG8_SB(1, 1), b3 + hstep, voffB); PG8_STAGE(PG8_SA(1, 0), a3, voffA);
;             PG8_WAIT_V(8); PG8_WAIT_L(0); PG8_BAR; PG8_MMA(1, 0, At, B0); PG8_MMA(1, 1, At, B1); PG8_BAR; PG8_SCHED;
	s_add_i32 s30, s51, s34
	v_lshl_add_u64 v[176:177], v[176:177], 0, s[12:13]
	s_mov_b32 m0, s30
	ds_read_b128 v[186:189], v183 offset:49152
	ds_read_b128 v[190:193], v183 offset:50176
	ds_read_b128 v[198:201], v183 offset:51200
	ds_read_b128 v[202:205], v183 offset:52224
	ds_read_b128 v[206:209], v183 offset:53248
	ds_read_b128 v[210:213], v183 offset:54272
	ds_read_b128 v[214:217], v183 offset:55296
	ds_read_b128 v[218:221], v183 offset:56320
	global_load_lds_dwordx4 v[176:177], off
	s_add_i32 m0, s30, 0x2000
	s_add_u32 s28, s28, 0x80080
	v_lshl_add_u64 v[176:177], v[194:195], 0, s[12:13]
	s_addc_u32 s29, s29, 0
	s_add_i32 s30, s52, s34
	global_load_lds_dwordx4 v[176:177], off
	v_lshl_add_u64 v[176:177], s[28:29], 0, v[154:155]
	s_mov_b32 m0, s30
	s_nop 0
	global_load_lds_dwordx4 v[176:177], off
	v_lshl_add_u64 v[176:177], s[28:29], 0, v[158:159]
	s_add_i32 m0, s30, 0x2000
	s_nop 0
	global_load_lds_dwordx4 v[176:177], off
	v_lshl_add_u64 v[176:177], v[222:223], 0, s[12:13]
	s_mov_b32 m0, s44
	s_nop 0
	global_load_lds_dwordx4 v[176:177], off
	v_lshl_add_u64 v[176:177], v[224:225], 0, s[12:13]
	s_mov_b32 m0, s45
	s_nop 0
	global_load_lds_dwordx4 v[176:177], off
	s_waitcnt vmcnt(8)
	s_waitcnt lgkmcnt(0)
	s_barrier
	s_setprio 1
	s_waitcnt lgkmcnt(0)
	v_mfma_f32_16x16x32_bf16 v[56:59], v[128:131], v[186:189], v[56:59]
	v_mfma_f32_16x16x32_bf16 v[60:63], v[136:139], v[186:189], v[60:63]
	v_mfma_f32_16x16x32_bf16 v[40:43], v[128:131], v[198:201], v[40:43]
	v_mfma_f32_16x16x32_bf16 v[44:47], v[136:139], v[198:201], v[44:47]
	v_mfma_f32_16x16x32_bf16 v[24:27], v[128:131], v[206:209], v[24:27]
	v_mfma_f32_16x16x32_bf16 v[28:31], v[136:139], v[206:209], v[28:31]
	v_mfma_f32_16x16x32_bf16 v[8:11], v[128:131], v[214:217], v[8:11]
	v_mfma_f32_16x16x32_bf16 v[12:15], v[136:139], v[214:217], v[12:15]
	v_mfma_f32_16x16x32_bf16 v[56:59], v[132:135], v[190:193], v[56:59]
	v_mfma_f32_16x16x32_bf16 v[60:63], v[140:143], v[190:193], v[60:63]
	v_mfma_f32_16x16x32_bf16 v[40:43], v[132:135], v[202:205], v[40:43]
	v_mfma_f32_16x16x32_bf16 v[44:47], v[140:143], v[202:205], v[44:47]
	v_mfma_f32_16x16x32_bf16 v[24:27], v[132:135], v[210:213], v[24:27]
	v_mfma_f32_16x16x32_bf16 v[28:31], v[140:143], v[210:213], v[28:31]
	v_mfma_f32_16x16x32_bf16 v[8:11], v[132:135], v[218:221], v[8:11]
	v_mfma_f32_16x16x32_bf16 v[12:15], v[140:143], v[218:221], v[12:15]
	s_setprio 0
	s_setprio 1
	v_mfma_f32_16x16x32_bf16 v[52:55], v[144:147], v[186:189], v[52:55]
	v_mfma_f32_16x16x32_bf16 v[48:51], v[168:171], v[186:189], v[48:51]
	v_mfma_f32_16x16x32_bf16 v[36:39], v[144:147], v[198:201], v[36:39]
	v_mfma_f32_16x16x32_bf16 v[32:35], v[168:171], v[198:201], v[32:35]
	v_mfma_f32_16x16x32_bf16 v[20:23], v[144:147], v[206:209], v[20:23]
	v_mfma_f32_16x16x32_bf16 v[16:19], v[168:171], v[206:209], v[16:19]
	v_mfma_f32_16x16x32_bf16 v[4:7], v[144:147], v[214:217], v[4:7]
	v_mfma_f32_16x16x32_bf16 v[0:3], v[168:171], v[214:217], v[0:3]
	v_mfma_f32_16x16x32_bf16 v[52:55], v[148:151], v[190:193], v[52:55]
	v_mfma_f32_16x16x32_bf16 v[48:51], v[172:175], v[190:193], v[48:51]
	v_mfma_f32_16x16x32_bf16 v[36:39], v[148:151], v[202:205], v[36:39]
	v_mfma_f32_16x16x32_bf16 v[32:35], v[172:175], v[202:205], v[32:35]
	v_mfma_f32_16x16x32_bf16 v[20:23], v[148:151], v[210:213], v[20:23]
	v_mfma_f32_16x16x32_bf16 v[16:19], v[172:175], v[210:213], v[16:19]
	v_mfma_f32_16x16x32_bf16 v[4:7], v[148:151], v[218:221], v[4:7]
	v_mfma_f32_16x16x32_bf16 v[0:3], v[172:175], v[218:221], v[0:3]
	s_setprio 0
	s_barrier
	s_add_i32 s50, s50, 2
	s_add_u32 s26, s26, 0x100
	s_addc_u32 s27, s27, 0
	s_add_u32 s48, s48, 0x100
	s_addc_u32 s49, s49, 0

; #define PG8_STAGE(bufoff, gbase, voff) do { _Pragma("unroll") for (int _i = 0; _i < 2; ++_i) \
;         __builtin_amdgcn_global_load_lds((const unsigned*)((const char*)(gbase) + (voff)[_i]), (PG8_LAS unsigned*)(lds + (bufoff) + ldsw + _i * 8192), 16, 0, 0); } while (0)
; #define PG8_LDA(dst, b, h) do { _Pragma("unroll") for (int m = 0; m < 4; ++m) _Pragma("unroll") for (int k = 0; k < 2; ++k) dst[m][k] = *(const PG8_LAS bf16x8*)(lds + PG8_SA(b, h) + aoff + m * 2048 + k * 1024); } while (0)
; #define PG8_LDB(dst, b, h) do { _Pragma("unroll") for (int n = 0; n < 2; ++n) _Pragma("unroll") for (int k = 0; k < 2; ++k) dst[n][k] = *(const PG8_LAS bf16x8*)(lds + PG8_SB(b, h) + boff + n * 2048 + k * 1024); } while (0)
; #define PG8_MMA(ai, bj, At, Bt) do { __builtin_amdgcn_s_setprio(1); _Pragma("unroll") for (int m = 0; m < 4; ++m) _Pragma("unroll") for (int n = 0; n < 2; ++n) _Pragma("unroll") for (int k = 0; k < 2; ++k) \
;         acc[ai][bj][m][n] = __builtin_amdgcn_mfma_f32_16x16x32_bf16(Bt[n][k], At[m][k], acc[ai][bj][m][n], 0, 0, 0); __builtin_amdgcn_s_setprio(0); } while (0)
; #define PG8_WAIT_V(n) asm volatile("s_waitcnt vmcnt(" #n ")" ::: "memory")
; #define PG8_BAR __builtin_amdgcn_s_barrier()
; template <class Epi, class Sched, bool ALIGN_EPI = false, bool SP2 = false>
; __device__ __forceinline__ void gemm_phase(PG8_LAS unsigned char* lds, const Gemm g, const Sched& S, const Epi& E) {
;     ...
;         for (int t = 0; t < nt; t += 2) {
;             const bool last = (t == nt - 2);
;             const char* a1 = cA + (size_t)(t + 1) * kstep;
;             const char* a2 = last ? nA : cA + (size_t)(t + 2) * kstep; const char* b2 = last ? nB : cB + (size_t)(t + 2) * kstep;
;             const char* a3 = a2 + kstep; const char* b3 = b2 + kstep;
;             if (last && has_next) S.a_ready(nxt);
;             if constexpr (SP2) {
;             PG8_LDB(B0, 0, 0); PG8_LDB(B1, 0, 1); PG8_SCHED; PG8_LDA(At, 0, 0); PG8_STAGE(PG8_SA(1, 1), a1 + hstep, voffA);
;             PG8_WAIT_V(8); PG8_WAIT_L(0); PG8_BAR; PG8_MMA(0, 0, At, B0); PG8_MMA(0, 1, At, B1); PG8_BAR; PG8_SCHED;
;             PG8_LDA(At, 0, 1); PG8_STAGE(PG8_SB(0, 0), b2, voffB); PG8_STAGE(PG8_SB(0, 1), b2 + hstep, voffB); PG8_STAGE(PG8_SA(0, 0), a2, voffA);
;             PG8_WAIT_V(8); PG8_WAIT_L(0); PG8_BAR; PG8_MMA(1, 0, At, B0); PG8_MMA(1, 1, At, B1); PG8_BAR; PG8_SCHED;
.LBB0_490:
	s_ashr_i32 s21, s20, 31
	s_lshl_b64 s[0:1], s[20:21], 20
	v_readlane_b32 s24, v254, 51
	v_readlane_b32 s25, v254, 52
	s_add_u32 s24, s24, s0
	s_addc_u32 s25, s25, s1
	s_and_b64 s[0:1], s[22:23], exec
	s_cselect_b32 s5, s25, s31
	s_cselect_b32 s21, s24, s30
	s_ashr_i32 s19, s18, 31
	s_lshl_b64 s[0:1], s[18:19], 20
	v_readlane_b32 s26, v254, 22
	v_readlane_b32 s27, v254, 23
	s_add_u32 s26, s26, s0
	s_addc_u32 s27, s27, s1
	s_and_b64 s[0:1], s[22:23], exec
	s_cselect_b32 s19, s27, s29
	s_cselect_b32 s33, s26, s28
	s_add_u32 s0, s30, 0x80080
	s_addc_u32 s1, s31, 0
	s_add_u32 s44, s28, 0x100
	s_addc_u32 s45, s29, 0
	s_mov_b32 s48, -2
	v_add_u32_e32 v140, s68, v163
	v_add_u32_e32 v152, s69, v163
	ds_read_b128 v[128:131], v140
	ds_read_b128 v[132:135], v140 offset:1024
	ds_read_b128 v[136:139], v140 offset:2048
	ds_read_b128 v[140:143], v140 offset:3072
	ds_read_b128 v[184:187], v152
	ds_read_b128 v[218:221], v152 offset:1024
	ds_read_b128 v[222:225], v152 offset:2048
	ds_read_b128 v[226:229], v152 offset:3072
	s_add_u32 s28, s0, 0xfff80080
	s_addc_u32 s29, s1, -1
	s_cmp_eq_u32 s48, 28
	s_cselect_b32 s31, s5, s29
	s_cselect_b32 s30, s21, s28
	s_cselect_b32 s29, s19, s45
	s_cselect_b32 s28, s33, s44
	v_lshl_add_u64 v[172:173], s[0:1], 0, v[156:157]
	s_add_i32 m0, s17, 0xc000
	ds_read_b128 v[230:233], v214
	ds_read_b128 v[234:237], v214 offset:1024
	ds_read_b128 v[238:241], v214 offset:2048
	ds_read_b128 v[242:245], v214 offset:3072
	ds_read_b128 v[246:249], v214 offset:4096
	ds_read_b128 v[250:253], v214 offset:5120
	ds_read_b128 v[206:209], v214 offset:6144
	ds_read_b128 v[210:213], v214 offset:7168
	global_load_lds_dwordx4 v[172:173], off
	v_lshl_add_u64 v[172:173], s[0:1], 0, v[158:159]
	s_add_i32 m0, s17, 0xe000
	s_nop 0
	global_load_lds_dwordx4 v[172:173], off
	s_waitcnt vmcnt(8)
	s_waitcnt lgkmcnt(0)
	s_barrier
	s_setprio 1
	s_waitcnt lgkmcnt(0)
	v_mfma_f32_16x16x32_bf16 v[124:127], v[128:131], v[230:233], 0
	v_mfma_f32_16x16x32_bf16 v[120:123], v[136:139], v[230:233], 0
	v_mfma_f32_16x16x32_bf16 v[116:119], v[128:131], v[238:241], 0
	v_mfma_f32_16x16x32_bf16 v[108:111], v[136:139], v[238:241], 0
	v_mfma_f32_16x16x32_bf16 v[100:103], v[128:131], v[246:249], 0
	v_mfma_f32_16x16x32_bf16 v[92:95], v[136:139], v[246:249], 0
	v_mfma_f32_16x16x32_bf16 v[84:87], v[128:131], v[206:209], 0
	v_mfma_f32_16x16x32_bf16 v[76:79], v[136:139], v[206:209], 0
	v_mfma_f32_16x16x32_bf16 v[124:127], v[132:135], v[234:237], v[124:127]
	v_mfma_f32_16x16x32_bf16 v[120:123], v[140:143], v[234:237], v[120:123]
	v_mfma_f32_16x16x32_bf16 v[116:119], v[132:135], v[242:245], v[116:119]
	v_mfma_f32_16x16x32_bf16 v[108:111], v[140:143], v[242:245], v[108:111]
	v_mfma_f32_16x16x32_bf16 v[100:103], v[132:135], v[250:253], v[100:103]
	v_mfma_f32_16x16x32_bf16 v[92:95], v[140:143], v[250:253], v[92:95]
	v_mfma_f32_16x16x32_bf16 v[84:87], v[132:135], v[210:213], v[84:87]
	v_mfma_f32_16x16x32_bf16 v[76:79], v[140:143], v[210:213], v[76:79]
	s_setprio 0
	s_setprio 1
	v_mfma_f32_16x16x32_bf16 v[112:115], v[184:187], v[230:233], 0
	v_mfma_f32_16x16x32_bf16 v[104:107], v[222:225], v[230:233], 0
	v_mfma_f32_16x16x32_bf16 v[96:99], v[184:187], v[238:241], 0
	v_mfma_f32_16x16x32_bf16 v[88:91], v[222:225], v[238:241], 0
	v_mfma_f32_16x16x32_bf16 v[80:83], v[184:187], v[246:249], 0
	v_mfma_f32_16x16x32_bf16 v[72:75], v[222:225], v[246:249], 0
	v_mfma_f32_16x16x32_bf16 v[68:71], v[184:187], v[206:209], 0
	v_mfma_f32_16x16x32_bf16 v[64:67], v[222:225], v[206:209], 0
	v_mfma_f32_16x16x32_bf16 v[112:115], v[218:221], v[234:237], v[112:115]
	v_mfma_f32_16x16x32_bf16 v[104:107], v[226:229], v[234:237], v[104:107]
	v_mfma_f32_16x16x32_bf16 v[96:99], v[218:221], v[242:245], v[96:99]
	v_mfma_f32_16x16x32_bf16 v[88:91], v[226:229], v[242:245], v[88:91]
	v_mfma_f32_16x16x32_bf16 v[80:83], v[218:221], v[250:253], v[80:83]
	v_mfma_f32_16x16x32_bf16 v[72:75], v[226:229], v[250:253], v[72:75]
	v_mfma_f32_16x16x32_bf16 v[68:71], v[218:221], v[210:213], v[68:71]
	v_mfma_f32_16x16x32_bf16 v[64:67], v[226:229], v[210:213], v[64:67]
	s_setprio 0
	s_barrier
	s_add_i32 s49, s68, s34
	v_lshl_add_u64 v[172:173], s[28:29], 0, v[146:147]
	s_mov_b32 m0, s49
	ds_read_b128 v[206:209], v214 offset:16384
	ds_read_b128 v[210:213], v214 offset:17408
	ds_read_b128 v[230:233], v214 offset:18432
	ds_read_b128 v[234:237], v214 offset:19456
	ds_read_b128 v[238:241], v214 offset:20480
	ds_read_b128 v[242:245], v214 offset:21504
	ds_read_b128 v[246:249], v214 offset:22528
	ds_read_b128 v[250:253], v214 offset:23552
	global_load_lds_dwordx4 v[172:173], off
	s_add_i32 m0, s49, 0x2000
	s_add_u32 s50, s28, 0x80000
	v_lshl_add_u64 v[176:177], s[28:29], 0, v[150:151]
	s_addc_u32 s51, s29, 0
	s_add_i32 s49, s69, s34
	global_load_lds_dwordx4 v[176:177], off
	v_lshl_add_u64 v[180:181], s[50:51], 0, v[146:147]
	s_mov_b32 m0, s49
	v_lshl_add_u64 v[188:189], s[30:31], 0, v[148:149]
	global_load_lds_dwordx4 v[180:181], off
	v_lshl_add_u64 v[180:181], s[50:51], 0, v[150:151]
	s_add_i32 m0, s49, 0x2000
	s_nop 0
	global_load_lds_dwordx4 v[180:181], off
	v_lshl_add_u64 v[180:181], s[30:31], 0, v[144:145]
	s_mov_b32 m0, s17
	s_nop 0
	global_load_lds_dwordx4 v[180:181], off
	s_mov_b32 m0, s35
	s_nop 0
	global_load_lds_dwordx4 v[188:189], off
	s_waitcnt vmcnt(8)
	s_waitcnt lgkmcnt(0)
	s_barrier
; #define PG8_STAGE(bufoff, gbase, voff) do { _Pragma("unroll") for (int _i = 0; _i < 2; ++_i) \
;         __builtin_amdgcn_global_load_lds((const unsigned*)((const char*)(gbase) + (voff)[_i]), (PG8_LAS unsigned*)(lds + (bufoff) + ldsw + _i * 8192), 16, 0, 0); } while (0)
; #define PG8_LDA(dst, b, h) do { _Pragma("unroll") for (int m = 0; m < 4; ++m) _Pragma("unroll") for (int k = 0; k < 2; ++k) dst[m][k] = *(const PG8_LAS bf16x8*)(lds + PG8_SA(b, h) + aoff + m * 2048 + k * 1024); } while (0)
; #define PG8_LDB(dst, b, h) do { _Pragma("unroll") for (int n = 0; n < 2; ++n) _Pragma("unroll") for (int k = 0; k < 2; ++k) dst[n][k] = *(const PG8_LAS bf16x8*)(lds + PG8_SB(b, h) + boff + n * 2048 + k * 1024); } while (0)
; #define PG8_MMA(ai, bj, At, Bt) do { __builtin_amdgcn_s_setprio(1); _Pragma("unroll") for (int m = 0; m < 4; ++m) _Pragma("unroll") for (int n = 0; n < 2; ++n) _Pragma("unroll") for (int k = 0; k < 2; ++k) \
;         acc[ai][bj][m][n] = __builtin_amdgcn_mfma_f32_16x16x32_bf16(Bt[n][k], At[m][k], acc[ai][bj][m][n], 0, 0, 0); __builtin_amdgcn_s_setprio(0); } while (0)
; #define PG8_WAIT_V(n) asm volatile("s_waitcnt vmcnt(" #n ")" ::: "memory")
; #define PG8_WAIT_L(n) asm volatile("s_waitcnt lgkmcnt(" #n ")" ::: "memory")
; #define PG8_BAR __builtin_amdgcn_s_barrier()
; #define PG8_SCHED __builtin_amdgcn_sched_barrier(0)
; template <class Epi, class Sched, bool ALIGN_EPI = false, bool SP2 = false>
; __device__ __forceinline__ void gemm_phase(PG8_LAS unsigned char* lds, const Gemm g, const Sched& S, const Epi& E) {
;     ...
;             PG8_WAIT_V(8); PG8_WAIT_L(0); PG8_BAR; PG8_MMA(1, 0, At, B0); PG8_MMA(1, 1, At, B1); PG8_BAR; PG8_SCHED;
;             PG8_LDB(B0, 1, 0); PG8_LDB(B1, 1, 1); PG8_SCHED; PG8_LDA(At, 1, 0); PG8_STAGE(PG8_SA(0, 1), a2 + hstep, voffA);
;             PG8_WAIT_V(8); PG8_WAIT_L(0); PG8_BAR; PG8_MMA(0, 0, At, B0); PG8_MMA(0, 1, At, B1); PG8_BAR; PG8_SCHED;
	s_setprio 1
	s_waitcnt lgkmcnt(0)
	v_mfma_f32_16x16x32_bf16 v[60:63], v[128:131], v[206:209], 0
	v_mfma_f32_16x16x32_bf16 v[56:59], v[136:139], v[206:209], 0
	v_mfma_f32_16x16x32_bf16 v[52:55], v[128:131], v[230:233], 0
	v_mfma_f32_16x16x32_bf16 v[44:47], v[136:139], v[230:233], 0
	v_mfma_f32_16x16x32_bf16 v[36:39], v[128:131], v[238:241], 0
	v_mfma_f32_16x16x32_bf16 v[28:31], v[136:139], v[238:241], 0
	v_mfma_f32_16x16x32_bf16 v[20:23], v[128:131], v[246:249], 0
	v_mfma_f32_16x16x32_bf16 v[12:15], v[136:139], v[246:249], 0
	v_mfma_f32_16x16x32_bf16 v[60:63], v[132:135], v[210:213], v[60:63]
	v_mfma_f32_16x16x32_bf16 v[56:59], v[140:143], v[210:213], v[56:59]
	v_mfma_f32_16x16x32_bf16 v[52:55], v[132:135], v[234:237], v[52:55]
	v_mfma_f32_16x16x32_bf16 v[44:47], v[140:143], v[234:237], v[44:47]
	v_mfma_f32_16x16x32_bf16 v[36:39], v[132:135], v[242:245], v[36:39]
	v_mfma_f32_16x16x32_bf16 v[28:31], v[140:143], v[242:245], v[28:31]
	v_mfma_f32_16x16x32_bf16 v[20:23], v[132:135], v[250:253], v[20:23]
	v_mfma_f32_16x16x32_bf16 v[12:15], v[140:143], v[250:253], v[12:15]
	s_setprio 0
	s_setprio 1
	v_mfma_f32_16x16x32_bf16 v[48:51], v[184:187], v[206:209], 0
	v_mfma_f32_16x16x32_bf16 v[40:43], v[222:225], v[206:209], 0
	v_mfma_f32_16x16x32_bf16 v[32:35], v[184:187], v[230:233], 0
	v_mfma_f32_16x16x32_bf16 v[24:27], v[222:225], v[230:233], 0
	v_mfma_f32_16x16x32_bf16 v[16:19], v[184:187], v[238:241], 0
	v_mfma_f32_16x16x32_bf16 v[8:11], v[222:225], v[238:241], 0
	v_mfma_f32_16x16x32_bf16 v[4:7], v[184:187], v[246:249], 0
	v_mfma_f32_16x16x32_bf16 v[0:3], v[222:225], v[246:249], 0
	v_mfma_f32_16x16x32_bf16 v[48:51], v[218:221], v[210:213], v[48:51]
	v_mfma_f32_16x16x32_bf16 v[40:43], v[226:229], v[210:213], v[40:43]
	v_mfma_f32_16x16x32_bf16 v[32:35], v[218:221], v[234:237], v[32:35]
	v_mfma_f32_16x16x32_bf16 v[24:27], v[226:229], v[234:237], v[24:27]
	v_mfma_f32_16x16x32_bf16 v[16:19], v[218:221], v[242:245], v[16:19]
	v_mfma_f32_16x16x32_bf16 v[8:11], v[226:229], v[242:245], v[8:11]
	v_mfma_f32_16x16x32_bf16 v[4:7], v[218:221], v[250:253], v[4:7]
	v_mfma_f32_16x16x32_bf16 v[0:3], v[226:229], v[250:253], v[0:3]
	s_setprio 0
	s_barrier
	s_add_i32 s49, 0, 0x18000
	s_add_i32 s50, 0, 0x1c000
	v_add_u32_e32 v140, s49, v163
	v_add_u32_e32 v152, s50, v163
	ds_read_b128 v[128:131], v140
	ds_read_b128 v[132:135], v140 offset:1024
	ds_read_b128 v[136:139], v140 offset:2048
	ds_read_b128 v[140:143], v140 offset:3072
	ds_read_b128 v[184:187], v152
	ds_read_b128 v[206:209], v152 offset:1024
	ds_read_b128 v[210:213], v152 offset:2048
	ds_read_b128 v[218:221], v152 offset:3072
	s_add_u32 s30, s30, 0x80000
	s_addc_u32 s31, s31, 0
	s_mov_b32 m0, s37
	v_lshl_add_u64 v[216:217], s[30:31], 0, v[144:145]
	ds_read_b128 v[222:225], v214 offset:32768
	ds_read_b128 v[226:229], v214 offset:33792
	ds_read_b128 v[230:233], v214 offset:34816
	ds_read_b128 v[234:237], v214 offset:35840
	ds_read_b128 v[238:241], v214 offset:36864
	ds_read_b128 v[242:245], v214 offset:37888
	ds_read_b128 v[246:249], v214 offset:38912
	ds_read_b128 v[250:253], v214 offset:39936
	global_load_lds_dwordx4 v[216:217], off
	v_lshl_add_u64 v[216:217], s[30:31], 0, v[148:149]
	s_mov_b32 m0, s39
	s_nop 0
	global_load_lds_dwordx4 v[216:217], off
	s_waitcnt vmcnt(8)
	s_waitcnt lgkmcnt(0)
	s_barrier
	s_setprio 1
	s_waitcnt lgkmcnt(0)
	v_mfma_f32_16x16x32_bf16 v[124:127], v[128:131], v[222:225], v[124:127]
	v_mfma_f32_16x16x32_bf16 v[120:123], v[136:139], v[222:225], v[120:123]
	v_mfma_f32_16x16x32_bf16 v[116:119], v[128:131], v[230:233], v[116:119]
	v_mfma_f32_16x16x32_bf16 v[108:111], v[136:139], v[230:233], v[108:111]
	v_mfma_f32_16x16x32_bf16 v[100:103], v[128:131], v[238:241], v[100:103]
	v_mfma_f32_16x16x32_bf16 v[92:95], v[136:139], v[238:241], v[92:95]
	v_mfma_f32_16x16x32_bf16 v[84:87], v[128:131], v[246:249], v[84:87]
	v_mfma_f32_16x16x32_bf16 v[76:79], v[136:139], v[246:249], v[76:79]
	v_mfma_f32_16x16x32_bf16 v[124:127], v[132:135], v[226:229], v[124:127]
	v_mfma_f32_16x16x32_bf16 v[120:123], v[140:143], v[226:229], v[120:123]
	v_mfma_f32_16x16x32_bf16 v[116:119], v[132:135], v[234:237], v[116:119]
	v_mfma_f32_16x16x32_bf16 v[108:111], v[140:143], v[234:237], v[108:111]
	v_mfma_f32_16x16x32_bf16 v[100:103], v[132:135], v[242:245], v[100:103]
	v_mfma_f32_16x16x32_bf16 v[92:95], v[140:143], v[242:245], v[92:95]
	v_mfma_f32_16x16x32_bf16 v[84:87], v[132:135], v[250:253], v[84:87]
	v_mfma_f32_16x16x32_bf16 v[76:79], v[140:143], v[250:253], v[76:79]
	s_setprio 0
	s_setprio 1
	v_mfma_f32_16x16x32_bf16 v[112:115], v[184:187], v[222:225], v[112:115]
	v_mfma_f32_16x16x32_bf16 v[104:107], v[210:213], v[222:225], v[104:107]
	v_mfma_f32_16x16x32_bf16 v[96:99], v[184:187], v[230:233], v[96:99]
	v_mfma_f32_16x16x32_bf16 v[88:91], v[210:213], v[230:233], v[88:91]
	v_mfma_f32_16x16x32_bf16 v[80:83], v[184:187], v[238:241], v[80:83]
	v_mfma_f32_16x16x32_bf16 v[72:75], v[210:213], v[238:241], v[72:75]
	v_mfma_f32_16x16x32_bf16 v[68:71], v[184:187], v[246:249], v[68:71]
	v_mfma_f32_16x16x32_bf16 v[64:67], v[210:213], v[246:249], v[64:67]
	v_mfma_f32_16x16x32_bf16 v[112:115], v[206:209], v[226:229], v[112:115]
	v_mfma_f32_16x16x32_bf16 v[104:107], v[218:221], v[226:229], v[104:107]
	v_mfma_f32_16x16x32_bf16 v[96:99], v[206:209], v[234:237], v[96:99]
	v_mfma_f32_16x16x32_bf16 v[88:91], v[218:221], v[234:237], v[88:91]
	v_mfma_f32_16x16x32_bf16 v[80:83], v[206:209], v[242:245], v[80:83]
	v_mfma_f32_16x16x32_bf16 v[72:75], v[218:221], v[242:245], v[72:75]
	v_mfma_f32_16x16x32_bf16 v[68:71], v[206:209], v[250:253], v[68:71]
	v_mfma_f32_16x16x32_bf16 v[64:67], v[218:221], v[250:253], v[64:67]
	s_setprio 0
	s_barrier
; #define PG8_STAGE(bufoff, gbase, voff) do { _Pragma("unroll") for (int _i = 0; _i < 2; ++_i) \
;         __builtin_amdgcn_global_load_lds((const unsigned*)((const char*)(gbase) + (voff)[_i]), (PG8_LAS unsigned*)(lds + (bufoff) + ldsw + _i * 8192), 16, 0, 0); } while (0)
; #define PG8_LDA(dst, b, h) do { _Pragma("unroll") for (int m = 0; m < 4; ++m) _Pragma("unroll") for (int k = 0; k < 2; ++k) dst[m][k] = *(const PG8_LAS bf16x8*)(lds + PG8_SA(b, h) + aoff + m * 2048 + k * 1024); } while (0)
; #define PG8_MMA(ai, bj, At, Bt) do { __builtin_amdgcn_s_setprio(1); _Pragma("unroll") for (int m = 0; m < 4; ++m) _Pragma("unroll") for (int n = 0; n < 2; ++n) _Pragma("unroll") for (int k = 0; k < 2; ++k) \
;         acc[ai][bj][m][n] = __builtin_amdgcn_mfma_f32_16x16x32_bf16(Bt[n][k], At[m][k], acc[ai][bj][m][n], 0, 0, 0); __builtin_amdgcn_s_setprio(0); } while (0)
; #define PG8_WAIT_V(n) asm volatile("s_waitcnt vmcnt(" #n ")" ::: "memory")
; #define PG8_WAIT_L(n) asm volatile("s_waitcnt lgkmcnt(" #n ")" ::: "memory")
; #define PG8_BAR __builtin_amdgcn_s_barrier()
; #define PG8_SCHED __builtin_amdgcn_sched_barrier(0)
; template <class Epi, class Sched, bool ALIGN_EPI = false, bool SP2 = false>
; __device__ __forceinline__ void gemm_phase(PG8_LAS unsigned char* lds, const Gemm g, const Sched& S, const Epi& E) {
;     ...
;             PG8_LDA(At, 1, 1); PG8_STAGE(PG8_SB(1, 0), b3, voffB); PG8_STAGE(PG8_SB(1, 1), b3 + hstep, voffB); PG8_STAGE(PG8_SA(1, 0), a3, voffA);
;             PG8_WAIT_V(8); PG8_WAIT_L(0); PG8_BAR; PG8_MMA(1, 0, At, B0); PG8_MMA(1, 1, At, B1); PG8_BAR; PG8_SCHED;
	s_add_i32 s30, s49, s34
	v_lshl_add_u64 v[172:173], v[172:173], 0, s[10:11]
	s_mov_b32 m0, s30
	ds_read_b128 v[222:225], v214 offset:49152
	ds_read_b128 v[226:229], v214 offset:50176
	ds_read_b128 v[230:233], v214 offset:51200
	ds_read_b128 v[234:237], v214 offset:52224
	ds_read_b128 v[238:241], v214 offset:53248
	ds_read_b128 v[242:245], v214 offset:54272
	ds_read_b128 v[246:249], v214 offset:55296
	ds_read_b128 v[250:253], v214 offset:56320
	global_load_lds_dwordx4 v[172:173], off
	s_add_i32 m0, s30, 0x2000
	s_add_u32 s28, s28, 0x80080
	v_lshl_add_u64 v[172:173], v[176:177], 0, s[10:11]
	s_addc_u32 s29, s29, 0
	s_add_i32 s30, s50, s34
	global_load_lds_dwordx4 v[172:173], off
	v_lshl_add_u64 v[172:173], s[28:29], 0, v[146:147]
	s_mov_b32 m0, s30
	s_nop 0
	global_load_lds_dwordx4 v[172:173], off
	v_lshl_add_u64 v[172:173], s[28:29], 0, v[150:151]
	s_add_i32 m0, s30, 0x2000
	s_nop 0
	global_load_lds_dwordx4 v[172:173], off
	v_lshl_add_u64 v[172:173], v[180:181], 0, s[10:11]
	s_mov_b32 m0, s43
	s_nop 0
	global_load_lds_dwordx4 v[172:173], off
	v_lshl_add_u64 v[172:173], v[188:189], 0, s[10:11]
	s_mov_b32 m0, s46
	s_nop 0
	global_load_lds_dwordx4 v[172:173], off
	s_waitcnt vmcnt(8)
	s_waitcnt lgkmcnt(0)
	s_barrier
	s_setprio 1
	s_waitcnt lgkmcnt(0)
	v_mfma_f32_16x16x32_bf16 v[60:63], v[128:131], v[222:225], v[60:63]
	v_mfma_f32_16x16x32_bf16 v[56:59], v[136:139], v[222:225], v[56:59]
	v_mfma_f32_16x16x32_bf16 v[52:55], v[128:131], v[230:233], v[52:55]
	v_mfma_f32_16x16x32_bf16 v[44:47], v[136:139], v[230:233], v[44:47]
	v_mfma_f32_16x16x32_bf16 v[36:39], v[128:131], v[238:241], v[36:39]
	v_mfma_f32_16x16x32_bf16 v[28:31], v[136:139], v[238:241], v[28:31]
	v_mfma_f32_16x16x32_bf16 v[20:23], v[128:131], v[246:249], v[20:23]
	v_mfma_f32_16x16x32_bf16 v[12:15], v[136:139], v[246:249], v[12:15]
	v_mfma_f32_16x16x32_bf16 v[60:63], v[132:135], v[226:229], v[60:63]
	v_mfma_f32_16x16x32_bf16 v[56:59], v[140:143], v[226:229], v[56:59]
	v_mfma_f32_16x16x32_bf16 v[52:55], v[132:135], v[234:237], v[52:55]
	v_mfma_f32_16x16x32_bf16 v[44:47], v[140:143], v[234:237], v[44:47]
	v_mfma_f32_16x16x32_bf16 v[36:39], v[132:135], v[242:245], v[36:39]
	v_mfma_f32_16x16x32_bf16 v[28:31], v[140:143], v[242:245], v[28:31]
	v_mfma_f32_16x16x32_bf16 v[20:23], v[132:135], v[250:253], v[20:23]
	v_mfma_f32_16x16x32_bf16 v[12:15], v[140:143], v[250:253], v[12:15]
	s_setprio 0
	s_setprio 1
	v_mfma_f32_16x16x32_bf16 v[48:51], v[184:187], v[222:225], v[48:51]
	v_mfma_f32_16x16x32_bf16 v[40:43], v[210:213], v[222:225], v[40:43]
	v_mfma_f32_16x16x32_bf16 v[32:35], v[184:187], v[230:233], v[32:35]
	v_mfma_f32_16x16x32_bf16 v[24:27], v[210:213], v[230:233], v[24:27]
	v_mfma_f32_16x16x32_bf16 v[16:19], v[184:187], v[238:241], v[16:19]
	v_mfma_f32_16x16x32_bf16 v[8:11], v[210:213], v[238:241], v[8:11]
	v_mfma_f32_16x16x32_bf16 v[4:7], v[184:187], v[246:249], v[4:7]
	v_mfma_f32_16x16x32_bf16 v[0:3], v[210:213], v[246:249], v[0:3]
	v_mfma_f32_16x16x32_bf16 v[48:51], v[206:209], v[226:229], v[48:51]
	v_mfma_f32_16x16x32_bf16 v[40:43], v[218:221], v[226:229], v[40:43]
	v_mfma_f32_16x16x32_bf16 v[32:35], v[206:209], v[234:237], v[32:35]
	v_mfma_f32_16x16x32_bf16 v[24:27], v[218:221], v[234:237], v[24:27]
	v_mfma_f32_16x16x32_bf16 v[16:19], v[206:209], v[242:245], v[16:19]
	v_mfma_f32_16x16x32_bf16 v[8:11], v[218:221], v[242:245], v[8:11]
	v_mfma_f32_16x16x32_bf16 v[4:7], v[206:209], v[250:253], v[4:7]
	v_mfma_f32_16x16x32_bf16 v[0:3], v[218:221], v[250:253], v[0:3]
	s_setprio 0
	s_barrier
	s_add_i32 s48, s48, 2
	s_add_u32 s0, s0, 0x100
	s_addc_u32 s1, s1, 0
	s_add_u32 s44, s44, 0x100
	s_addc_u32 s45, s45, 0

; #define PG8_STAGE(bufoff, gbase, voff) do { _Pragma("unroll") for (int _i = 0; _i < 2; ++_i) \
;         __builtin_amdgcn_global_load_lds((const unsigned*)((const char*)(gbase) + (voff)[_i]), (PG8_LAS unsigned*)(lds + (bufoff) + ldsw + _i * 8192), 16, 0, 0); } while (0)
; #define PG8_LDA(dst, b, h) do { _Pragma("unroll") for (int m = 0; m < 4; ++m) _Pragma("unroll") for (int k = 0; k < 2; ++k) dst[m][k] = *(const PG8_LAS bf16x8*)(lds + PG8_SA(b, h) + aoff + m * 2048 + k * 1024); } while (0)
; #define PG8_LDB(dst, b, h) do { _Pragma("unroll") for (int n = 0; n < 2; ++n) _Pragma("unroll") for (int k = 0; k < 2; ++k) dst[n][k] = *(const PG8_LAS bf16x8*)(lds + PG8_SB(b, h) + boff + n * 2048 + k * 1024); } while (0)
; #define PG8_MMA(ai, bj, At, Bt) do { __builtin_amdgcn_s_setprio(1); _Pragma("unroll") for (int m = 0; m < 4; ++m) _Pragma("unroll") for (int n = 0; n < 2; ++n) _Pragma("unroll") for (int k = 0; k < 2; ++k) \
;         acc[ai][bj][m][n] = __builtin_amdgcn_mfma_f32_16x16x32_bf16(Bt[n][k], At[m][k], acc[ai][bj][m][n], 0, 0, 0); __builtin_amdgcn_s_setprio(0); } while (0)
; #define PG8_WAIT_V(n) asm volatile("s_waitcnt vmcnt(" #n ")" ::: "memory")
; #define PG8_BAR __builtin_amdgcn_s_barrier()
; template <class Epi, class Sched, bool ALIGN_EPI = false, bool SP2 = false>
; __device__ __forceinline__ void gemm_phase(PG8_LAS unsigned char* lds, const Gemm g, const Sched& S, const Epi& E) {
;     ...
;         for (int t = 0; t < nt; t += 2) {
;             const bool last = (t == nt - 2);
;             const char* a1 = cA + (size_t)(t + 1) * kstep;
;             const char* a2 = last ? nA : cA + (size_t)(t + 2) * kstep; const char* b2 = last ? nB : cB + (size_t)(t + 2) * kstep;
;             const char* a3 = a2 + kstep; const char* b3 = b2 + kstep;
;             if (last && has_next) S.a_ready(nxt);
;             if constexpr (SP2) {
;             PG8_LDB(B0, 0, 0); PG8_LDB(B1, 0, 1); PG8_SCHED; PG8_LDA(At, 0, 0); PG8_STAGE(PG8_SA(1, 1), a1 + hstep, voffA);
;             PG8_WAIT_V(8); PG8_WAIT_L(0); PG8_BAR; PG8_MMA(0, 0, At, B0); PG8_MMA(0, 1, At, B1); PG8_BAR; PG8_SCHED;
;             PG8_LDA(At, 0, 1); PG8_STAGE(PG8_SB(0, 0), b2, voffB); PG8_STAGE(PG8_SB(0, 1), b2 + hstep, voffB); PG8_STAGE(PG8_SA(0, 0), a2, voffA);
;             PG8_WAIT_V(8); PG8_WAIT_L(0); PG8_BAR; PG8_MMA(1, 0, At, B0); PG8_MMA(1, 1, At, B1); PG8_BAR; PG8_SCHED;
.LBB0_762:
	s_ashr_i32 s21, s20, 31
	s_lshl_b64 s[22:23], s[20:21], 21
	s_add_u32 s22, s60, s22
	s_addc_u32 s23, s61, s23
	s_and_b64 s[24:25], s[4:5], exec
	s_cselect_b32 s7, s23, s27
	s_cselect_b32 s21, s22, s26
	s_ashr_i32 s19, s18, 31
	s_lshl_b64 s[24:25], s[18:19], 21
	v_readlane_b32 s30, v254, 32
	v_readlane_b32 s31, v254, 33
	s_add_u32 s24, s30, s24
	s_addc_u32 s25, s31, s25
	s_and_b64 s[30:31], s[4:5], exec
	s_cselect_b32 s19, s25, s29
	s_cselect_b32 s48, s24, s28
	s_add_u32 s26, s26, 0x100080
	s_addc_u32 s27, s27, 0
	s_add_u32 s49, s28, 0x100
	s_addc_u32 s52, s29, 0
	s_mov_b32 s53, -2
	s_waitcnt lgkmcnt(0)
	ds_read_b128 v[128:131], v181
	ds_read_b128 v[132:135], v181 offset:1024
	ds_read_b128 v[136:139], v181 offset:2048
	ds_read_b128 v[140:143], v181 offset:3072
	ds_read_b128 v[144:147], v182
	ds_read_b128 v[148:151], v182 offset:1024
	ds_read_b128 v[168:171], v182 offset:2048
	ds_read_b128 v[172:175], v182 offset:3072
	s_add_u32 s28, s26, 0xfff00080
	s_addc_u32 s29, s27, -1
	s_cmp_eq_u32 s53, 60
	s_cselect_b32 s31, s7, s29
	s_cselect_b32 s30, s21, s28
	s_cselect_b32 s29, s19, s52
	s_cselect_b32 s28, s48, s49
	v_lshl_add_u64 v[176:177], s[26:27], 0, v[160:161]
	s_add_i32 m0, s35, 0xc000
	ds_read_b128 v[186:189], v183
	ds_read_b128 v[190:193], v183 offset:1024
	ds_read_b128 v[198:201], v183 offset:2048
	ds_read_b128 v[202:205], v183 offset:3072
	ds_read_b128 v[206:209], v183 offset:4096
	ds_read_b128 v[210:213], v183 offset:5120
	ds_read_b128 v[214:217], v183 offset:6144
	ds_read_b128 v[218:221], v183 offset:7168
	global_load_lds_dwordx4 v[176:177], off
	v_lshl_add_u64 v[176:177], s[26:27], 0, v[162:163]
	s_add_i32 m0, s35, 0xe000
	s_nop 0
	global_load_lds_dwordx4 v[176:177], off
	s_waitcnt vmcnt(8)
	s_waitcnt lgkmcnt(0)
	s_barrier
	s_setprio 1
	s_waitcnt lgkmcnt(0)
	v_mfma_f32_16x16x32_bf16 v[124:127], v[128:131], v[186:189], 0
	v_mfma_f32_16x16x32_bf16 v[120:123], v[136:139], v[186:189], 0
	v_mfma_f32_16x16x32_bf16 v[104:107], v[128:131], v[198:201], 0
	v_mfma_f32_16x16x32_bf16 v[108:111], v[136:139], v[198:201], 0
	v_mfma_f32_16x16x32_bf16 v[88:91], v[128:131], v[206:209], 0
	v_mfma_f32_16x16x32_bf16 v[92:95], v[136:139], v[206:209], 0
	v_mfma_f32_16x16x32_bf16 v[72:75], v[128:131], v[214:217], 0
	v_mfma_f32_16x16x32_bf16 v[76:79], v[136:139], v[214:217], 0
	v_mfma_f32_16x16x32_bf16 v[124:127], v[132:135], v[190:193], v[124:127]
	v_mfma_f32_16x16x32_bf16 v[120:123], v[140:143], v[190:193], v[120:123]
	v_mfma_f32_16x16x32_bf16 v[104:107], v[132:135], v[202:205], v[104:107]
	v_mfma_f32_16x16x32_bf16 v[108:111], v[140:143], v[202:205], v[108:111]
	v_mfma_f32_16x16x32_bf16 v[88:91], v[132:135], v[210:213], v[88:91]
	v_mfma_f32_16x16x32_bf16 v[92:95], v[140:143], v[210:213], v[92:95]
	v_mfma_f32_16x16x32_bf16 v[72:75], v[132:135], v[218:221], v[72:75]
	v_mfma_f32_16x16x32_bf16 v[76:79], v[140:143], v[218:221], v[76:79]
	s_setprio 0
	s_setprio 1
	v_mfma_f32_16x16x32_bf16 v[116:119], v[144:147], v[186:189], 0
	v_mfma_f32_16x16x32_bf16 v[112:115], v[168:171], v[186:189], 0
	v_mfma_f32_16x16x32_bf16 v[100:103], v[144:147], v[198:201], 0
	v_mfma_f32_16x16x32_bf16 v[96:99], v[168:171], v[198:201], 0
	v_mfma_f32_16x16x32_bf16 v[84:87], v[144:147], v[206:209], 0
	v_mfma_f32_16x16x32_bf16 v[80:83], v[168:171], v[206:209], 0
	v_mfma_f32_16x16x32_bf16 v[68:71], v[144:147], v[214:217], 0
	v_mfma_f32_16x16x32_bf16 v[64:67], v[168:171], v[214:217], 0
	v_mfma_f32_16x16x32_bf16 v[116:119], v[148:151], v[190:193], v[116:119]
	v_mfma_f32_16x16x32_bf16 v[112:115], v[172:175], v[190:193], v[112:115]
	v_mfma_f32_16x16x32_bf16 v[100:103], v[148:151], v[202:205], v[100:103]
	v_mfma_f32_16x16x32_bf16 v[96:99], v[172:175], v[202:205], v[96:99]
	v_mfma_f32_16x16x32_bf16 v[84:87], v[148:151], v[210:213], v[84:87]
	v_mfma_f32_16x16x32_bf16 v[80:83], v[172:175], v[210:213], v[80:83]
	v_mfma_f32_16x16x32_bf16 v[68:71], v[148:151], v[218:221], v[68:71]
	v_mfma_f32_16x16x32_bf16 v[64:67], v[172:175], v[218:221], v[64:67]
	s_setprio 0
	s_barrier
	s_add_i32 s54, s47, s34
	v_lshl_add_u64 v[176:177], s[28:29], 0, v[154:155]
	s_mov_b32 m0, s54
	ds_read_b128 v[186:189], v183 offset:16384
	ds_read_b128 v[190:193], v183 offset:17408
	ds_read_b128 v[198:201], v183 offset:18432
	ds_read_b128 v[202:205], v183 offset:19456
	ds_read_b128 v[206:209], v183 offset:20480
	ds_read_b128 v[210:213], v183 offset:21504
	ds_read_b128 v[214:217], v183 offset:22528
	ds_read_b128 v[218:221], v183 offset:23552
	global_load_lds_dwordx4 v[176:177], off
	s_add_i32 m0, s54, 0x2000
	s_add_u32 s54, s28, 0x100000
	v_lshl_add_u64 v[194:195], s[28:29], 0, v[158:159]
	s_addc_u32 s55, s29, 0
	s_add_i32 s56, s50, s34
	global_load_lds_dwordx4 v[194:195], off
	v_lshl_add_u64 v[222:223], s[54:55], 0, v[154:155]
	s_mov_b32 m0, s56
	v_lshl_add_u64 v[224:225], s[30:31], 0, v[156:157]
	global_load_lds_dwordx4 v[222:223], off
	v_lshl_add_u64 v[222:223], s[54:55], 0, v[158:159]
	s_add_i32 m0, s56, 0x2000
	s_nop 0
	global_load_lds_dwordx4 v[222:223], off
	v_lshl_add_u64 v[222:223], s[30:31], 0, v[152:153]
	s_mov_b32 m0, s35
	s_nop 0
	global_load_lds_dwordx4 v[222:223], off
	s_mov_b32 m0, s33
	s_nop 0
	global_load_lds_dwordx4 v[224:225], off
	s_waitcnt vmcnt(8)
	s_waitcnt lgkmcnt(0)
	s_barrier
; #define PG8_STAGE(bufoff, gbase, voff) do { _Pragma("unroll") for (int _i = 0; _i < 2; ++_i) \
;         __builtin_amdgcn_global_load_lds((const unsigned*)((const char*)(gbase) + (voff)[_i]), (PG8_LAS unsigned*)(lds + (bufoff) + ldsw + _i * 8192), 16, 0, 0); } while (0)
; #define PG8_LDA(dst, b, h) do { _Pragma("unroll") for (int m = 0; m < 4; ++m) _Pragma("unroll") for (int k = 0; k < 2; ++k) dst[m][k] = *(const PG8_LAS bf16x8*)(lds + PG8_SA(b, h) + aoff + m * 2048 + k * 1024); } while (0)
; #define PG8_LDB(dst, b, h) do { _Pragma("unroll") for (int n = 0; n < 2; ++n) _Pragma("unroll") for (int k = 0; k < 2; ++k) dst[n][k] = *(const PG8_LAS bf16x8*)(lds + PG8_SB(b, h) + boff + n * 2048 + k * 1024); } while (0)
; #define PG8_MMA(ai, bj, At, Bt) do { __builtin_amdgcn_s_setprio(1); _Pragma("unroll") for (int m = 0; m < 4; ++m) _Pragma("unroll") for (int n = 0; n < 2; ++n) _Pragma("unroll") for (int k = 0; k < 2; ++k) \
;         acc[ai][bj][m][n] = __builtin_amdgcn_mfma_f32_16x16x32_bf16(Bt[n][k], At[m][k], acc[ai][bj][m][n], 0, 0, 0); __builtin_amdgcn_s_setprio(0); } while (0)
; #define PG8_WAIT_V(n) asm volatile("s_waitcnt vmcnt(" #n ")" ::: "memory")
; #define PG8_WAIT_L(n) asm volatile("s_waitcnt lgkmcnt(" #n ")" ::: "memory")
; #define PG8_BAR __builtin_amdgcn_s_barrier()
; #define PG8_SCHED __builtin_amdgcn_sched_barrier(0)
; template <class Epi, class Sched, bool ALIGN_EPI = false, bool SP2 = false>
; __device__ __forceinline__ void gemm_phase(PG8_LAS unsigned char* lds, const Gemm g, const Sched& S, const Epi& E) {
;     ...
;             PG8_WAIT_V(8); PG8_WAIT_L(0); PG8_BAR; PG8_MMA(1, 0, At, B0); PG8_MMA(1, 1, At, B1); PG8_BAR; PG8_SCHED;
;             PG8_LDB(B0, 1, 0); PG8_LDB(B1, 1, 1); PG8_SCHED; PG8_LDA(At, 1, 0); PG8_STAGE(PG8_SA(0, 1), a2 + hstep, voffA);
;             PG8_WAIT_V(8); PG8_WAIT_L(0); PG8_BAR; PG8_MMA(0, 0, At, B0); PG8_MMA(0, 1, At, B1); PG8_BAR; PG8_SCHED;
	s_setprio 1
	s_waitcnt lgkmcnt(0)
	v_mfma_f32_16x16x32_bf16 v[56:59], v[128:131], v[186:189], 0
	v_mfma_f32_16x16x32_bf16 v[60:63], v[136:139], v[186:189], 0
	v_mfma_f32_16x16x32_bf16 v[40:43], v[128:131], v[198:201], 0
	v_mfma_f32_16x16x32_bf16 v[44:47], v[136:139], v[198:201], 0
	v_mfma_f32_16x16x32_bf16 v[24:27], v[128:131], v[206:209], 0
	v_mfma_f32_16x16x32_bf16 v[28:31], v[136:139], v[206:209], 0
	v_mfma_f32_16x16x32_bf16 v[8:11], v[128:131], v[214:217], 0
	v_mfma_f32_16x16x32_bf16 v[12:15], v[136:139], v[214:217], 0
	v_mfma_f32_16x16x32_bf16 v[56:59], v[132:135], v[190:193], v[56:59]
	v_mfma_f32_16x16x32_bf16 v[60:63], v[140:143], v[190:193], v[60:63]
	v_mfma_f32_16x16x32_bf16 v[40:43], v[132:135], v[202:205], v[40:43]
	v_mfma_f32_16x16x32_bf16 v[44:47], v[140:143], v[202:205], v[44:47]
	v_mfma_f32_16x16x32_bf16 v[24:27], v[132:135], v[210:213], v[24:27]
	v_mfma_f32_16x16x32_bf16 v[28:31], v[140:143], v[210:213], v[28:31]
	v_mfma_f32_16x16x32_bf16 v[8:11], v[132:135], v[218:221], v[8:11]
	v_mfma_f32_16x16x32_bf16 v[12:15], v[140:143], v[218:221], v[12:15]
	s_setprio 0
	s_setprio 1
	v_mfma_f32_16x16x32_bf16 v[52:55], v[144:147], v[186:189], 0
	v_mfma_f32_16x16x32_bf16 v[48:51], v[168:171], v[186:189], 0
	v_mfma_f32_16x16x32_bf16 v[36:39], v[144:147], v[198:201], 0
	v_mfma_f32_16x16x32_bf16 v[32:35], v[168:171], v[198:201], 0
	v_mfma_f32_16x16x32_bf16 v[20:23], v[144:147], v[206:209], 0
	v_mfma_f32_16x16x32_bf16 v[16:19], v[168:171], v[206:209], 0
	v_mfma_f32_16x16x32_bf16 v[4:7], v[144:147], v[214:217], 0
	v_mfma_f32_16x16x32_bf16 v[0:3], v[168:171], v[214:217], 0
	v_mfma_f32_16x16x32_bf16 v[52:55], v[148:151], v[190:193], v[52:55]
	v_mfma_f32_16x16x32_bf16 v[48:51], v[172:175], v[190:193], v[48:51]
	v_mfma_f32_16x16x32_bf16 v[36:39], v[148:151], v[202:205], v[36:39]
	v_mfma_f32_16x16x32_bf16 v[32:35], v[172:175], v[202:205], v[32:35]
	v_mfma_f32_16x16x32_bf16 v[20:23], v[148:151], v[210:213], v[20:23]
	v_mfma_f32_16x16x32_bf16 v[16:19], v[172:175], v[210:213], v[16:19]
	v_mfma_f32_16x16x32_bf16 v[4:7], v[148:151], v[218:221], v[4:7]
	v_mfma_f32_16x16x32_bf16 v[0:3], v[172:175], v[218:221], v[0:3]
	s_setprio 0
	s_barrier
	s_add_i32 s54, 0, 0x18000
	s_add_i32 s55, 0, 0x1c000
	v_add_u32_e32 v140, s54, v179
	v_add_u32_e32 v172, s55, v179
	ds_read_b128 v[128:131], v140
	ds_read_b128 v[132:135], v140 offset:1024
	ds_read_b128 v[136:139], v140 offset:2048
	ds_read_b128 v[140:143], v140 offset:3072
	ds_read_b128 v[144:147], v172
	ds_read_b128 v[148:151], v172 offset:1024
	ds_read_b128 v[168:171], v172 offset:2048
	ds_read_b128 v[172:175], v172 offset:3072
	s_add_u32 s30, s30, 0x100000
	s_addc_u32 s31, s31, 0
	s_mov_b32 m0, s37
	v_lshl_add_u64 v[226:227], s[30:31], 0, v[152:153]
	ds_read_b128 v[186:189], v183 offset:32768
	ds_read_b128 v[190:193], v183 offset:33792
	ds_read_b128 v[198:201], v183 offset:34816
	ds_read_b128 v[202:205], v183 offset:35840
	ds_read_b128 v[206:209], v183 offset:36864
	ds_read_b128 v[210:213], v183 offset:37888
	ds_read_b128 v[214:217], v183 offset:38912
	ds_read_b128 v[218:221], v183 offset:39936
	global_load_lds_dwordx4 v[226:227], off
	v_lshl_add_u64 v[226:227], s[30:31], 0, v[156:157]
	s_mov_b32 m0, s39
	s_nop 0
	global_load_lds_dwordx4 v[226:227], off
	s_waitcnt vmcnt(8)
	s_waitcnt lgkmcnt(0)
	s_barrier
	s_setprio 1
	s_waitcnt lgkmcnt(0)
	v_mfma_f32_16x16x32_bf16 v[124:127], v[128:131], v[186:189], v[124:127]
	v_mfma_f32_16x16x32_bf16 v[120:123], v[136:139], v[186:189], v[120:123]
	v_mfma_f32_16x16x32_bf16 v[104:107], v[128:131], v[198:201], v[104:107]
	v_mfma_f32_16x16x32_bf16 v[108:111], v[136:139], v[198:201], v[108:111]
	v_mfma_f32_16x16x32_bf16 v[88:91], v[128:131], v[206:209], v[88:91]
	v_mfma_f32_16x16x32_bf16 v[92:95], v[136:139], v[206:209], v[92:95]
	v_mfma_f32_16x16x32_bf16 v[72:75], v[128:131], v[214:217], v[72:75]
	v_mfma_f32_16x16x32_bf16 v[76:79], v[136:139], v[214:217], v[76:79]
	v_mfma_f32_16x16x32_bf16 v[124:127], v[132:135], v[190:193], v[124:127]
	v_mfma_f32_16x16x32_bf16 v[120:123], v[140:143], v[190:193], v[120:123]
	v_mfma_f32_16x16x32_bf16 v[104:107], v[132:135], v[202:205], v[104:107]
	v_mfma_f32_16x16x32_bf16 v[108:111], v[140:143], v[202:205], v[108:111]
	v_mfma_f32_16x16x32_bf16 v[88:91], v[132:135], v[210:213], v[88:91]
	v_mfma_f32_16x16x32_bf16 v[92:95], v[140:143], v[210:213], v[92:95]
	v_mfma_f32_16x16x32_bf16 v[72:75], v[132:135], v[218:221], v[72:75]
	v_mfma_f32_16x16x32_bf16 v[76:79], v[140:143], v[218:221], v[76:79]
	s_setprio 0
	s_setprio 1
	v_mfma_f32_16x16x32_bf16 v[116:119], v[144:147], v[186:189], v[116:119]
	v_mfma_f32_16x16x32_bf16 v[112:115], v[168:171], v[186:189], v[112:115]
	v_mfma_f32_16x16x32_bf16 v[100:103], v[144:147], v[198:201], v[100:103]
	v_mfma_f32_16x16x32_bf16 v[96:99], v[168:171], v[198:201], v[96:99]
	v_mfma_f32_16x16x32_bf16 v[84:87], v[144:147], v[206:209], v[84:87]
	v_mfma_f32_16x16x32_bf16 v[80:83], v[168:171], v[206:209], v[80:83]
	v_mfma_f32_16x16x32_bf16 v[68:71], v[144:147], v[214:217], v[68:71]
	v_mfma_f32_16x16x32_bf16 v[64:67], v[168:171], v[214:217], v[64:67]
	v_mfma_f32_16x16x32_bf16 v[116:119], v[148:151], v[190:193], v[116:119]
	v_mfma_f32_16x16x32_bf16 v[112:115], v[172:175], v[190:193], v[112:115]
	v_mfma_f32_16x16x32_bf16 v[100:103], v[148:151], v[202:205], v[100:103]
	v_mfma_f32_16x16x32_bf16 v[96:99], v[172:175], v[202:205], v[96:99]
	v_mfma_f32_16x16x32_bf16 v[84:87], v[148:151], v[210:213], v[84:87]
	v_mfma_f32_16x16x32_bf16 v[80:83], v[172:175], v[210:213], v[80:83]
	v_mfma_f32_16x16x32_bf16 v[68:71], v[148:151], v[218:221], v[68:71]
	v_mfma_f32_16x16x32_bf16 v[64:67], v[172:175], v[218:221], v[64:67]
	s_setprio 0
	s_barrier
; #define PG8_STAGE(bufoff, gbase, voff) do { _Pragma("unroll") for (int _i = 0; _i < 2; ++_i) \
;         __builtin_amdgcn_global_load_lds((const unsigned*)((const char*)(gbase) + (voff)[_i]), (PG8_LAS unsigned*)(lds + (bufoff) + ldsw + _i * 8192), 16, 0, 0); } while (0)
; #define PG8_LDA(dst, b, h) do { _Pragma("unroll") for (int m = 0; m < 4; ++m) _Pragma("unroll") for (int k = 0; k < 2; ++k) dst[m][k] = *(const PG8_LAS bf16x8*)(lds + PG8_SA(b, h) + aoff + m * 2048 + k * 1024); } while (0)
; #define PG8_MMA(ai, bj, At, Bt) do { __builtin_amdgcn_s_setprio(1); _Pragma("unroll") for (int m = 0; m < 4; ++m) _Pragma("unroll") for (int n = 0; n < 2; ++n) _Pragma("unroll") for (int k = 0; k < 2; ++k) \
;         acc[ai][bj][m][n] = __builtin_amdgcn_mfma_f32_16x16x32_bf16(Bt[n][k], At[m][k], acc[ai][bj][m][n], 0, 0, 0); __builtin_amdgcn_s_setprio(0); } while (0)
; #define PG8_WAIT_V(n) asm volatile("s_waitcnt vmcnt(" #n ")" ::: "memory")
; #define PG8_WAIT_L(n) asm volatile("s_waitcnt lgkmcnt(" #n ")" ::: "memory")
; #define PG8_BAR __builtin_amdgcn_s_barrier()
; #define PG8_SCHED __builtin_amdgcn_sched_barrier(0)
; template <class Epi, class Sched, bool ALIGN_EPI = false, bool SP2 = false>
; __device__ __forceinline__ void gemm_phase(PG8_LAS unsigned char* lds, const Gemm g, const Sched& S, const Epi& E) {
;     ...
;             PG8_LDA(At, 1, 1); PG8_STAGE(PG8_SB(1, 0), b3, voffB); PG8_STAGE(PG8_SB(1, 1), b3 + hstep, voffB); PG8_STAGE(PG8_SA(1, 0), a3, voffA);
;             PG8_WAIT_V(8); PG8_WAIT_L(0); PG8_BAR; PG8_MMA(1, 0, At, B0); PG8_MMA(1, 1, At, B1); PG8_BAR; PG8_SCHED;
	s_add_i32 s30, s54, s34
	v_lshl_add_u64 v[176:177], v[176:177], 0, s[12:13]
	s_mov_b32 m0, s30
	ds_read_b128 v[186:189], v183 offset:49152
	ds_read_b128 v[190:193], v183 offset:50176
	ds_read_b128 v[198:201], v183 offset:51200
	ds_read_b128 v[202:205], v183 offset:52224
	ds_read_b128 v[206:209], v183 offset:53248
	ds_read_b128 v[210:213], v183 offset:54272
	ds_read_b128 v[214:217], v183 offset:55296
	ds_read_b128 v[218:221], v183 offset:56320
	global_load_lds_dwordx4 v[176:177], off
	s_add_i32 m0, s30, 0x2000
	s_add_u32 s28, s28, 0x100080
	v_lshl_add_u64 v[176:177], v[194:195], 0, s[12:13]
	s_addc_u32 s29, s29, 0
	s_add_i32 s30, s55, s34
	global_load_lds_dwordx4 v[176:177], off
	v_lshl_add_u64 v[176:177], s[28:29], 0, v[154:155]
	s_mov_b32 m0, s30
	s_nop 0
	global_load_lds_dwordx4 v[176:177], off
	v_lshl_add_u64 v[176:177], s[28:29], 0, v[158:159]
	s_add_i32 m0, s30, 0x2000
	s_nop 0
	global_load_lds_dwordx4 v[176:177], off
	v_lshl_add_u64 v[176:177], v[222:223], 0, s[12:13]
	s_mov_b32 m0, s43
	s_nop 0
	global_load_lds_dwordx4 v[176:177], off
	v_lshl_add_u64 v[176:177], v[224:225], 0, s[12:13]
	s_mov_b32 m0, s44
	s_nop 0
	global_load_lds_dwordx4 v[176:177], off
	s_waitcnt vmcnt(8)
	s_waitcnt lgkmcnt(0)
	s_barrier
	s_setprio 1
	s_waitcnt lgkmcnt(0)
	v_mfma_f32_16x16x32_bf16 v[56:59], v[128:131], v[186:189], v[56:59]
	v_mfma_f32_16x16x32_bf16 v[60:63], v[136:139], v[186:189], v[60:63]
	v_mfma_f32_16x16x32_bf16 v[40:43], v[128:131], v[198:201], v[40:43]
	v_mfma_f32_16x16x32_bf16 v[44:47], v[136:139], v[198:201], v[44:47]
	v_mfma_f32_16x16x32_bf16 v[24:27], v[128:131], v[206:209], v[24:27]
	v_mfma_f32_16x16x32_bf16 v[28:31], v[136:139], v[206:209], v[28:31]
	v_mfma_f32_16x16x32_bf16 v[8:11], v[128:131], v[214:217], v[8:11]
	v_mfma_f32_16x16x32_bf16 v[12:15], v[136:139], v[214:217], v[12:15]
	v_mfma_f32_16x16x32_bf16 v[56:59], v[132:135], v[190:193], v[56:59]
	v_mfma_f32_16x16x32_bf16 v[60:63], v[140:143], v[190:193], v[60:63]
	v_mfma_f32_16x16x32_bf16 v[40:43], v[132:135], v[202:205], v[40:43]
	v_mfma_f32_16x16x32_bf16 v[44:47], v[140:143], v[202:205], v[44:47]
	v_mfma_f32_16x16x32_bf16 v[24:27], v[132:135], v[210:213], v[24:27]
	v_mfma_f32_16x16x32_bf16 v[28:31], v[140:143], v[210:213], v[28:31]
	v_mfma_f32_16x16x32_bf16 v[8:11], v[132:135], v[218:221], v[8:11]
	v_mfma_f32_16x16x32_bf16 v[12:15], v[140:143], v[218:221], v[12:15]
	s_setprio 0
	s_setprio 1
	v_mfma_f32_16x16x32_bf16 v[52:55], v[144:147], v[186:189], v[52:55]
	v_mfma_f32_16x16x32_bf16 v[48:51], v[168:171], v[186:189], v[48:51]
	v_mfma_f32_16x16x32_bf16 v[36:39], v[144:147], v[198:201], v[36:39]
	v_mfma_f32_16x16x32_bf16 v[32:35], v[168:171], v[198:201], v[32:35]
	v_mfma_f32_16x16x32_bf16 v[20:23], v[144:147], v[206:209], v[20:23]
	v_mfma_f32_16x16x32_bf16 v[16:19], v[168:171], v[206:209], v[16:19]
	v_mfma_f32_16x16x32_bf16 v[4:7], v[144:147], v[214:217], v[4:7]
	v_mfma_f32_16x16x32_bf16 v[0:3], v[168:171], v[214:217], v[0:3]
	v_mfma_f32_16x16x32_bf16 v[52:55], v[148:151], v[190:193], v[52:55]
	v_mfma_f32_16x16x32_bf16 v[48:51], v[172:175], v[190:193], v[48:51]
	v_mfma_f32_16x16x32_bf16 v[36:39], v[148:151], v[202:205], v[36:39]
	v_mfma_f32_16x16x32_bf16 v[32:35], v[172:175], v[202:205], v[32:35]
	v_mfma_f32_16x16x32_bf16 v[20:23], v[148:151], v[210:213], v[20:23]
	v_mfma_f32_16x16x32_bf16 v[16:19], v[172:175], v[210:213], v[16:19]
	v_mfma_f32_16x16x32_bf16 v[4:7], v[148:151], v[218:221], v[4:7]
	v_mfma_f32_16x16x32_bf16 v[0:3], v[172:175], v[218:221], v[0:3]
	s_setprio 0
	s_barrier
	s_add_i32 s53, s53, 2
	s_add_u32 s26, s26, 0x100
	s_addc_u32 s27, s27, 0
	s_add_u32 s49, s49, 0x100
	s_addc_u32 s52, s52, 0

; #define PG8_STAGE(bufoff, gbase, voff) do { _Pragma("unroll") for (int _i = 0; _i < 2; ++_i) \
;         __builtin_amdgcn_global_load_lds((const unsigned*)((const char*)(gbase) + (voff)[_i]), (PG8_LAS unsigned*)(lds + (bufoff) + ldsw + _i * 8192), 16, 0, 0); } while (0)
; #define PG8_LDA(dst, b, h) do { _Pragma("unroll") for (int m = 0; m < 4; ++m) _Pragma("unroll") for (int k = 0; k < 2; ++k) dst[m][k] = *(const PG8_LAS bf16x8*)(lds + PG8_SA(b, h) + aoff + m * 2048 + k * 1024); } while (0)
; #define PG8_LDB(dst, b, h) do { _Pragma("unroll") for (int n = 0; n < 2; ++n) _Pragma("unroll") for (int k = 0; k < 2; ++k) dst[n][k] = *(const PG8_LAS bf16x8*)(lds + PG8_SB(b, h) + boff + n * 2048 + k * 1024); } while (0)
; #define PG8_MMA(ai, bj, At, Bt) do { __builtin_amdgcn_s_setprio(1); _Pragma("unroll") for (int m = 0; m < 4; ++m) _Pragma("unroll") for (int n = 0; n < 2; ++n) _Pragma("unroll") for (int k = 0; k < 2; ++k) \
;         acc[ai][bj][m][n] = __builtin_amdgcn_mfma_f32_16x16x32_bf16(Bt[n][k], At[m][k], acc[ai][bj][m][n], 0, 0, 0); __builtin_amdgcn_s_setprio(0); } while (0)
; #define PG8_WAIT_V(n) asm volatile("s_waitcnt vmcnt(" #n ")" ::: "memory")
; #define PG8_BAR __builtin_amdgcn_s_barrier()
; template <class Epi, class Sched, bool ALIGN_EPI = false, bool SP2 = false>
; __device__ __forceinline__ void gemm_phase(PG8_LAS unsigned char* lds, const Gemm g, const Sched& S, const Epi& E) {
;     ...
;         for (int t = 0; t < nt; t += 2) {
;             const bool last = (t == nt - 2);
;             const char* a1 = cA + (size_t)(t + 1) * kstep;
;             const char* a2 = last ? nA : cA + (size_t)(t + 2) * kstep; const char* b2 = last ? nB : cB + (size_t)(t + 2) * kstep;
;             const char* a3 = a2 + kstep; const char* b3 = b2 + kstep;
;             if (last && has_next) S.a_ready(nxt);
;             if constexpr (SP2) {
;             PG8_LDB(B0, 0, 0); PG8_LDB(B1, 0, 1); PG8_SCHED; PG8_LDA(At, 0, 0); PG8_STAGE(PG8_SA(1, 1), a1 + hstep, voffA);
;             PG8_WAIT_V(8); PG8_WAIT_L(0); PG8_BAR; PG8_MMA(0, 0, At, B0); PG8_MMA(0, 1, At, B1); PG8_BAR; PG8_SCHED;
;             PG8_LDA(At, 0, 1); PG8_STAGE(PG8_SB(0, 0), b2, voffB); PG8_STAGE(PG8_SB(0, 1), b2 + hstep, voffB); PG8_STAGE(PG8_SA(0, 0), a2, voffA);
;             PG8_WAIT_V(8); PG8_WAIT_L(0); PG8_BAR; PG8_MMA(1, 0, At, B0); PG8_MMA(1, 1, At, B1); PG8_BAR; PG8_SCHED;
.LBB0_954:
	s_ashr_i32 s53, s52, 31
	s_lshl_b64 s[22:23], s[52:53], 20
	s_add_u32 s54, s74, s22
	s_addc_u32 s55, s75, s23
	s_and_b64 s[24:25], s[62:63], exec
	s_cselect_b32 s1, s55, s27
	s_cselect_b32 s5, s54, s26
	s_ashr_i32 s41, s40, 31
	s_lshl_b64 s[24:25], s[40:41], 20
	s_add_u32 s56, s94, s24
	s_addc_u32 s57, s95, s25
	s_and_b64 s[30:31], s[62:63], exec
	s_cselect_b32 s17, s57, s29
	s_cselect_b32 s19, s56, s28
	s_add_u32 s26, s26, 0x80080
	s_addc_u32 s27, s27, 0
	s_add_u32 s33, s28, 0x100
	s_addc_u32 s44, s29, 0
	s_mov_b32 s45, -2
	s_waitcnt vmcnt(0)
	ds_read_b128 v[128:131], v209
	ds_read_b128 v[132:135], v209 offset:1024
	ds_read_b128 v[136:139], v209 offset:2048
	ds_read_b128 v[178:181], v209 offset:3072
	ds_read_b128 v[182:185], v210
	ds_read_b128 v[186:189], v210 offset:1024
	ds_read_b128 v[190:193], v210 offset:2048
	ds_read_b128 v[222:225], v210 offset:3072
	s_add_u32 s28, s26, 0xfff80080
	s_addc_u32 s29, s27, -1
	s_cmp_eq_u32 s45, 28
	s_cselect_b32 s31, s1, s29
	s_cselect_b32 s30, s5, s28
	s_cselect_b32 s29, s17, s44
	s_cselect_b32 s28, s19, s33
	v_lshl_add_u64 v[166:167], s[26:27], 0, v[150:151]
	s_add_i32 m0, s35, 0xc000
	ds_read_b128 v[226:229], v211
	ds_read_b128 v[230:233], v211 offset:1024
	ds_read_b128 v[234:237], v211 offset:2048
	ds_read_b128 v[238:241], v211 offset:3072
	ds_read_b128 v[242:245], v211 offset:4096
	ds_read_b128 v[246:249], v211 offset:5120
	ds_read_b128 v[250:253], v211 offset:6144
	ds_read_b128 v[160:163], v211 offset:7168
	global_load_lds_dwordx4 v[166:167], off
	v_lshl_add_u64 v[166:167], s[26:27], 0, v[152:153]
	s_add_i32 m0, s35, 0xe000
	s_nop 0
	global_load_lds_dwordx4 v[166:167], off
	s_waitcnt vmcnt(8)
	s_waitcnt lgkmcnt(0)
	s_barrier
	s_setprio 1
	s_waitcnt lgkmcnt(0)
	v_mfma_f32_16x16x32_bf16 v[124:127], v[128:131], v[226:229], 0
	v_mfma_f32_16x16x32_bf16 v[120:123], v[136:139], v[226:229], 0
	v_mfma_f32_16x16x32_bf16 v[116:119], v[128:131], v[234:237], 0
	v_mfma_f32_16x16x32_bf16 v[108:111], v[136:139], v[234:237], 0
	v_mfma_f32_16x16x32_bf16 v[100:103], v[128:131], v[242:245], 0
	v_mfma_f32_16x16x32_bf16 v[92:95], v[136:139], v[242:245], 0
	v_mfma_f32_16x16x32_bf16 v[84:87], v[128:131], v[250:253], 0
	v_mfma_f32_16x16x32_bf16 v[76:79], v[136:139], v[250:253], 0
	v_mfma_f32_16x16x32_bf16 v[124:127], v[132:135], v[230:233], v[124:127]
	v_mfma_f32_16x16x32_bf16 v[120:123], v[178:181], v[230:233], v[120:123]
	v_mfma_f32_16x16x32_bf16 v[116:119], v[132:135], v[238:241], v[116:119]
	v_mfma_f32_16x16x32_bf16 v[108:111], v[178:181], v[238:241], v[108:111]
	v_mfma_f32_16x16x32_bf16 v[100:103], v[132:135], v[246:249], v[100:103]
	v_mfma_f32_16x16x32_bf16 v[92:95], v[178:181], v[246:249], v[92:95]
	v_mfma_f32_16x16x32_bf16 v[84:87], v[132:135], v[160:163], v[84:87]
	v_mfma_f32_16x16x32_bf16 v[76:79], v[178:181], v[160:163], v[76:79]
	s_setprio 0
	s_setprio 1
	v_mfma_f32_16x16x32_bf16 v[112:115], v[182:185], v[226:229], 0
	v_mfma_f32_16x16x32_bf16 v[104:107], v[190:193], v[226:229], 0
	v_mfma_f32_16x16x32_bf16 v[96:99], v[182:185], v[234:237], 0
	v_mfma_f32_16x16x32_bf16 v[88:91], v[190:193], v[234:237], 0
	v_mfma_f32_16x16x32_bf16 v[80:83], v[182:185], v[242:245], 0
	v_mfma_f32_16x16x32_bf16 v[72:75], v[190:193], v[242:245], 0
	v_mfma_f32_16x16x32_bf16 v[68:71], v[182:185], v[250:253], 0
	v_mfma_f32_16x16x32_bf16 v[64:67], v[190:193], v[250:253], 0
	v_mfma_f32_16x16x32_bf16 v[112:115], v[186:189], v[230:233], v[112:115]
	v_mfma_f32_16x16x32_bf16 v[104:107], v[222:225], v[230:233], v[104:107]
	v_mfma_f32_16x16x32_bf16 v[96:99], v[186:189], v[238:241], v[96:99]
	v_mfma_f32_16x16x32_bf16 v[88:91], v[222:225], v[238:241], v[88:91]
	v_mfma_f32_16x16x32_bf16 v[80:83], v[186:189], v[246:249], v[80:83]
	v_mfma_f32_16x16x32_bf16 v[72:75], v[222:225], v[246:249], v[72:75]
	v_mfma_f32_16x16x32_bf16 v[68:71], v[186:189], v[160:163], v[68:71]
	v_mfma_f32_16x16x32_bf16 v[64:67], v[222:225], v[160:163], v[64:67]
	s_setprio 0
	s_barrier
	s_add_i32 s48, s69, s34
	v_lshl_add_u64 v[166:167], s[28:29], 0, v[142:143]
	s_mov_b32 m0, s48
	ds_read_b128 v[160:163], v211 offset:16384
	ds_read_b128 v[226:229], v211 offset:17408
	ds_read_b128 v[230:233], v211 offset:18432
	ds_read_b128 v[234:237], v211 offset:19456
	ds_read_b128 v[238:241], v211 offset:20480
	ds_read_b128 v[242:245], v211 offset:21504
	ds_read_b128 v[246:249], v211 offset:22528
	ds_read_b128 v[250:253], v211 offset:23552
	global_load_lds_dwordx4 v[166:167], off
	s_add_i32 m0, s48, 0x2000
	s_add_u32 s48, s28, 0x80000
	v_lshl_add_u64 v[170:171], s[28:29], 0, v[146:147]
	s_addc_u32 s49, s29, 0
	s_add_i32 s50, s70, s34
	global_load_lds_dwordx4 v[170:171], off
	v_lshl_add_u64 v[174:175], s[48:49], 0, v[142:143]
	s_mov_b32 m0, s50
	v_lshl_add_u64 v[194:195], s[30:31], 0, v[144:145]
	global_load_lds_dwordx4 v[174:175], off
	v_lshl_add_u64 v[174:175], s[48:49], 0, v[146:147]
	s_add_i32 m0, s50, 0x2000
	s_nop 0
	global_load_lds_dwordx4 v[174:175], off
	v_lshl_add_u64 v[174:175], s[30:31], 0, v[140:141]
	s_mov_b32 m0, s35
	s_nop 0
	global_load_lds_dwordx4 v[174:175], off
	s_mov_b32 m0, s37
	s_nop 0
	global_load_lds_dwordx4 v[194:195], off
	s_waitcnt vmcnt(8)
	s_waitcnt lgkmcnt(0)
	s_barrier
; #define PG8_STAGE(bufoff, gbase, voff) do { _Pragma("unroll") for (int _i = 0; _i < 2; ++_i) \
;         __builtin_amdgcn_global_load_lds((const unsigned*)((const char*)(gbase) + (voff)[_i]), (PG8_LAS unsigned*)(lds + (bufoff) + ldsw + _i * 8192), 16, 0, 0); } while (0)
; #define PG8_LDA(dst, b, h) do { _Pragma("unroll") for (int m = 0; m < 4; ++m) _Pragma("unroll") for (int k = 0; k < 2; ++k) dst[m][k] = *(const PG8_LAS bf16x8*)(lds + PG8_SA(b, h) + aoff + m * 2048 + k * 1024); } while (0)
; #define PG8_LDB(dst, b, h) do { _Pragma("unroll") for (int n = 0; n < 2; ++n) _Pragma("unroll") for (int k = 0; k < 2; ++k) dst[n][k] = *(const PG8_LAS bf16x8*)(lds + PG8_SB(b, h) + boff + n * 2048 + k * 1024); } while (0)
; #define PG8_MMA(ai, bj, At, Bt) do { __builtin_amdgcn_s_setprio(1); _Pragma("unroll") for (int m = 0; m < 4; ++m) _Pragma("unroll") for (int n = 0; n < 2; ++n) _Pragma("unroll") for (int k = 0; k < 2; ++k) \
;         acc[ai][bj][m][n] = __builtin_amdgcn_mfma_f32_16x16x32_bf16(Bt[n][k], At[m][k], acc[ai][bj][m][n], 0, 0, 0); __builtin_amdgcn_s_setprio(0); } while (0)
; #define PG8_WAIT_V(n) asm volatile("s_waitcnt vmcnt(" #n ")" ::: "memory")
; #define PG8_WAIT_L(n) asm volatile("s_waitcnt lgkmcnt(" #n ")" ::: "memory")
; #define PG8_BAR __builtin_amdgcn_s_barrier()
; #define PG8_SCHED __builtin_amdgcn_sched_barrier(0)
; template <class Epi, class Sched, bool ALIGN_EPI = false, bool SP2 = false>
; __device__ __forceinline__ void gemm_phase(PG8_LAS unsigned char* lds, const Gemm g, const Sched& S, const Epi& E) {
;     ...
;             PG8_WAIT_V(8); PG8_WAIT_L(0); PG8_BAR; PG8_MMA(1, 0, At, B0); PG8_MMA(1, 1, At, B1); PG8_BAR; PG8_SCHED;
;             PG8_LDB(B0, 1, 0); PG8_LDB(B1, 1, 1); PG8_SCHED; PG8_LDA(At, 1, 0); PG8_STAGE(PG8_SA(0, 1), a2 + hstep, voffA);
;             PG8_WAIT_V(8); PG8_WAIT_L(0); PG8_BAR; PG8_MMA(0, 0, At, B0); PG8_MMA(0, 1, At, B1); PG8_BAR; PG8_SCHED;
	s_setprio 1
	s_waitcnt lgkmcnt(0)
	v_mfma_f32_16x16x32_bf16 v[60:63], v[128:131], v[160:163], 0
	v_mfma_f32_16x16x32_bf16 v[56:59], v[136:139], v[160:163], 0
	v_mfma_f32_16x16x32_bf16 v[52:55], v[128:131], v[230:233], 0
	v_mfma_f32_16x16x32_bf16 v[44:47], v[136:139], v[230:233], 0
	v_mfma_f32_16x16x32_bf16 v[36:39], v[128:131], v[238:241], 0
	v_mfma_f32_16x16x32_bf16 v[28:31], v[136:139], v[238:241], 0
	v_mfma_f32_16x16x32_bf16 v[20:23], v[128:131], v[246:249], 0
	v_mfma_f32_16x16x32_bf16 v[12:15], v[136:139], v[246:249], 0
	v_mfma_f32_16x16x32_bf16 v[60:63], v[132:135], v[226:229], v[60:63]
	v_mfma_f32_16x16x32_bf16 v[56:59], v[178:181], v[226:229], v[56:59]
	v_mfma_f32_16x16x32_bf16 v[52:55], v[132:135], v[234:237], v[52:55]
	v_mfma_f32_16x16x32_bf16 v[44:47], v[178:181], v[234:237], v[44:47]
	v_mfma_f32_16x16x32_bf16 v[36:39], v[132:135], v[242:245], v[36:39]
	v_mfma_f32_16x16x32_bf16 v[28:31], v[178:181], v[242:245], v[28:31]
	v_mfma_f32_16x16x32_bf16 v[20:23], v[132:135], v[250:253], v[20:23]
	v_mfma_f32_16x16x32_bf16 v[12:15], v[178:181], v[250:253], v[12:15]
	s_setprio 0
	s_setprio 1
	v_mfma_f32_16x16x32_bf16 v[48:51], v[182:185], v[160:163], 0
	v_mfma_f32_16x16x32_bf16 v[40:43], v[190:193], v[160:163], 0
	v_mfma_f32_16x16x32_bf16 v[32:35], v[182:185], v[230:233], 0
	v_mfma_f32_16x16x32_bf16 v[24:27], v[190:193], v[230:233], 0
	v_mfma_f32_16x16x32_bf16 v[16:19], v[182:185], v[238:241], 0
	v_mfma_f32_16x16x32_bf16 v[8:11], v[190:193], v[238:241], 0
	v_mfma_f32_16x16x32_bf16 v[4:7], v[182:185], v[246:249], 0
	v_mfma_f32_16x16x32_bf16 v[0:3], v[190:193], v[246:249], 0
	v_mfma_f32_16x16x32_bf16 v[48:51], v[186:189], v[226:229], v[48:51]
	v_mfma_f32_16x16x32_bf16 v[40:43], v[222:225], v[226:229], v[40:43]
	v_mfma_f32_16x16x32_bf16 v[32:35], v[186:189], v[234:237], v[32:35]
	v_mfma_f32_16x16x32_bf16 v[24:27], v[222:225], v[234:237], v[24:27]
	v_mfma_f32_16x16x32_bf16 v[16:19], v[186:189], v[242:245], v[16:19]
	v_mfma_f32_16x16x32_bf16 v[8:11], v[222:225], v[242:245], v[8:11]
	v_mfma_f32_16x16x32_bf16 v[4:7], v[186:189], v[250:253], v[4:7]
	v_mfma_f32_16x16x32_bf16 v[0:3], v[222:225], v[250:253], v[0:3]
	s_setprio 0
	s_barrier
	s_add_i32 s48, 0, 0x18000
	v_add_u32_e32 v148, s48, v159
	s_add_i32 s49, 0, 0x1c000
	ds_read_b128 v[128:131], v148
	ds_read_b128 v[132:135], v148 offset:1024
	ds_read_b128 v[136:139], v148 offset:2048
	ds_read_b128 v[160:163], v148 offset:3072
	v_add_u32_e32 v148, s49, v159
	ds_read_b128 v[178:181], v148
	ds_read_b128 v[182:185], v148 offset:1024
	ds_read_b128 v[186:189], v148 offset:2048
	ds_read_b128 v[190:193], v148 offset:3072
	s_add_u32 s30, s30, 0x80000
	s_addc_u32 s31, s31, 0
	s_mov_b32 m0, s39
	v_lshl_add_u64 v[154:155], s[30:31], 0, v[140:141]
	ds_read_b128 v[222:225], v211 offset:32768
	ds_read_b128 v[226:229], v211 offset:33792
	ds_read_b128 v[230:233], v211 offset:34816
	ds_read_b128 v[234:237], v211 offset:35840
	ds_read_b128 v[238:241], v211 offset:36864
	ds_read_b128 v[242:245], v211 offset:37888
	ds_read_b128 v[246:249], v211 offset:38912
	ds_read_b128 v[250:253], v211 offset:39936
	global_load_lds_dwordx4 v[154:155], off
	v_lshl_add_u64 v[154:155], s[30:31], 0, v[144:145]
	s_mov_b32 m0, s42
	s_nop 0
	global_load_lds_dwordx4 v[154:155], off
	s_waitcnt vmcnt(8)
	s_waitcnt lgkmcnt(0)
	s_barrier
	s_setprio 1
	s_waitcnt lgkmcnt(0)
	v_mfma_f32_16x16x32_bf16 v[124:127], v[128:131], v[222:225], v[124:127]
	v_mfma_f32_16x16x32_bf16 v[120:123], v[136:139], v[222:225], v[120:123]
	v_mfma_f32_16x16x32_bf16 v[116:119], v[128:131], v[230:233], v[116:119]
	v_mfma_f32_16x16x32_bf16 v[108:111], v[136:139], v[230:233], v[108:111]
	v_mfma_f32_16x16x32_bf16 v[100:103], v[128:131], v[238:241], v[100:103]
	v_mfma_f32_16x16x32_bf16 v[92:95], v[136:139], v[238:241], v[92:95]
	v_mfma_f32_16x16x32_bf16 v[84:87], v[128:131], v[246:249], v[84:87]
	v_mfma_f32_16x16x32_bf16 v[76:79], v[136:139], v[246:249], v[76:79]
	v_mfma_f32_16x16x32_bf16 v[124:127], v[132:135], v[226:229], v[124:127]
	v_mfma_f32_16x16x32_bf16 v[120:123], v[160:163], v[226:229], v[120:123]
	v_mfma_f32_16x16x32_bf16 v[116:119], v[132:135], v[234:237], v[116:119]
	v_mfma_f32_16x16x32_bf16 v[108:111], v[160:163], v[234:237], v[108:111]
	v_mfma_f32_16x16x32_bf16 v[100:103], v[132:135], v[242:245], v[100:103]
	v_mfma_f32_16x16x32_bf16 v[92:95], v[160:163], v[242:245], v[92:95]
	v_mfma_f32_16x16x32_bf16 v[84:87], v[132:135], v[250:253], v[84:87]
	v_mfma_f32_16x16x32_bf16 v[76:79], v[160:163], v[250:253], v[76:79]
	s_setprio 0
	s_setprio 1
	v_mfma_f32_16x16x32_bf16 v[112:115], v[178:181], v[222:225], v[112:115]
	v_mfma_f32_16x16x32_bf16 v[104:107], v[186:189], v[222:225], v[104:107]
	v_mfma_f32_16x16x32_bf16 v[96:99], v[178:181], v[230:233], v[96:99]
	v_mfma_f32_16x16x32_bf16 v[88:91], v[186:189], v[230:233], v[88:91]
	v_mfma_f32_16x16x32_bf16 v[80:83], v[178:181], v[238:241], v[80:83]
	v_mfma_f32_16x16x32_bf16 v[72:75], v[186:189], v[238:241], v[72:75]
	v_mfma_f32_16x16x32_bf16 v[68:71], v[178:181], v[246:249], v[68:71]
	v_mfma_f32_16x16x32_bf16 v[64:67], v[186:189], v[246:249], v[64:67]
	v_mfma_f32_16x16x32_bf16 v[112:115], v[182:185], v[226:229], v[112:115]
	v_mfma_f32_16x16x32_bf16 v[104:107], v[190:193], v[226:229], v[104:107]
	v_mfma_f32_16x16x32_bf16 v[96:99], v[182:185], v[234:237], v[96:99]
	v_mfma_f32_16x16x32_bf16 v[88:91], v[190:193], v[234:237], v[88:91]
	v_mfma_f32_16x16x32_bf16 v[80:83], v[182:185], v[242:245], v[80:83]
	v_mfma_f32_16x16x32_bf16 v[72:75], v[190:193], v[242:245], v[72:75]
	v_mfma_f32_16x16x32_bf16 v[68:71], v[182:185], v[250:253], v[68:71]
	v_mfma_f32_16x16x32_bf16 v[64:67], v[190:193], v[250:253], v[64:67]
	s_setprio 0
	s_barrier
; #define PG8_STAGE(bufoff, gbase, voff) do { _Pragma("unroll") for (int _i = 0; _i < 2; ++_i) \
;         __builtin_amdgcn_global_load_lds((const unsigned*)((const char*)(gbase) + (voff)[_i]), (PG8_LAS unsigned*)(lds + (bufoff) + ldsw + _i * 8192), 16, 0, 0); } while (0)
; #define PG8_LDA(dst, b, h) do { _Pragma("unroll") for (int m = 0; m < 4; ++m) _Pragma("unroll") for (int k = 0; k < 2; ++k) dst[m][k] = *(const PG8_LAS bf16x8*)(lds + PG8_SA(b, h) + aoff + m * 2048 + k * 1024); } while (0)
; #define PG8_MMA(ai, bj, At, Bt) do { __builtin_amdgcn_s_setprio(1); _Pragma("unroll") for (int m = 0; m < 4; ++m) _Pragma("unroll") for (int n = 0; n < 2; ++n) _Pragma("unroll") for (int k = 0; k < 2; ++k) \
;         acc[ai][bj][m][n] = __builtin_amdgcn_mfma_f32_16x16x32_bf16(Bt[n][k], At[m][k], acc[ai][bj][m][n], 0, 0, 0); __builtin_amdgcn_s_setprio(0); } while (0)
; #define PG8_WAIT_V(n) asm volatile("s_waitcnt vmcnt(" #n ")" ::: "memory")
; #define PG8_WAIT_L(n) asm volatile("s_waitcnt lgkmcnt(" #n ")" ::: "memory")
; #define PG8_BAR __builtin_amdgcn_s_barrier()
; #define PG8_SCHED __builtin_amdgcn_sched_barrier(0)
; template <class Epi, class Sched, bool ALIGN_EPI = false, bool SP2 = false>
; __device__ __forceinline__ void gemm_phase(PG8_LAS unsigned char* lds, const Gemm g, const Sched& S, const Epi& E) {
;     ...
;             PG8_LDA(At, 1, 1); PG8_STAGE(PG8_SB(1, 0), b3, voffB); PG8_STAGE(PG8_SB(1, 1), b3 + hstep, voffB); PG8_STAGE(PG8_SA(1, 0), a3, voffA);
;             PG8_WAIT_V(8); PG8_WAIT_L(0); PG8_BAR; PG8_MMA(1, 0, At, B0); PG8_MMA(1, 1, At, B1); PG8_BAR; PG8_SCHED;
	s_add_i32 s30, s48, s34
	v_lshl_add_u64 v[154:155], v[166:167], 0, s[10:11]
	s_mov_b32 m0, s30
	ds_read_b128 v[222:225], v211 offset:49152
	ds_read_b128 v[226:229], v211 offset:50176
	ds_read_b128 v[230:233], v211 offset:51200
	ds_read_b128 v[234:237], v211 offset:52224
	ds_read_b128 v[238:241], v211 offset:53248
	ds_read_b128 v[242:245], v211 offset:54272
	ds_read_b128 v[246:249], v211 offset:55296
	ds_read_b128 v[250:253], v211 offset:56320
	global_load_lds_dwordx4 v[154:155], off
	s_add_i32 m0, s30, 0x2000
	s_add_u32 s28, s28, 0x80080
	v_lshl_add_u64 v[154:155], v[170:171], 0, s[10:11]
	s_addc_u32 s29, s29, 0
	s_add_i32 s30, s49, s34
	global_load_lds_dwordx4 v[154:155], off
	v_lshl_add_u64 v[154:155], s[28:29], 0, v[142:143]
	s_mov_b32 m0, s30
	s_nop 0
	global_load_lds_dwordx4 v[154:155], off
	v_lshl_add_u64 v[154:155], s[28:29], 0, v[146:147]
	s_add_i32 m0, s30, 0x2000
	s_nop 0
	global_load_lds_dwordx4 v[154:155], off
	v_lshl_add_u64 v[154:155], v[174:175], 0, s[10:11]
	s_mov_b32 m0, s46
	s_nop 0
	global_load_lds_dwordx4 v[154:155], off
	v_lshl_add_u64 v[154:155], v[194:195], 0, s[10:11]
	s_mov_b32 m0, s47
	s_nop 0
	global_load_lds_dwordx4 v[154:155], off
	s_waitcnt vmcnt(8)
	s_waitcnt lgkmcnt(0)
	s_barrier
	s_setprio 1
	s_waitcnt lgkmcnt(0)
	v_mfma_f32_16x16x32_bf16 v[60:63], v[128:131], v[222:225], v[60:63]
	v_mfma_f32_16x16x32_bf16 v[56:59], v[136:139], v[222:225], v[56:59]
	v_mfma_f32_16x16x32_bf16 v[52:55], v[128:131], v[230:233], v[52:55]
	v_mfma_f32_16x16x32_bf16 v[44:47], v[136:139], v[230:233], v[44:47]
	v_mfma_f32_16x16x32_bf16 v[36:39], v[128:131], v[238:241], v[36:39]
	v_mfma_f32_16x16x32_bf16 v[28:31], v[136:139], v[238:241], v[28:31]
	v_mfma_f32_16x16x32_bf16 v[20:23], v[128:131], v[246:249], v[20:23]
	v_mfma_f32_16x16x32_bf16 v[12:15], v[136:139], v[246:249], v[12:15]
	v_mfma_f32_16x16x32_bf16 v[60:63], v[132:135], v[226:229], v[60:63]
	v_mfma_f32_16x16x32_bf16 v[56:59], v[160:163], v[226:229], v[56:59]
	v_mfma_f32_16x16x32_bf16 v[52:55], v[132:135], v[234:237], v[52:55]
	v_mfma_f32_16x16x32_bf16 v[44:47], v[160:163], v[234:237], v[44:47]
	v_mfma_f32_16x16x32_bf16 v[36:39], v[132:135], v[242:245], v[36:39]
	v_mfma_f32_16x16x32_bf16 v[28:31], v[160:163], v[242:245], v[28:31]
	v_mfma_f32_16x16x32_bf16 v[20:23], v[132:135], v[250:253], v[20:23]
	v_mfma_f32_16x16x32_bf16 v[12:15], v[160:163], v[250:253], v[12:15]
	s_setprio 0
	s_setprio 1
	v_mfma_f32_16x16x32_bf16 v[48:51], v[178:181], v[222:225], v[48:51]
	v_mfma_f32_16x16x32_bf16 v[40:43], v[186:189], v[222:225], v[40:43]
	v_mfma_f32_16x16x32_bf16 v[32:35], v[178:181], v[230:233], v[32:35]
	v_mfma_f32_16x16x32_bf16 v[24:27], v[186:189], v[230:233], v[24:27]
	v_mfma_f32_16x16x32_bf16 v[16:19], v[178:181], v[238:241], v[16:19]
	v_mfma_f32_16x16x32_bf16 v[8:11], v[186:189], v[238:241], v[8:11]
	v_mfma_f32_16x16x32_bf16 v[4:7], v[178:181], v[246:249], v[4:7]
	v_mfma_f32_16x16x32_bf16 v[0:3], v[186:189], v[246:249], v[0:3]
	v_mfma_f32_16x16x32_bf16 v[48:51], v[182:185], v[226:229], v[48:51]
	v_mfma_f32_16x16x32_bf16 v[40:43], v[190:193], v[226:229], v[40:43]
	v_mfma_f32_16x16x32_bf16 v[32:35], v[182:185], v[234:237], v[32:35]
	v_mfma_f32_16x16x32_bf16 v[24:27], v[190:193], v[234:237], v[24:27]
	v_mfma_f32_16x16x32_bf16 v[16:19], v[182:185], v[242:245], v[16:19]
	v_mfma_f32_16x16x32_bf16 v[8:11], v[190:193], v[242:245], v[8:11]
	v_mfma_f32_16x16x32_bf16 v[4:7], v[182:185], v[250:253], v[4:7]
	v_mfma_f32_16x16x32_bf16 v[0:3], v[190:193], v[250:253], v[0:3]
	s_setprio 0
	s_barrier
	s_add_i32 s45, s45, 2
	s_add_u32 s26, s26, 0x100
	s_addc_u32 s27, s27, 0
	s_add_u32 s33, s33, 0x100
	s_addc_u32 s44, s44, 0

; #define PG8_STAGE(bufoff, gbase, voff) do { _Pragma("unroll") for (int _i = 0; _i < 2; ++_i) \
;         __builtin_amdgcn_global_load_lds((const unsigned*)((const char*)(gbase) + (voff)[_i]), (PG8_LAS unsigned*)(lds + (bufoff) + ldsw + _i * 8192), 16, 0, 0); } while (0)
; #define PG8_LDA(dst, b, h) do { _Pragma("unroll") for (int m = 0; m < 4; ++m) _Pragma("unroll") for (int k = 0; k < 2; ++k) dst[m][k] = *(const PG8_LAS bf16x8*)(lds + PG8_SA(b, h) + aoff + m * 2048 + k * 1024); } while (0)
; #define PG8_LDB(dst, b, h) do { _Pragma("unroll") for (int n = 0; n < 2; ++n) _Pragma("unroll") for (int k = 0; k < 2; ++k) dst[n][k] = *(const PG8_LAS bf16x8*)(lds + PG8_SB(b, h) + boff + n * 2048 + k * 1024); } while (0)
; #define PG8_MMA(ai, bj, At, Bt) do { __builtin_amdgcn_s_setprio(1); _Pragma("unroll") for (int m = 0; m < 4; ++m) _Pragma("unroll") for (int n = 0; n < 2; ++n) _Pragma("unroll") for (int k = 0; k < 2; ++k) \
;         acc[ai][bj][m][n] = __builtin_amdgcn_mfma_f32_16x16x32_bf16(Bt[n][k], At[m][k], acc[ai][bj][m][n], 0, 0, 0); __builtin_amdgcn_s_setprio(0); } while (0)
; #define PG8_BAR __builtin_amdgcn_s_barrier()
; template <class Epi, class Sched, bool ALIGN_EPI = false, bool SP2 = false>
; __device__ __forceinline__ void gemm_phase(PG8_LAS unsigned char* lds, const Gemm g, const Sched& S, const Epi& E) {
;     ...
;         const bool has_next = S.next(ui + 1, nxt);
;         const char* nA = has_next ? (const char*)g.A + (size_t)nxt.pm * tstep : cA; const char* nB = has_next ? (const char*)g.Bt + (size_t)nxt.pn * tstep : cB;
;         for (int t = 0; t < nt; t += 2) {
;             const bool last = (t == nt - 2);
;             const char* a1 = cA + (size_t)(t + 1) * kstep;
;             const char* a2 = last ? nA : cA + (size_t)(t + 2) * kstep; const char* b2 = last ? nB : cB + (size_t)(t + 2) * kstep;
;             const char* a3 = a2 + kstep; const char* b3 = b2 + kstep;
;             if (last && has_next) S.a_ready(nxt);
;             if constexpr (SP2) {
;             PG8_LDB(B0, 0, 0); PG8_LDB(B1, 0, 1); PG8_SCHED; PG8_LDA(At, 0, 0); PG8_STAGE(PG8_SA(1, 1), a1 + hstep, voffA);
;             PG8_WAIT_V(8); PG8_WAIT_L(0); PG8_BAR; PG8_MMA(0, 0, At, B0); PG8_MMA(0, 1, At, B1); PG8_BAR; PG8_SCHED;
;             PG8_LDA(At, 0, 1); PG8_STAGE(PG8_SB(0, 0), b2, voffB); PG8_STAGE(PG8_SB(0, 1), b2 + hstep, voffB); PG8_STAGE(PG8_SA(0, 0), a2, voffA);
.LBB0_1179:
	s_ashr_i32 s21, s20, 31
	s_lshl_b64 s[22:23], s[20:21], 20
	s_add_u32 s22, s56, s22
	s_addc_u32 s23, s57, s23
	s_and_b64 s[24:25], s[4:5], exec
	s_cselect_b32 s7, s23, s27
	s_cselect_b32 s21, s22, s26
	s_ashr_i32 s19, s18, 31
	s_lshl_b64 s[24:25], s[18:19], 20
	s_add_u32 s24, s68, s24
	s_addc_u32 s25, s69, s25
	s_and_b64 s[30:31], s[4:5], exec
	s_cselect_b32 s19, s25, s29
	s_cselect_b32 s46, s24, s28
	s_add_u32 s26, s26, 0x80080
	s_addc_u32 s27, s27, 0
	s_add_u32 s47, s28, 0x100
	s_addc_u32 s48, s29, 0
	s_mov_b32 s49, -2
	s_waitcnt lgkmcnt(0)
	ds_read_b128 v[128:131], v181
	ds_read_b128 v[132:135], v181 offset:1024
	ds_read_b128 v[136:139], v181 offset:2048
	ds_read_b128 v[140:143], v181 offset:3072
	ds_read_b128 v[144:147], v182
	ds_read_b128 v[148:151], v182 offset:1024
	ds_read_b128 v[168:171], v182 offset:2048
	ds_read_b128 v[172:175], v182 offset:3072
	s_add_u32 s28, s26, 0xfff80080
	s_addc_u32 s29, s27, -1
	s_cmp_eq_u32 s49, 28
	s_cselect_b32 s31, s7, s29
	s_cselect_b32 s30, s21, s28
	s_cselect_b32 s29, s19, s48
	s_cselect_b32 s28, s46, s47
	v_lshl_add_u64 v[176:177], s[26:27], 0, v[160:161]
	s_add_i32 m0, s35, 0xc000
	ds_read_b128 v[186:189], v183
	ds_read_b128 v[190:193], v183 offset:1024
	ds_read_b128 v[198:201], v183 offset:2048
	ds_read_b128 v[202:205], v183 offset:3072
	ds_read_b128 v[206:209], v183 offset:4096
	ds_read_b128 v[210:213], v183 offset:5120
	ds_read_b128 v[214:217], v183 offset:6144
	ds_read_b128 v[218:221], v183 offset:7168
	global_load_lds_dwordx4 v[176:177], off
	v_lshl_add_u64 v[176:177], s[26:27], 0, v[162:163]
	s_add_i32 m0, s35, 0xe000
	s_nop 0
	global_load_lds_dwordx4 v[176:177], off
	s_waitcnt vmcnt(8)
	s_waitcnt lgkmcnt(0)
	s_barrier
	s_setprio 1
	s_waitcnt lgkmcnt(0)
	v_mfma_f32_16x16x32_bf16 v[124:127], v[128:131], v[186:189], 0
	v_mfma_f32_16x16x32_bf16 v[120:123], v[136:139], v[186:189], 0
	v_mfma_f32_16x16x32_bf16 v[104:107], v[128:131], v[198:201], 0
	v_mfma_f32_16x16x32_bf16 v[108:111], v[136:139], v[198:201], 0
	v_mfma_f32_16x16x32_bf16 v[88:91], v[128:131], v[206:209], 0
	v_mfma_f32_16x16x32_bf16 v[92:95], v[136:139], v[206:209], 0
	v_mfma_f32_16x16x32_bf16 v[72:75], v[128:131], v[214:217], 0
	v_mfma_f32_16x16x32_bf16 v[76:79], v[136:139], v[214:217], 0
	v_mfma_f32_16x16x32_bf16 v[124:127], v[132:135], v[190:193], v[124:127]
	v_mfma_f32_16x16x32_bf16 v[120:123], v[140:143], v[190:193], v[120:123]
	v_mfma_f32_16x16x32_bf16 v[104:107], v[132:135], v[202:205], v[104:107]
	v_mfma_f32_16x16x32_bf16 v[108:111], v[140:143], v[202:205], v[108:111]
	v_mfma_f32_16x16x32_bf16 v[88:91], v[132:135], v[210:213], v[88:91]
	v_mfma_f32_16x16x32_bf16 v[92:95], v[140:143], v[210:213], v[92:95]
	v_mfma_f32_16x16x32_bf16 v[72:75], v[132:135], v[218:221], v[72:75]
	v_mfma_f32_16x16x32_bf16 v[76:79], v[140:143], v[218:221], v[76:79]
	s_setprio 0
	s_setprio 1
	v_mfma_f32_16x16x32_bf16 v[116:119], v[144:147], v[186:189], 0
	v_mfma_f32_16x16x32_bf16 v[112:115], v[168:171], v[186:189], 0
	v_mfma_f32_16x16x32_bf16 v[100:103], v[144:147], v[198:201], 0
	v_mfma_f32_16x16x32_bf16 v[96:99], v[168:171], v[198:201], 0
	v_mfma_f32_16x16x32_bf16 v[84:87], v[144:147], v[206:209], 0
	v_mfma_f32_16x16x32_bf16 v[80:83], v[168:171], v[206:209], 0
	v_mfma_f32_16x16x32_bf16 v[68:71], v[144:147], v[214:217], 0
	v_mfma_f32_16x16x32_bf16 v[64:67], v[168:171], v[214:217], 0
	v_mfma_f32_16x16x32_bf16 v[116:119], v[148:151], v[190:193], v[116:119]
	v_mfma_f32_16x16x32_bf16 v[112:115], v[172:175], v[190:193], v[112:115]
	v_mfma_f32_16x16x32_bf16 v[100:103], v[148:151], v[202:205], v[100:103]
	v_mfma_f32_16x16x32_bf16 v[96:99], v[172:175], v[202:205], v[96:99]
	v_mfma_f32_16x16x32_bf16 v[84:87], v[148:151], v[210:213], v[84:87]
	v_mfma_f32_16x16x32_bf16 v[80:83], v[172:175], v[210:213], v[80:83]
	v_mfma_f32_16x16x32_bf16 v[68:71], v[148:151], v[218:221], v[68:71]
	v_mfma_f32_16x16x32_bf16 v[64:67], v[172:175], v[218:221], v[64:67]
	s_setprio 0
	s_barrier
	s_add_i32 s50, s43, s34
	v_lshl_add_u64 v[176:177], s[28:29], 0, v[154:155]
	s_mov_b32 m0, s50
	ds_read_b128 v[186:189], v183 offset:16384
	ds_read_b128 v[190:193], v183 offset:17408
	ds_read_b128 v[198:201], v183 offset:18432
	ds_read_b128 v[202:205], v183 offset:19456
	ds_read_b128 v[206:209], v183 offset:20480
	ds_read_b128 v[210:213], v183 offset:21504
	ds_read_b128 v[214:217], v183 offset:22528
	ds_read_b128 v[218:221], v183 offset:23552
	global_load_lds_dwordx4 v[176:177], off
	s_add_i32 m0, s50, 0x2000
	s_add_u32 s50, s28, 0x80000
	v_lshl_add_u64 v[194:195], s[28:29], 0, v[158:159]
	s_addc_u32 s51, s29, 0
	s_add_i32 s52, s44, s34
	global_load_lds_dwordx4 v[194:195], off
	v_lshl_add_u64 v[222:223], s[50:51], 0, v[154:155]
	s_mov_b32 m0, s52
	v_lshl_add_u64 v[224:225], s[30:31], 0, v[156:157]
	global_load_lds_dwordx4 v[222:223], off
	v_lshl_add_u64 v[222:223], s[50:51], 0, v[158:159]
	s_add_i32 m0, s52, 0x2000
	s_nop 0
	global_load_lds_dwordx4 v[222:223], off
	v_lshl_add_u64 v[222:223], s[30:31], 0, v[152:153]
	s_mov_b32 m0, s35
	s_nop 0
	global_load_lds_dwordx4 v[222:223], off
	s_mov_b32 m0, s33
	s_nop 0
	global_load_lds_dwordx4 v[224:225], off
	s_waitcnt vmcnt(8)
	s_waitcnt lgkmcnt(0)
	s_barrier
; #define PG8_STAGE(bufoff, gbase, voff) do { _Pragma("unroll") for (int _i = 0; _i < 2; ++_i) \
;         __builtin_amdgcn_global_load_lds((const unsigned*)((const char*)(gbase) + (voff)[_i]), (PG8_LAS unsigned*)(lds + (bufoff) + ldsw + _i * 8192), 16, 0, 0); } while (0)
; #define PG8_LDA(dst, b, h) do { _Pragma("unroll") for (int m = 0; m < 4; ++m) _Pragma("unroll") for (int k = 0; k < 2; ++k) dst[m][k] = *(const PG8_LAS bf16x8*)(lds + PG8_SA(b, h) + aoff + m * 2048 + k * 1024); } while (0)
; #define PG8_LDB(dst, b, h) do { _Pragma("unroll") for (int n = 0; n < 2; ++n) _Pragma("unroll") for (int k = 0; k < 2; ++k) dst[n][k] = *(const PG8_LAS bf16x8*)(lds + PG8_SB(b, h) + boff + n * 2048 + k * 1024); } while (0)
; #define PG8_MMA(ai, bj, At, Bt) do { __builtin_amdgcn_s_setprio(1); _Pragma("unroll") for (int m = 0; m < 4; ++m) _Pragma("unroll") for (int n = 0; n < 2; ++n) _Pragma("unroll") for (int k = 0; k < 2; ++k) \
;         acc[ai][bj][m][n] = __builtin_amdgcn_mfma_f32_16x16x32_bf16(Bt[n][k], At[m][k], acc[ai][bj][m][n], 0, 0, 0); __builtin_amdgcn_s_setprio(0); } while (0)
; #define PG8_WAIT_V(n) asm volatile("s_waitcnt vmcnt(" #n ")" ::: "memory")
; #define PG8_WAIT_L(n) asm volatile("s_waitcnt lgkmcnt(" #n ")" ::: "memory")
; #define PG8_BAR __builtin_amdgcn_s_barrier()
; #define PG8_SCHED __builtin_amdgcn_sched_barrier(0)
; template <class Epi, class Sched, bool ALIGN_EPI = false, bool SP2 = false>
; __device__ __forceinline__ void gemm_phase(PG8_LAS unsigned char* lds, const Gemm g, const Sched& S, const Epi& E) {
;     ...
;             PG8_WAIT_V(8); PG8_WAIT_L(0); PG8_BAR; PG8_MMA(1, 0, At, B0); PG8_MMA(1, 1, At, B1); PG8_BAR; PG8_SCHED;
;             PG8_LDB(B0, 1, 0); PG8_LDB(B1, 1, 1); PG8_SCHED; PG8_LDA(At, 1, 0); PG8_STAGE(PG8_SA(0, 1), a2 + hstep, voffA);
;             PG8_WAIT_V(8); PG8_WAIT_L(0); PG8_BAR; PG8_MMA(0, 0, At, B0); PG8_MMA(0, 1, At, B1); PG8_BAR; PG8_SCHED;
	s_setprio 1
	s_waitcnt lgkmcnt(0)
	v_mfma_f32_16x16x32_bf16 v[56:59], v[128:131], v[186:189], 0
	v_mfma_f32_16x16x32_bf16 v[60:63], v[136:139], v[186:189], 0
	v_mfma_f32_16x16x32_bf16 v[40:43], v[128:131], v[198:201], 0
	v_mfma_f32_16x16x32_bf16 v[44:47], v[136:139], v[198:201], 0
	v_mfma_f32_16x16x32_bf16 v[24:27], v[128:131], v[206:209], 0
	v_mfma_f32_16x16x32_bf16 v[28:31], v[136:139], v[206:209], 0
	v_mfma_f32_16x16x32_bf16 v[8:11], v[128:131], v[214:217], 0
	v_mfma_f32_16x16x32_bf16 v[12:15], v[136:139], v[214:217], 0
	v_mfma_f32_16x16x32_bf16 v[56:59], v[132:135], v[190:193], v[56:59]
	v_mfma_f32_16x16x32_bf16 v[60:63], v[140:143], v[190:193], v[60:63]
	v_mfma_f32_16x16x32_bf16 v[40:43], v[132:135], v[202:205], v[40:43]
	v_mfma_f32_16x16x32_bf16 v[44:47], v[140:143], v[202:205], v[44:47]
	v_mfma_f32_16x16x32_bf16 v[24:27], v[132:135], v[210:213], v[24:27]
	v_mfma_f32_16x16x32_bf16 v[28:31], v[140:143], v[210:213], v[28:31]
	v_mfma_f32_16x16x32_bf16 v[8:11], v[132:135], v[218:221], v[8:11]
	v_mfma_f32_16x16x32_bf16 v[12:15], v[140:143], v[218:221], v[12:15]
	s_setprio 0
	s_setprio 1
	v_mfma_f32_16x16x32_bf16 v[52:55], v[144:147], v[186:189], 0
	v_mfma_f32_16x16x32_bf16 v[48:51], v[168:171], v[186:189], 0
	v_mfma_f32_16x16x32_bf16 v[36:39], v[144:147], v[198:201], 0
	v_mfma_f32_16x16x32_bf16 v[32:35], v[168:171], v[198:201], 0
	v_mfma_f32_16x16x32_bf16 v[20:23], v[144:147], v[206:209], 0
	v_mfma_f32_16x16x32_bf16 v[16:19], v[168:171], v[206:209], 0
	v_mfma_f32_16x16x32_bf16 v[4:7], v[144:147], v[214:217], 0
	v_mfma_f32_16x16x32_bf16 v[0:3], v[168:171], v[214:217], 0
	v_mfma_f32_16x16x32_bf16 v[52:55], v[148:151], v[190:193], v[52:55]
	v_mfma_f32_16x16x32_bf16 v[48:51], v[172:175], v[190:193], v[48:51]
	v_mfma_f32_16x16x32_bf16 v[36:39], v[148:151], v[202:205], v[36:39]
	v_mfma_f32_16x16x32_bf16 v[32:35], v[172:175], v[202:205], v[32:35]
	v_mfma_f32_16x16x32_bf16 v[20:23], v[148:151], v[210:213], v[20:23]
	v_mfma_f32_16x16x32_bf16 v[16:19], v[172:175], v[210:213], v[16:19]
	v_mfma_f32_16x16x32_bf16 v[4:7], v[148:151], v[218:221], v[4:7]
	v_mfma_f32_16x16x32_bf16 v[0:3], v[172:175], v[218:221], v[0:3]
	s_setprio 0
	s_barrier
	s_add_i32 s50, 0, 0x18000
	s_add_i32 s51, 0, 0x1c000
	v_add_u32_e32 v140, s50, v179
	v_add_u32_e32 v172, s51, v179
	ds_read_b128 v[128:131], v140
	ds_read_b128 v[132:135], v140 offset:1024
	ds_read_b128 v[136:139], v140 offset:2048
	ds_read_b128 v[140:143], v140 offset:3072
	ds_read_b128 v[144:147], v172
	ds_read_b128 v[148:151], v172 offset:1024
	ds_read_b128 v[168:171], v172 offset:2048
	ds_read_b128 v[172:175], v172 offset:3072
	s_add_u32 s30, s30, 0x80000
	s_addc_u32 s31, s31, 0
	s_mov_b32 m0, s36
	v_lshl_add_u64 v[226:227], s[30:31], 0, v[152:153]
	ds_read_b128 v[186:189], v183 offset:32768
	ds_read_b128 v[190:193], v183 offset:33792
	ds_read_b128 v[198:201], v183 offset:34816
	ds_read_b128 v[202:205], v183 offset:35840
	ds_read_b128 v[206:209], v183 offset:36864
	ds_read_b128 v[210:213], v183 offset:37888
	ds_read_b128 v[214:217], v183 offset:38912
	ds_read_b128 v[218:221], v183 offset:39936
	global_load_lds_dwordx4 v[226:227], off
	v_lshl_add_u64 v[226:227], s[30:31], 0, v[156:157]
	s_mov_b32 m0, s37
	s_nop 0
	global_load_lds_dwordx4 v[226:227], off
	s_waitcnt vmcnt(8)
	s_waitcnt lgkmcnt(0)
	s_barrier
	s_setprio 1
	s_waitcnt lgkmcnt(0)
	v_mfma_f32_16x16x32_bf16 v[124:127], v[128:131], v[186:189], v[124:127]
	v_mfma_f32_16x16x32_bf16 v[120:123], v[136:139], v[186:189], v[120:123]
	v_mfma_f32_16x16x32_bf16 v[104:107], v[128:131], v[198:201], v[104:107]
	v_mfma_f32_16x16x32_bf16 v[108:111], v[136:139], v[198:201], v[108:111]
	v_mfma_f32_16x16x32_bf16 v[88:91], v[128:131], v[206:209], v[88:91]
	v_mfma_f32_16x16x32_bf16 v[92:95], v[136:139], v[206:209], v[92:95]
	v_mfma_f32_16x16x32_bf16 v[72:75], v[128:131], v[214:217], v[72:75]
	v_mfma_f32_16x16x32_bf16 v[76:79], v[136:139], v[214:217], v[76:79]
	v_mfma_f32_16x16x32_bf16 v[124:127], v[132:135], v[190:193], v[124:127]
	v_mfma_f32_16x16x32_bf16 v[120:123], v[140:143], v[190:193], v[120:123]
	v_mfma_f32_16x16x32_bf16 v[104:107], v[132:135], v[202:205], v[104:107]
	v_mfma_f32_16x16x32_bf16 v[108:111], v[140:143], v[202:205], v[108:111]
	v_mfma_f32_16x16x32_bf16 v[88:91], v[132:135], v[210:213], v[88:91]
	v_mfma_f32_16x16x32_bf16 v[92:95], v[140:143], v[210:213], v[92:95]
	v_mfma_f32_16x16x32_bf16 v[72:75], v[132:135], v[218:221], v[72:75]
	v_mfma_f32_16x16x32_bf16 v[76:79], v[140:143], v[218:221], v[76:79]
	s_setprio 0
	s_setprio 1
	v_mfma_f32_16x16x32_bf16 v[116:119], v[144:147], v[186:189], v[116:119]
	v_mfma_f32_16x16x32_bf16 v[112:115], v[168:171], v[186:189], v[112:115]
	v_mfma_f32_16x16x32_bf16 v[100:103], v[144:147], v[198:201], v[100:103]
	v_mfma_f32_16x16x32_bf16 v[96:99], v[168:171], v[198:201], v[96:99]
	v_mfma_f32_16x16x32_bf16 v[84:87], v[144:147], v[206:209], v[84:87]
	v_mfma_f32_16x16x32_bf16 v[80:83], v[168:171], v[206:209], v[80:83]
	v_mfma_f32_16x16x32_bf16 v[68:71], v[144:147], v[214:217], v[68:71]
	v_mfma_f32_16x16x32_bf16 v[64:67], v[168:171], v[214:217], v[64:67]
	v_mfma_f32_16x16x32_bf16 v[116:119], v[148:151], v[190:193], v[116:119]
	v_mfma_f32_16x16x32_bf16 v[112:115], v[172:175], v[190:193], v[112:115]
	v_mfma_f32_16x16x32_bf16 v[100:103], v[148:151], v[202:205], v[100:103]
	v_mfma_f32_16x16x32_bf16 v[96:99], v[172:175], v[202:205], v[96:99]
	v_mfma_f32_16x16x32_bf16 v[84:87], v[148:151], v[210:213], v[84:87]
	v_mfma_f32_16x16x32_bf16 v[80:83], v[172:175], v[210:213], v[80:83]
	v_mfma_f32_16x16x32_bf16 v[68:71], v[148:151], v[218:221], v[68:71]
	v_mfma_f32_16x16x32_bf16 v[64:67], v[172:175], v[218:221], v[64:67]
	s_setprio 0
	s_barrier
; #define PG8_STAGE(bufoff, gbase, voff) do { _Pragma("unroll") for (int _i = 0; _i < 2; ++_i) \
;         __builtin_amdgcn_global_load_lds((const unsigned*)((const char*)(gbase) + (voff)[_i]), (PG8_LAS unsigned*)(lds + (bufoff) + ldsw + _i * 8192), 16, 0, 0); } while (0)
; #define PG8_LDA(dst, b, h) do { _Pragma("unroll") for (int m = 0; m < 4; ++m) _Pragma("unroll") for (int k = 0; k < 2; ++k) dst[m][k] = *(const PG8_LAS bf16x8*)(lds + PG8_SA(b, h) + aoff + m * 2048 + k * 1024); } while (0)
; #define PG8_MMA(ai, bj, At, Bt) do { __builtin_amdgcn_s_setprio(1); _Pragma("unroll") for (int m = 0; m < 4; ++m) _Pragma("unroll") for (int n = 0; n < 2; ++n) _Pragma("unroll") for (int k = 0; k < 2; ++k) \
;         acc[ai][bj][m][n] = __builtin_amdgcn_mfma_f32_16x16x32_bf16(Bt[n][k], At[m][k], acc[ai][bj][m][n], 0, 0, 0); __builtin_amdgcn_s_setprio(0); } while (0)
; #define PG8_WAIT_V(n) asm volatile("s_waitcnt vmcnt(" #n ")" ::: "memory")
; #define PG8_WAIT_L(n) asm volatile("s_waitcnt lgkmcnt(" #n ")" ::: "memory")
; #define PG8_BAR __builtin_amdgcn_s_barrier()
; #define PG8_SCHED __builtin_amdgcn_sched_barrier(0)
; template <class Epi, class Sched, bool ALIGN_EPI = false, bool SP2 = false>
; __device__ __forceinline__ void gemm_phase(PG8_LAS unsigned char* lds, const Gemm g, const Sched& S, const Epi& E) {
;     ...
;             PG8_LDA(At, 1, 1); PG8_STAGE(PG8_SB(1, 0), b3, voffB); PG8_STAGE(PG8_SB(1, 1), b3 + hstep, voffB); PG8_STAGE(PG8_SA(1, 0), a3, voffA);
;             PG8_WAIT_V(8); PG8_WAIT_L(0); PG8_BAR; PG8_MMA(1, 0, At, B0); PG8_MMA(1, 1, At, B1); PG8_BAR; PG8_SCHED;
	s_add_i32 s30, s50, s34
	v_lshl_add_u64 v[176:177], v[176:177], 0, s[12:13]
	s_mov_b32 m0, s30
	ds_read_b128 v[186:189], v183 offset:49152
	ds_read_b128 v[190:193], v183 offset:50176
	ds_read_b128 v[198:201], v183 offset:51200
	ds_read_b128 v[202:205], v183 offset:52224
	ds_read_b128 v[206:209], v183 offset:53248
	ds_read_b128 v[210:213], v183 offset:54272
	ds_read_b128 v[214:217], v183 offset:55296
	ds_read_b128 v[218:221], v183 offset:56320
	global_load_lds_dwordx4 v[176:177], off
	s_add_i32 m0, s30, 0x2000
	s_add_u32 s28, s28, 0x80080
	v_lshl_add_u64 v[176:177], v[194:195], 0, s[12:13]
	s_addc_u32 s29, s29, 0
	s_add_i32 s30, s51, s34
	global_load_lds_dwordx4 v[176:177], off
	v_lshl_add_u64 v[176:177], s[28:29], 0, v[154:155]
	s_mov_b32 m0, s30
	s_nop 0
	global_load_lds_dwordx4 v[176:177], off
	v_lshl_add_u64 v[176:177], s[28:29], 0, v[158:159]
	s_add_i32 m0, s30, 0x2000
	s_nop 0
	global_load_lds_dwordx4 v[176:177], off
	v_lshl_add_u64 v[176:177], v[222:223], 0, s[12:13]
	s_mov_b32 m0, s39
	s_nop 0
	global_load_lds_dwordx4 v[176:177], off
	v_lshl_add_u64 v[176:177], v[224:225], 0, s[12:13]
	s_mov_b32 m0, s40
	s_nop 0
	global_load_lds_dwordx4 v[176:177], off
	s_waitcnt vmcnt(8)
	s_waitcnt lgkmcnt(0)
	s_barrier
	s_setprio 1
	s_waitcnt lgkmcnt(0)
	v_mfma_f32_16x16x32_bf16 v[56:59], v[128:131], v[186:189], v[56:59]
	v_mfma_f32_16x16x32_bf16 v[60:63], v[136:139], v[186:189], v[60:63]
	v_mfma_f32_16x16x32_bf16 v[40:43], v[128:131], v[198:201], v[40:43]
	v_mfma_f32_16x16x32_bf16 v[44:47], v[136:139], v[198:201], v[44:47]
	v_mfma_f32_16x16x32_bf16 v[24:27], v[128:131], v[206:209], v[24:27]
	v_mfma_f32_16x16x32_bf16 v[28:31], v[136:139], v[206:209], v[28:31]
	v_mfma_f32_16x16x32_bf16 v[8:11], v[128:131], v[214:217], v[8:11]
	v_mfma_f32_16x16x32_bf16 v[12:15], v[136:139], v[214:217], v[12:15]
	v_mfma_f32_16x16x32_bf16 v[56:59], v[132:135], v[190:193], v[56:59]
	v_mfma_f32_16x16x32_bf16 v[60:63], v[140:143], v[190:193], v[60:63]
	v_mfma_f32_16x16x32_bf16 v[40:43], v[132:135], v[202:205], v[40:43]
	v_mfma_f32_16x16x32_bf16 v[44:47], v[140:143], v[202:205], v[44:47]
	v_mfma_f32_16x16x32_bf16 v[24:27], v[132:135], v[210:213], v[24:27]
	v_mfma_f32_16x16x32_bf16 v[28:31], v[140:143], v[210:213], v[28:31]
	v_mfma_f32_16x16x32_bf16 v[8:11], v[132:135], v[218:221], v[8:11]
	v_mfma_f32_16x16x32_bf16 v[12:15], v[140:143], v[218:221], v[12:15]
	s_setprio 0
	s_setprio 1
	v_mfma_f32_16x16x32_bf16 v[52:55], v[144:147], v[186:189], v[52:55]
	v_mfma_f32_16x16x32_bf16 v[48:51], v[168:171], v[186:189], v[48:51]
	v_mfma_f32_16x16x32_bf16 v[36:39], v[144:147], v[198:201], v[36:39]
	v_mfma_f32_16x16x32_bf16 v[32:35], v[168:171], v[198:201], v[32:35]
	v_mfma_f32_16x16x32_bf16 v[20:23], v[144:147], v[206:209], v[20:23]
	v_mfma_f32_16x16x32_bf16 v[16:19], v[168:171], v[206:209], v[16:19]
	v_mfma_f32_16x16x32_bf16 v[4:7], v[144:147], v[214:217], v[4:7]
	v_mfma_f32_16x16x32_bf16 v[0:3], v[168:171], v[214:217], v[0:3]
	v_mfma_f32_16x16x32_bf16 v[52:55], v[148:151], v[190:193], v[52:55]
	v_mfma_f32_16x16x32_bf16 v[48:51], v[172:175], v[190:193], v[48:51]
	v_mfma_f32_16x16x32_bf16 v[36:39], v[148:151], v[202:205], v[36:39]
	v_mfma_f32_16x16x32_bf16 v[32:35], v[172:175], v[202:205], v[32:35]
	v_mfma_f32_16x16x32_bf16 v[20:23], v[148:151], v[210:213], v[20:23]
	v_mfma_f32_16x16x32_bf16 v[16:19], v[172:175], v[210:213], v[16:19]
	v_mfma_f32_16x16x32_bf16 v[4:7], v[148:151], v[218:221], v[4:7]
	v_mfma_f32_16x16x32_bf16 v[0:3], v[172:175], v[218:221], v[0:3]
	s_setprio 0
	s_barrier
	s_add_i32 s49, s49, 2
	s_add_u32 s26, s26, 0x100
	s_addc_u32 s27, s27, 0
	s_add_u32 s47, s47, 0x100
	s_addc_u32 s48, s48, 0

; #define PG8_STAGE(bufoff, gbase, voff) do { _Pragma("unroll") for (int _i = 0; _i < 2; ++_i) \
;         __builtin_amdgcn_global_load_lds((const unsigned*)((const char*)(gbase) + (voff)[_i]), (PG8_LAS unsigned*)(lds + (bufoff) + ldsw + _i * 8192), 16, 0, 0); } while (0)
; #define PG8_LDA(dst, b, h) do { _Pragma("unroll") for (int m = 0; m < 4; ++m) _Pragma("unroll") for (int k = 0; k < 2; ++k) dst[m][k] = *(const PG8_LAS bf16x8*)(lds + PG8_SA(b, h) + aoff + m * 2048 + k * 1024); } while (0)
; #define PG8_LDB(dst, b, h) do { _Pragma("unroll") for (int n = 0; n < 2; ++n) _Pragma("unroll") for (int k = 0; k < 2; ++k) dst[n][k] = *(const PG8_LAS bf16x8*)(lds + PG8_SB(b, h) + boff + n * 2048 + k * 1024); } while (0)
; #define PG8_MMA(ai, bj, At, Bt) do { __builtin_amdgcn_s_setprio(1); _Pragma("unroll") for (int m = 0; m < 4; ++m) _Pragma("unroll") for (int n = 0; n < 2; ++n) _Pragma("unroll") for (int k = 0; k < 2; ++k) \
;         acc[ai][bj][m][n] = __builtin_amdgcn_mfma_f32_16x16x32_bf16(Bt[n][k], At[m][k], acc[ai][bj][m][n], 0, 0, 0); __builtin_amdgcn_s_setprio(0); } while (0)
; #define PG8_BAR __builtin_amdgcn_s_barrier()
; template <class Epi, class Sched, bool ALIGN_EPI = false, bool SP2 = false>
; __device__ __forceinline__ void gemm_phase(PG8_LAS unsigned char* lds, const Gemm g, const Sched& S, const Epi& E) {
;     ...
;         const bool has_next = S.next(ui + 1, nxt);
;         const char* nA = has_next ? (const char*)g.A + (size_t)nxt.pm * tstep : cA; const char* nB = has_next ? (const char*)g.Bt + (size_t)nxt.pn * tstep : cB;
;         for (int t = 0; t < nt; t += 2) {
;             const bool last = (t == nt - 2);
;             const char* a1 = cA + (size_t)(t + 1) * kstep;
;             const char* a2 = last ? nA : cA + (size_t)(t + 2) * kstep; const char* b2 = last ? nB : cB + (size_t)(t + 2) * kstep;
;             const char* a3 = a2 + kstep; const char* b3 = b2 + kstep;
;             if (last && has_next) S.a_ready(nxt);
;             if constexpr (SP2) {
;             PG8_LDB(B0, 0, 0); PG8_LDB(B1, 0, 1); PG8_SCHED; PG8_LDA(At, 0, 0); PG8_STAGE(PG8_SA(1, 1), a1 + hstep, voffA);
;             PG8_WAIT_V(8); PG8_WAIT_L(0); PG8_BAR; PG8_MMA(0, 0, At, B0); PG8_MMA(0, 1, At, B1); PG8_BAR; PG8_SCHED;
;             PG8_LDA(At, 0, 1); PG8_STAGE(PG8_SB(0, 0), b2, voffB); PG8_STAGE(PG8_SB(0, 1), b2 + hstep, voffB); PG8_STAGE(PG8_SA(0, 0), a2, voffA);
.LBB0_1372:
	s_ashr_i32 s29, s28, 31
	s_lshl_b64 s[34:35], s[28:29], 20
	s_add_u32 s34, s74, s34
	s_addc_u32 s35, s75, s35
	s_and_b64 s[36:37], s[30:31], exec
	s_cselect_b32 s29, s35, s9
	s_cselect_b32 s39, s34, s8
	s_ashr_i32 s27, s26, 31
	s_lshl_b64 s[36:37], s[26:27], 20
	v_readlane_b32 s44, v254, 22
	v_readlane_b32 s45, v254, 23
	s_add_u32 s36, s44, s36
	s_addc_u32 s37, s45, s37
	s_and_b64 s[44:45], s[30:31], exec
	s_cselect_b32 s27, s37, s43
	s_cselect_b32 s41, s36, s42
	s_add_u32 s8, s8, 0x80080
	s_addc_u32 s9, s9, 0
	s_add_u32 s48, s42, 0x100
	s_addc_u32 s49, s43, 0
	s_mov_b32 s66, -2
	ds_read_b128 v[108:111], v173
	ds_read_b128 v[112:115], v173 offset:1024
	ds_read_b128 v[116:119], v173 offset:2048
	ds_read_b128 v[120:123], v173 offset:3072
	ds_read_b128 v[178:181], v175
	ds_read_b128 v[182:185], v175 offset:1024
	ds_read_b128 v[186:189], v175 offset:2048
	ds_read_b128 v[190:193], v175 offset:3072
	s_add_u32 s42, s8, 0xfff80080
	s_addc_u32 s43, s9, -1
	s_cmp_eq_u32 s66, 28
	s_cselect_b32 s45, s29, s43
	s_cselect_b32 s44, s39, s42
	s_cselect_b32 s43, s27, s49
	s_cselect_b32 s42, s41, s48
	v_lshl_add_u64 v[160:161], s[8:9], 0, v[154:155]
	s_add_i32 m0, s50, 0xc000
	ds_read_b128 v[198:201], v177
	ds_read_b128 v[202:205], v177 offset:1024
	ds_read_b128 v[206:209], v177 offset:2048
	ds_read_b128 v[210:213], v177 offset:3072
	ds_read_b128 v[214:217], v177 offset:4096
	ds_read_b128 v[218:221], v177 offset:5120
	ds_read_b128 v[222:225], v177 offset:6144
	ds_read_b128 v[226:229], v177 offset:7168
	global_load_lds_dwordx4 v[160:161], off
	v_lshl_add_u64 v[160:161], s[8:9], 0, v[156:157]
	s_add_i32 m0, s50, 0xe000
	s_nop 0
	global_load_lds_dwordx4 v[160:161], off
	s_waitcnt vmcnt(8)
	s_waitcnt lgkmcnt(0)
	s_barrier
	s_setprio 1
	s_waitcnt lgkmcnt(0)
	v_mfma_f32_16x16x32_bf16 v[140:143], v[108:111], v[198:201], 0
	v_mfma_f32_16x16x32_bf16 v[136:139], v[116:119], v[198:201], 0
	v_mfma_f32_16x16x32_bf16 v[100:103], v[108:111], v[206:209], 0
	v_mfma_f32_16x16x32_bf16 v[124:127], v[116:119], v[206:209], 0
	v_mfma_f32_16x16x32_bf16 v[84:87], v[108:111], v[214:217], 0
	v_mfma_f32_16x16x32_bf16 v[92:95], v[116:119], v[214:217], 0
	v_mfma_f32_16x16x32_bf16 v[68:71], v[108:111], v[222:225], 0
	v_mfma_f32_16x16x32_bf16 v[76:79], v[116:119], v[222:225], 0
	v_mfma_f32_16x16x32_bf16 v[140:143], v[112:115], v[202:205], v[140:143]
	v_mfma_f32_16x16x32_bf16 v[136:139], v[120:123], v[202:205], v[136:139]
	v_mfma_f32_16x16x32_bf16 v[100:103], v[112:115], v[210:213], v[100:103]
	v_mfma_f32_16x16x32_bf16 v[124:127], v[120:123], v[210:213], v[124:127]
	v_mfma_f32_16x16x32_bf16 v[84:87], v[112:115], v[218:221], v[84:87]
	v_mfma_f32_16x16x32_bf16 v[92:95], v[120:123], v[218:221], v[92:95]
	v_mfma_f32_16x16x32_bf16 v[68:71], v[112:115], v[226:229], v[68:71]
	v_mfma_f32_16x16x32_bf16 v[76:79], v[120:123], v[226:229], v[76:79]
	s_setprio 0
	s_setprio 1
	v_mfma_f32_16x16x32_bf16 v[128:131], v[178:181], v[198:201], 0
	v_mfma_f32_16x16x32_bf16 v[132:135], v[186:189], v[198:201], 0
	v_mfma_f32_16x16x32_bf16 v[104:107], v[178:181], v[206:209], 0
	v_mfma_f32_16x16x32_bf16 v[96:99], v[186:189], v[206:209], 0
	v_mfma_f32_16x16x32_bf16 v[88:91], v[178:181], v[214:217], 0
	v_mfma_f32_16x16x32_bf16 v[80:83], v[186:189], v[214:217], 0
	v_mfma_f32_16x16x32_bf16 v[72:75], v[178:181], v[222:225], 0
	v_mfma_f32_16x16x32_bf16 v[64:67], v[186:189], v[222:225], 0
	v_mfma_f32_16x16x32_bf16 v[128:131], v[182:185], v[202:205], v[128:131]
	v_mfma_f32_16x16x32_bf16 v[132:135], v[190:193], v[202:205], v[132:135]
	v_mfma_f32_16x16x32_bf16 v[104:107], v[182:185], v[210:213], v[104:107]
	v_mfma_f32_16x16x32_bf16 v[96:99], v[190:193], v[210:213], v[96:99]
	v_mfma_f32_16x16x32_bf16 v[88:91], v[182:185], v[218:221], v[88:91]
	v_mfma_f32_16x16x32_bf16 v[80:83], v[190:193], v[218:221], v[80:83]
	v_mfma_f32_16x16x32_bf16 v[72:75], v[182:185], v[226:229], v[72:75]
	v_mfma_f32_16x16x32_bf16 v[64:67], v[190:193], v[226:229], v[64:67]
	s_setprio 0
	s_barrier
	s_add_i32 s67, s62, s47
	v_lshl_add_u64 v[160:161], s[42:43], 0, v[144:145]
	s_mov_b32 m0, s67
	ds_read_b128 v[198:201], v177 offset:16384
	ds_read_b128 v[202:205], v177 offset:17408
	ds_read_b128 v[206:209], v177 offset:18432
	ds_read_b128 v[210:213], v177 offset:19456
	ds_read_b128 v[214:217], v177 offset:20480
	ds_read_b128 v[218:221], v177 offset:21504
	ds_read_b128 v[222:225], v177 offset:22528
	ds_read_b128 v[226:229], v177 offset:23552
	global_load_lds_dwordx4 v[160:161], off
	s_add_i32 m0, s67, 0x2000
	s_add_u32 s68, s42, 0x80000
	v_lshl_add_u64 v[164:165], s[42:43], 0, v[146:147]
	s_addc_u32 s69, s43, 0
	s_add_i32 s67, s63, s47
	global_load_lds_dwordx4 v[164:165], off
	v_lshl_add_u64 v[170:171], s[68:69], 0, v[144:145]
	s_mov_b32 m0, s67
	v_lshl_add_u64 v[194:195], s[44:45], 0, v[146:147]
	global_load_lds_dwordx4 v[170:171], off
	v_lshl_add_u64 v[170:171], s[68:69], 0, v[146:147]
	s_add_i32 m0, s67, 0x2000
	s_nop 0
	global_load_lds_dwordx4 v[170:171], off
	v_lshl_add_u64 v[170:171], s[44:45], 0, v[144:145]
	s_mov_b32 m0, s50
	s_nop 0
	global_load_lds_dwordx4 v[170:171], off
	s_mov_b32 m0, s51
	s_nop 0
	global_load_lds_dwordx4 v[194:195], off
	s_waitcnt vmcnt(8)
	s_waitcnt lgkmcnt(0)
	s_barrier
; #define PG8_STAGE(bufoff, gbase, voff) do { _Pragma("unroll") for (int _i = 0; _i < 2; ++_i) \
;         __builtin_amdgcn_global_load_lds((const unsigned*)((const char*)(gbase) + (voff)[_i]), (PG8_LAS unsigned*)(lds + (bufoff) + ldsw + _i * 8192), 16, 0, 0); } while (0)
; #define PG8_LDA(dst, b, h) do { _Pragma("unroll") for (int m = 0; m < 4; ++m) _Pragma("unroll") for (int k = 0; k < 2; ++k) dst[m][k] = *(const PG8_LAS bf16x8*)(lds + PG8_SA(b, h) + aoff + m * 2048 + k * 1024); } while (0)
; #define PG8_LDB(dst, b, h) do { _Pragma("unroll") for (int n = 0; n < 2; ++n) _Pragma("unroll") for (int k = 0; k < 2; ++k) dst[n][k] = *(const PG8_LAS bf16x8*)(lds + PG8_SB(b, h) + boff + n * 2048 + k * 1024); } while (0)
; #define PG8_MMA(ai, bj, At, Bt) do { __builtin_amdgcn_s_setprio(1); _Pragma("unroll") for (int m = 0; m < 4; ++m) _Pragma("unroll") for (int n = 0; n < 2; ++n) _Pragma("unroll") for (int k = 0; k < 2; ++k) \
;         acc[ai][bj][m][n] = __builtin_amdgcn_mfma_f32_16x16x32_bf16(Bt[n][k], At[m][k], acc[ai][bj][m][n], 0, 0, 0); __builtin_amdgcn_s_setprio(0); } while (0)
; #define PG8_WAIT_V(n) asm volatile("s_waitcnt vmcnt(" #n ")" ::: "memory")
; #define PG8_WAIT_L(n) asm volatile("s_waitcnt lgkmcnt(" #n ")" ::: "memory")
; #define PG8_BAR __builtin_amdgcn_s_barrier()
; #define PG8_SCHED __builtin_amdgcn_sched_barrier(0)
; template <class Epi, class Sched, bool ALIGN_EPI = false, bool SP2 = false>
; __device__ __forceinline__ void gemm_phase(PG8_LAS unsigned char* lds, const Gemm g, const Sched& S, const Epi& E) {
;     ...
;             PG8_WAIT_V(8); PG8_WAIT_L(0); PG8_BAR; PG8_MMA(1, 0, At, B0); PG8_MMA(1, 1, At, B1); PG8_BAR; PG8_SCHED;
;             PG8_LDB(B0, 1, 0); PG8_LDB(B1, 1, 1); PG8_SCHED; PG8_LDA(At, 1, 0); PG8_STAGE(PG8_SA(0, 1), a2 + hstep, voffA);
;             PG8_WAIT_V(8); PG8_WAIT_L(0); PG8_BAR; PG8_MMA(0, 0, At, B0); PG8_MMA(0, 1, At, B1); PG8_BAR; PG8_SCHED;
	s_setprio 1
	s_waitcnt lgkmcnt(0)
	v_mfma_f32_16x16x32_bf16 v[60:63], v[108:111], v[198:201], 0
	v_mfma_f32_16x16x32_bf16 v[56:59], v[116:119], v[198:201], 0
	v_mfma_f32_16x16x32_bf16 v[36:39], v[108:111], v[206:209], 0
	v_mfma_f32_16x16x32_bf16 v[44:47], v[116:119], v[206:209], 0
	v_mfma_f32_16x16x32_bf16 v[20:23], v[108:111], v[214:217], 0
	v_mfma_f32_16x16x32_bf16 v[28:31], v[116:119], v[214:217], 0
	v_mfma_f32_16x16x32_bf16 v[4:7], v[108:111], v[222:225], 0
	v_mfma_f32_16x16x32_bf16 v[12:15], v[116:119], v[222:225], 0
	v_mfma_f32_16x16x32_bf16 v[60:63], v[112:115], v[202:205], v[60:63]
	v_mfma_f32_16x16x32_bf16 v[56:59], v[120:123], v[202:205], v[56:59]
	v_mfma_f32_16x16x32_bf16 v[36:39], v[112:115], v[210:213], v[36:39]
	v_mfma_f32_16x16x32_bf16 v[44:47], v[120:123], v[210:213], v[44:47]
	v_mfma_f32_16x16x32_bf16 v[20:23], v[112:115], v[218:221], v[20:23]
	v_mfma_f32_16x16x32_bf16 v[28:31], v[120:123], v[218:221], v[28:31]
	v_mfma_f32_16x16x32_bf16 v[4:7], v[112:115], v[226:229], v[4:7]
	v_mfma_f32_16x16x32_bf16 v[12:15], v[120:123], v[226:229], v[12:15]
	s_setprio 0
	s_setprio 1
	v_mfma_f32_16x16x32_bf16 v[48:51], v[178:181], v[198:201], 0
	v_mfma_f32_16x16x32_bf16 v[52:55], v[186:189], v[198:201], 0
	v_mfma_f32_16x16x32_bf16 v[40:43], v[178:181], v[206:209], 0
	v_mfma_f32_16x16x32_bf16 v[32:35], v[186:189], v[206:209], 0
	v_mfma_f32_16x16x32_bf16 v[24:27], v[178:181], v[214:217], 0
	v_mfma_f32_16x16x32_bf16 v[16:19], v[186:189], v[214:217], 0
	v_mfma_f32_16x16x32_bf16 v[8:11], v[178:181], v[222:225], 0
	v_mfma_f32_16x16x32_bf16 v[0:3], v[186:189], v[222:225], 0
	v_mfma_f32_16x16x32_bf16 v[48:51], v[182:185], v[202:205], v[48:51]
	v_mfma_f32_16x16x32_bf16 v[52:55], v[190:193], v[202:205], v[52:55]
	v_mfma_f32_16x16x32_bf16 v[40:43], v[182:185], v[210:213], v[40:43]
	v_mfma_f32_16x16x32_bf16 v[32:35], v[190:193], v[210:213], v[32:35]
	v_mfma_f32_16x16x32_bf16 v[24:27], v[182:185], v[218:221], v[24:27]
	v_mfma_f32_16x16x32_bf16 v[16:19], v[190:193], v[218:221], v[16:19]
	v_mfma_f32_16x16x32_bf16 v[8:11], v[182:185], v[226:229], v[8:11]
	v_mfma_f32_16x16x32_bf16 v[0:3], v[190:193], v[226:229], v[0:3]
	s_setprio 0
	s_barrier
	s_add_i32 s67, 0, 0x18000
	s_add_i32 s68, 0, 0x1c000
	v_add_u32_e32 v120, s67, v167
	v_add_u32_e32 v162, s68, v167
	ds_read_b128 v[108:111], v120
	ds_read_b128 v[112:115], v120 offset:1024
	ds_read_b128 v[116:119], v120 offset:2048
	ds_read_b128 v[120:123], v120 offset:3072
	ds_read_b128 v[178:181], v162
	ds_read_b128 v[182:185], v162 offset:1024
	ds_read_b128 v[186:189], v162 offset:2048
	ds_read_b128 v[190:193], v162 offset:3072
	s_add_u32 s44, s44, 0x80000
	s_addc_u32 s45, s45, 0
	s_mov_b32 m0, s52
	v_lshl_add_u64 v[230:231], s[44:45], 0, v[144:145]
	ds_read_b128 v[198:201], v177 offset:32768
	ds_read_b128 v[202:205], v177 offset:33792
	ds_read_b128 v[206:209], v177 offset:34816
	ds_read_b128 v[210:213], v177 offset:35840
	ds_read_b128 v[214:217], v177 offset:36864
	ds_read_b128 v[218:221], v177 offset:37888
	ds_read_b128 v[222:225], v177 offset:38912
	ds_read_b128 v[226:229], v177 offset:39936
	global_load_lds_dwordx4 v[230:231], off
	v_lshl_add_u64 v[230:231], s[44:45], 0, v[146:147]
	s_mov_b32 m0, s53
	s_nop 0
	global_load_lds_dwordx4 v[230:231], off
	s_waitcnt vmcnt(8)
	s_waitcnt lgkmcnt(0)
	s_barrier
	s_setprio 1
	s_waitcnt lgkmcnt(0)
	v_mfma_f32_16x16x32_bf16 v[140:143], v[108:111], v[198:201], v[140:143]
	v_mfma_f32_16x16x32_bf16 v[136:139], v[116:119], v[198:201], v[136:139]
	v_mfma_f32_16x16x32_bf16 v[100:103], v[108:111], v[206:209], v[100:103]
	v_mfma_f32_16x16x32_bf16 v[124:127], v[116:119], v[206:209], v[124:127]
	v_mfma_f32_16x16x32_bf16 v[84:87], v[108:111], v[214:217], v[84:87]
	v_mfma_f32_16x16x32_bf16 v[92:95], v[116:119], v[214:217], v[92:95]
	v_mfma_f32_16x16x32_bf16 v[68:71], v[108:111], v[222:225], v[68:71]
	v_mfma_f32_16x16x32_bf16 v[76:79], v[116:119], v[222:225], v[76:79]
	v_mfma_f32_16x16x32_bf16 v[140:143], v[112:115], v[202:205], v[140:143]
	v_mfma_f32_16x16x32_bf16 v[136:139], v[120:123], v[202:205], v[136:139]
	v_mfma_f32_16x16x32_bf16 v[100:103], v[112:115], v[210:213], v[100:103]
	v_mfma_f32_16x16x32_bf16 v[124:127], v[120:123], v[210:213], v[124:127]
	v_mfma_f32_16x16x32_bf16 v[84:87], v[112:115], v[218:221], v[84:87]
	v_mfma_f32_16x16x32_bf16 v[92:95], v[120:123], v[218:221], v[92:95]
	v_mfma_f32_16x16x32_bf16 v[68:71], v[112:115], v[226:229], v[68:71]
	v_mfma_f32_16x16x32_bf16 v[76:79], v[120:123], v[226:229], v[76:79]
	s_setprio 0
	s_setprio 1
	v_mfma_f32_16x16x32_bf16 v[128:131], v[178:181], v[198:201], v[128:131]
	v_mfma_f32_16x16x32_bf16 v[132:135], v[186:189], v[198:201], v[132:135]
	v_mfma_f32_16x16x32_bf16 v[104:107], v[178:181], v[206:209], v[104:107]
	v_mfma_f32_16x16x32_bf16 v[96:99], v[186:189], v[206:209], v[96:99]
	v_mfma_f32_16x16x32_bf16 v[88:91], v[178:181], v[214:217], v[88:91]
	v_mfma_f32_16x16x32_bf16 v[80:83], v[186:189], v[214:217], v[80:83]
	v_mfma_f32_16x16x32_bf16 v[72:75], v[178:181], v[222:225], v[72:75]
	v_mfma_f32_16x16x32_bf16 v[64:67], v[186:189], v[222:225], v[64:67]
	v_mfma_f32_16x16x32_bf16 v[128:131], v[182:185], v[202:205], v[128:131]
	v_mfma_f32_16x16x32_bf16 v[132:135], v[190:193], v[202:205], v[132:135]
	v_mfma_f32_16x16x32_bf16 v[104:107], v[182:185], v[210:213], v[104:107]
	v_mfma_f32_16x16x32_bf16 v[96:99], v[190:193], v[210:213], v[96:99]
	v_mfma_f32_16x16x32_bf16 v[88:91], v[182:185], v[218:221], v[88:91]
	v_mfma_f32_16x16x32_bf16 v[80:83], v[190:193], v[218:221], v[80:83]
	v_mfma_f32_16x16x32_bf16 v[72:75], v[182:185], v[226:229], v[72:75]
	v_mfma_f32_16x16x32_bf16 v[64:67], v[190:193], v[226:229], v[64:67]
	s_setprio 0
	s_barrier
; #define PG8_STAGE(bufoff, gbase, voff) do { _Pragma("unroll") for (int _i = 0; _i < 2; ++_i) \
;         __builtin_amdgcn_global_load_lds((const unsigned*)((const char*)(gbase) + (voff)[_i]), (PG8_LAS unsigned*)(lds + (bufoff) + ldsw + _i * 8192), 16, 0, 0); } while (0)
; #define PG8_LDA(dst, b, h) do { _Pragma("unroll") for (int m = 0; m < 4; ++m) _Pragma("unroll") for (int k = 0; k < 2; ++k) dst[m][k] = *(const PG8_LAS bf16x8*)(lds + PG8_SA(b, h) + aoff + m * 2048 + k * 1024); } while (0)
; #define PG8_MMA(ai, bj, At, Bt) do { __builtin_amdgcn_s_setprio(1); _Pragma("unroll") for (int m = 0; m < 4; ++m) _Pragma("unroll") for (int n = 0; n < 2; ++n) _Pragma("unroll") for (int k = 0; k < 2; ++k) \
;         acc[ai][bj][m][n] = __builtin_amdgcn_mfma_f32_16x16x32_bf16(Bt[n][k], At[m][k], acc[ai][bj][m][n], 0, 0, 0); __builtin_amdgcn_s_setprio(0); } while (0)
; #define PG8_WAIT_V(n) asm volatile("s_waitcnt vmcnt(" #n ")" ::: "memory")
; #define PG8_WAIT_L(n) asm volatile("s_waitcnt lgkmcnt(" #n ")" ::: "memory")
; #define PG8_BAR __builtin_amdgcn_s_barrier()
; #define PG8_SCHED __builtin_amdgcn_sched_barrier(0)
; template <class Epi, class Sched, bool ALIGN_EPI = false, bool SP2 = false>
; __device__ __forceinline__ void gemm_phase(PG8_LAS unsigned char* lds, const Gemm g, const Sched& S, const Epi& E) {
;     ...
;             PG8_LDA(At, 1, 1); PG8_STAGE(PG8_SB(1, 0), b3, voffB); PG8_STAGE(PG8_SB(1, 1), b3 + hstep, voffB); PG8_STAGE(PG8_SA(1, 0), a3, voffA);
;             PG8_WAIT_V(8); PG8_WAIT_L(0); PG8_BAR; PG8_MMA(1, 0, At, B0); PG8_MMA(1, 1, At, B1); PG8_BAR; PG8_SCHED;
	s_add_i32 s44, s67, s47
	v_lshl_add_u64 v[160:161], v[160:161], 0, s[16:17]
	s_mov_b32 m0, s44
	ds_read_b128 v[198:201], v177 offset:49152
	ds_read_b128 v[202:205], v177 offset:50176
	ds_read_b128 v[206:209], v177 offset:51200
	ds_read_b128 v[210:213], v177 offset:52224
	ds_read_b128 v[214:217], v177 offset:53248
	ds_read_b128 v[218:221], v177 offset:54272
	ds_read_b128 v[222:225], v177 offset:55296
	ds_read_b128 v[226:229], v177 offset:56320
	global_load_lds_dwordx4 v[160:161], off
	s_add_i32 m0, s44, 0x2000
	s_add_u32 s42, s42, 0x80080
	v_lshl_add_u64 v[160:161], v[164:165], 0, s[16:17]
	s_addc_u32 s43, s43, 0
	s_add_i32 s44, s68, s47
	global_load_lds_dwordx4 v[160:161], off
	v_lshl_add_u64 v[160:161], s[42:43], 0, v[144:145]
	s_mov_b32 m0, s44
	s_nop 0
	global_load_lds_dwordx4 v[160:161], off
	v_lshl_add_u64 v[160:161], s[42:43], 0, v[146:147]
	s_add_i32 m0, s44, 0x2000
	s_nop 0
	global_load_lds_dwordx4 v[160:161], off
	v_lshl_add_u64 v[160:161], v[170:171], 0, s[16:17]
	s_mov_b32 m0, s55
	s_nop 0
	global_load_lds_dwordx4 v[160:161], off
	v_lshl_add_u64 v[160:161], v[194:195], 0, s[16:17]
	s_mov_b32 m0, s56
	s_nop 0
	global_load_lds_dwordx4 v[160:161], off
	s_waitcnt vmcnt(8)
	s_waitcnt lgkmcnt(0)
	s_barrier
	s_setprio 1
	s_waitcnt lgkmcnt(0)
	v_mfma_f32_16x16x32_bf16 v[60:63], v[108:111], v[198:201], v[60:63]
	v_mfma_f32_16x16x32_bf16 v[56:59], v[116:119], v[198:201], v[56:59]
	v_mfma_f32_16x16x32_bf16 v[36:39], v[108:111], v[206:209], v[36:39]
	v_mfma_f32_16x16x32_bf16 v[44:47], v[116:119], v[206:209], v[44:47]
	v_mfma_f32_16x16x32_bf16 v[20:23], v[108:111], v[214:217], v[20:23]
	v_mfma_f32_16x16x32_bf16 v[28:31], v[116:119], v[214:217], v[28:31]
	v_mfma_f32_16x16x32_bf16 v[4:7], v[108:111], v[222:225], v[4:7]
	v_mfma_f32_16x16x32_bf16 v[12:15], v[116:119], v[222:225], v[12:15]
	v_mfma_f32_16x16x32_bf16 v[60:63], v[112:115], v[202:205], v[60:63]
	v_mfma_f32_16x16x32_bf16 v[56:59], v[120:123], v[202:205], v[56:59]
	v_mfma_f32_16x16x32_bf16 v[36:39], v[112:115], v[210:213], v[36:39]
	v_mfma_f32_16x16x32_bf16 v[44:47], v[120:123], v[210:213], v[44:47]
	v_mfma_f32_16x16x32_bf16 v[20:23], v[112:115], v[218:221], v[20:23]
	v_mfma_f32_16x16x32_bf16 v[28:31], v[120:123], v[218:221], v[28:31]
	v_mfma_f32_16x16x32_bf16 v[4:7], v[112:115], v[226:229], v[4:7]
	v_mfma_f32_16x16x32_bf16 v[12:15], v[120:123], v[226:229], v[12:15]
	s_setprio 0
	s_setprio 1
	v_mfma_f32_16x16x32_bf16 v[48:51], v[178:181], v[198:201], v[48:51]
	v_mfma_f32_16x16x32_bf16 v[52:55], v[186:189], v[198:201], v[52:55]
	v_mfma_f32_16x16x32_bf16 v[40:43], v[178:181], v[206:209], v[40:43]
	v_mfma_f32_16x16x32_bf16 v[32:35], v[186:189], v[206:209], v[32:35]
	v_mfma_f32_16x16x32_bf16 v[24:27], v[178:181], v[214:217], v[24:27]
	v_mfma_f32_16x16x32_bf16 v[16:19], v[186:189], v[214:217], v[16:19]
	v_mfma_f32_16x16x32_bf16 v[8:11], v[178:181], v[222:225], v[8:11]
	v_mfma_f32_16x16x32_bf16 v[0:3], v[186:189], v[222:225], v[0:3]
	v_mfma_f32_16x16x32_bf16 v[48:51], v[182:185], v[202:205], v[48:51]
	v_mfma_f32_16x16x32_bf16 v[52:55], v[190:193], v[202:205], v[52:55]
	v_mfma_f32_16x16x32_bf16 v[40:43], v[182:185], v[210:213], v[40:43]
	v_mfma_f32_16x16x32_bf16 v[32:35], v[190:193], v[210:213], v[32:35]
	v_mfma_f32_16x16x32_bf16 v[24:27], v[182:185], v[218:221], v[24:27]
	v_mfma_f32_16x16x32_bf16 v[16:19], v[190:193], v[218:221], v[16:19]
	v_mfma_f32_16x16x32_bf16 v[8:11], v[182:185], v[226:229], v[8:11]
	v_mfma_f32_16x16x32_bf16 v[0:3], v[190:193], v[226:229], v[0:3]
	s_setprio 0
	s_barrier
	s_add_i32 s66, s66, 2
	s_add_u32 s8, s8, 0x100
	s_addc_u32 s9, s9, 0
	s_add_u32 s48, s48, 0x100
	s_addc_u32 s49, s49, 0

; #define PG8_STAGE(bufoff, gbase, voff) do { _Pragma("unroll") for (int _i = 0; _i < 2; ++_i) \
;         __builtin_amdgcn_global_load_lds((const unsigned*)((const char*)(gbase) + (voff)[_i]), (PG8_LAS unsigned*)(lds + (bufoff) + ldsw + _i * 8192), 16, 0, 0); } while (0)
; #define PG8_LDA(dst, b, h) do { _Pragma("unroll") for (int m = 0; m < 4; ++m) _Pragma("unroll") for (int k = 0; k < 2; ++k) dst[m][k] = *(const PG8_LAS bf16x8*)(lds + PG8_SA(b, h) + aoff + m * 2048 + k * 1024); } while (0)
; #define PG8_LDB(dst, b, h) do { _Pragma("unroll") for (int n = 0; n < 2; ++n) _Pragma("unroll") for (int k = 0; k < 2; ++k) dst[n][k] = *(const PG8_LAS bf16x8*)(lds + PG8_SB(b, h) + boff + n * 2048 + k * 1024); } while (0)
; #define PG8_MMA(ai, bj, At, Bt) do { __builtin_amdgcn_s_setprio(1); _Pragma("unroll") for (int m = 0; m < 4; ++m) _Pragma("unroll") for (int n = 0; n < 2; ++n) _Pragma("unroll") for (int k = 0; k < 2; ++k) \
;         acc[ai][bj][m][n] = __builtin_amdgcn_mfma_f32_16x16x32_bf16(Bt[n][k], At[m][k], acc[ai][bj][m][n], 0, 0, 0); __builtin_amdgcn_s_setprio(0); } while (0)
; #define PG8_BAR __builtin_amdgcn_s_barrier()
; template <class Epi, class Sched, bool ALIGN_EPI = false, bool SP2 = false>
; __device__ __forceinline__ void gemm_phase(PG8_LAS unsigned char* lds, const Gemm g, const Sched& S, const Epi& E) {
;     ...
;         const bool has_next = S.next(ui + 1, nxt);
;         const char* nA = has_next ? (const char*)g.A + (size_t)nxt.pm * tstep : cA; const char* nB = has_next ? (const char*)g.Bt + (size_t)nxt.pn * tstep : cB;
;         for (int t = 0; t < nt; t += 2) {
;             const bool last = (t == nt - 2);
;             const char* a1 = cA + (size_t)(t + 1) * kstep;
;             const char* a2 = last ? nA : cA + (size_t)(t + 2) * kstep; const char* b2 = last ? nB : cB + (size_t)(t + 2) * kstep;
;             const char* a3 = a2 + kstep; const char* b3 = b2 + kstep;
;             if (last && has_next) S.a_ready(nxt);
;             if constexpr (SP2) {
;             PG8_LDB(B0, 0, 0); PG8_LDB(B1, 0, 1); PG8_SCHED; PG8_LDA(At, 0, 0); PG8_STAGE(PG8_SA(1, 1), a1 + hstep, voffA);
;             PG8_WAIT_V(8); PG8_WAIT_L(0); PG8_BAR; PG8_MMA(0, 0, At, B0); PG8_MMA(0, 1, At, B1); PG8_BAR; PG8_SCHED;
;             PG8_LDA(At, 0, 1); PG8_STAGE(PG8_SB(0, 0), b2, voffB); PG8_STAGE(PG8_SB(0, 1), b2 + hstep, voffB); PG8_STAGE(PG8_SA(0, 0), a2, voffA);
.LBB0_1548:
	s_ashr_i32 s13, s12, 31
	s_lshl_b64 s[14:15], s[12:13], 20
	s_add_u32 s14, s60, s14
	s_addc_u32 s15, s61, s15
	s_and_b64 s[16:17], s[0:1], exec
	s_cselect_b32 s13, s15, s21
	s_cselect_b32 s39, s14, s20
	s_ashr_i32 s11, s10, 31
	s_lshl_b64 s[16:17], s[10:11], 20
	s_add_u32 s16, s72, s16
	s_addc_u32 s17, s73, s17
	s_and_b64 s[24:25], s[0:1], exec
	s_cselect_b32 s11, s17, s23
	s_cselect_b32 s40, s16, s22
	s_add_u32 s20, s20, 0x80080
	s_addc_u32 s21, s21, 0
	s_add_u32 s41, s22, 0x100
	s_addc_u32 s42, s23, 0
	s_mov_b32 s43, -2
	ds_read_b128 v[144:147], v155
	ds_read_b128 v[148:151], v155 offset:1024
	ds_read_b128 v[158:161], v155 offset:2048
	ds_read_b128 v[162:165], v155 offset:3072
	ds_read_b128 v[166:169], v156
	ds_read_b128 v[170:173], v156 offset:1024
	ds_read_b128 v[174:177], v156 offset:2048
	ds_read_b128 v[178:181], v156 offset:3072
	s_add_u32 s22, s20, 0xfff80080
	s_addc_u32 s23, s21, -1
	s_cmp_eq_u32 s43, 28
	s_cselect_b32 s25, s13, s23
	s_cselect_b32 s24, s39, s22
	s_cselect_b32 s23, s11, s42
	s_cselect_b32 s22, s40, s41
	v_lshl_add_u64 v[214:215], s[20:21], 0, v[136:137]
	s_add_i32 m0, s19, 0xc000
	ds_read_b128 v[182:185], v157
	ds_read_b128 v[186:189], v157 offset:1024
	ds_read_b128 v[190:193], v157 offset:2048
	ds_read_b128 v[194:197], v157 offset:3072
	ds_read_b128 v[198:201], v157 offset:4096
	ds_read_b128 v[202:205], v157 offset:5120
	ds_read_b128 v[206:209], v157 offset:6144
	ds_read_b128 v[210:213], v157 offset:7168
	global_load_lds_dwordx4 v[214:215], off
	v_lshl_add_u64 v[214:215], s[20:21], 0, v[138:139]
	s_add_i32 m0, s19, 0xe000
	s_nop 0
	global_load_lds_dwordx4 v[214:215], off
	s_waitcnt vmcnt(8)
	s_waitcnt lgkmcnt(0)
	s_barrier
	s_setprio 1
	s_waitcnt lgkmcnt(0)
	v_mfma_f32_16x16x32_bf16 v[124:127], v[144:147], v[182:185], 0
	v_mfma_f32_16x16x32_bf16 v[120:123], v[158:161], v[182:185], 0
	v_mfma_f32_16x16x32_bf16 v[108:111], v[144:147], v[190:193], 0
	v_mfma_f32_16x16x32_bf16 v[104:107], v[158:161], v[190:193], 0
	v_mfma_f32_16x16x32_bf16 v[88:91], v[144:147], v[198:201], 0
	v_mfma_f32_16x16x32_bf16 v[92:95], v[158:161], v[198:201], 0
	v_mfma_f32_16x16x32_bf16 v[72:75], v[144:147], v[206:209], 0
	v_mfma_f32_16x16x32_bf16 v[76:79], v[158:161], v[206:209], 0
	v_mfma_f32_16x16x32_bf16 v[124:127], v[148:151], v[186:189], v[124:127]
	v_mfma_f32_16x16x32_bf16 v[120:123], v[162:165], v[186:189], v[120:123]
	v_mfma_f32_16x16x32_bf16 v[108:111], v[148:151], v[194:197], v[108:111]
	v_mfma_f32_16x16x32_bf16 v[104:107], v[162:165], v[194:197], v[104:107]
	v_mfma_f32_16x16x32_bf16 v[88:91], v[148:151], v[202:205], v[88:91]
	v_mfma_f32_16x16x32_bf16 v[92:95], v[162:165], v[202:205], v[92:95]
	v_mfma_f32_16x16x32_bf16 v[72:75], v[148:151], v[210:213], v[72:75]
	v_mfma_f32_16x16x32_bf16 v[76:79], v[162:165], v[210:213], v[76:79]
	s_setprio 0
	s_setprio 1
	v_mfma_f32_16x16x32_bf16 v[116:119], v[166:169], v[182:185], 0
	v_mfma_f32_16x16x32_bf16 v[112:115], v[174:177], v[182:185], 0
	v_mfma_f32_16x16x32_bf16 v[96:99], v[166:169], v[190:193], 0
	v_mfma_f32_16x16x32_bf16 v[100:103], v[174:177], v[190:193], 0
	v_mfma_f32_16x16x32_bf16 v[80:83], v[166:169], v[198:201], 0
	v_mfma_f32_16x16x32_bf16 v[84:87], v[174:177], v[198:201], 0
	v_mfma_f32_16x16x32_bf16 v[64:67], v[166:169], v[206:209], 0
	v_mfma_f32_16x16x32_bf16 v[68:71], v[174:177], v[206:209], 0
	v_mfma_f32_16x16x32_bf16 v[116:119], v[170:173], v[186:189], v[116:119]
	v_mfma_f32_16x16x32_bf16 v[112:115], v[178:181], v[186:189], v[112:115]
	v_mfma_f32_16x16x32_bf16 v[96:99], v[170:173], v[194:197], v[96:99]
	v_mfma_f32_16x16x32_bf16 v[100:103], v[178:181], v[194:197], v[100:103]
	v_mfma_f32_16x16x32_bf16 v[80:83], v[170:173], v[202:205], v[80:83]
	v_mfma_f32_16x16x32_bf16 v[84:87], v[178:181], v[202:205], v[84:87]
	v_mfma_f32_16x16x32_bf16 v[64:67], v[170:173], v[210:213], v[64:67]
	v_mfma_f32_16x16x32_bf16 v[68:71], v[178:181], v[210:213], v[68:71]
	s_setprio 0
	s_barrier
	s_add_i32 s44, s36, s27
	v_lshl_add_u64 v[214:215], s[22:23], 0, v[130:131]
	s_mov_b32 m0, s44
	ds_read_b128 v[182:185], v157 offset:16384
	ds_read_b128 v[186:189], v157 offset:17408
	ds_read_b128 v[190:193], v157 offset:18432
	ds_read_b128 v[194:197], v157 offset:19456
	ds_read_b128 v[198:201], v157 offset:20480
	ds_read_b128 v[202:205], v157 offset:21504
	ds_read_b128 v[206:209], v157 offset:22528
	ds_read_b128 v[210:213], v157 offset:23552
	global_load_lds_dwordx4 v[214:215], off
	s_add_i32 m0, s44, 0x2000
	s_add_u32 s44, s22, 0x80000
	v_lshl_add_u64 v[216:217], s[22:23], 0, v[134:135]
	s_addc_u32 s45, s23, 0
	s_add_i32 s46, s37, s27
	global_load_lds_dwordx4 v[216:217], off
	v_lshl_add_u64 v[218:219], s[44:45], 0, v[130:131]
	s_mov_b32 m0, s46
	v_lshl_add_u64 v[220:221], s[24:25], 0, v[132:133]
	global_load_lds_dwordx4 v[218:219], off
	v_lshl_add_u64 v[218:219], s[44:45], 0, v[134:135]
	s_add_i32 m0, s46, 0x2000
	s_nop 0
	global_load_lds_dwordx4 v[218:219], off
	v_lshl_add_u64 v[218:219], s[24:25], 0, v[128:129]
	s_mov_b32 m0, s19
	s_nop 0
	global_load_lds_dwordx4 v[218:219], off
	s_mov_b32 m0, s28
	s_nop 0
	global_load_lds_dwordx4 v[220:221], off
	s_waitcnt vmcnt(8)
	s_waitcnt lgkmcnt(0)
	s_barrier
; #define PG8_STAGE(bufoff, gbase, voff) do { _Pragma("unroll") for (int _i = 0; _i < 2; ++_i) \
;         __builtin_amdgcn_global_load_lds((const unsigned*)((const char*)(gbase) + (voff)[_i]), (PG8_LAS unsigned*)(lds + (bufoff) + ldsw + _i * 8192), 16, 0, 0); } while (0)
; #define PG8_LDA(dst, b, h) do { _Pragma("unroll") for (int m = 0; m < 4; ++m) _Pragma("unroll") for (int k = 0; k < 2; ++k) dst[m][k] = *(const PG8_LAS bf16x8*)(lds + PG8_SA(b, h) + aoff + m * 2048 + k * 1024); } while (0)
; #define PG8_LDB(dst, b, h) do { _Pragma("unroll") for (int n = 0; n < 2; ++n) _Pragma("unroll") for (int k = 0; k < 2; ++k) dst[n][k] = *(const PG8_LAS bf16x8*)(lds + PG8_SB(b, h) + boff + n * 2048 + k * 1024); } while (0)
; #define PG8_MMA(ai, bj, At, Bt) do { __builtin_amdgcn_s_setprio(1); _Pragma("unroll") for (int m = 0; m < 4; ++m) _Pragma("unroll") for (int n = 0; n < 2; ++n) _Pragma("unroll") for (int k = 0; k < 2; ++k) \
;         acc[ai][bj][m][n] = __builtin_amdgcn_mfma_f32_16x16x32_bf16(Bt[n][k], At[m][k], acc[ai][bj][m][n], 0, 0, 0); __builtin_amdgcn_s_setprio(0); } while (0)
; #define PG8_WAIT_V(n) asm volatile("s_waitcnt vmcnt(" #n ")" ::: "memory")
; #define PG8_WAIT_L(n) asm volatile("s_waitcnt lgkmcnt(" #n ")" ::: "memory")
; #define PG8_BAR __builtin_amdgcn_s_barrier()
; #define PG8_SCHED __builtin_amdgcn_sched_barrier(0)
; template <class Epi, class Sched, bool ALIGN_EPI = false, bool SP2 = false>
; __device__ __forceinline__ void gemm_phase(PG8_LAS unsigned char* lds, const Gemm g, const Sched& S, const Epi& E) {
;     ...
;             PG8_WAIT_V(8); PG8_WAIT_L(0); PG8_BAR; PG8_MMA(1, 0, At, B0); PG8_MMA(1, 1, At, B1); PG8_BAR; PG8_SCHED;
;             PG8_LDB(B0, 1, 0); PG8_LDB(B1, 1, 1); PG8_SCHED; PG8_LDA(At, 1, 0); PG8_STAGE(PG8_SA(0, 1), a2 + hstep, voffA);
;             PG8_WAIT_V(8); PG8_WAIT_L(0); PG8_BAR; PG8_MMA(0, 0, At, B0); PG8_MMA(0, 1, At, B1); PG8_BAR; PG8_SCHED;
	s_setprio 1
	s_waitcnt lgkmcnt(0)
	v_mfma_f32_16x16x32_bf16 v[56:59], v[144:147], v[182:185], 0
	v_mfma_f32_16x16x32_bf16 v[60:63], v[158:161], v[182:185], 0
	v_mfma_f32_16x16x32_bf16 v[40:43], v[144:147], v[190:193], 0
	v_mfma_f32_16x16x32_bf16 v[44:47], v[158:161], v[190:193], 0
	v_mfma_f32_16x16x32_bf16 v[24:27], v[144:147], v[198:201], 0
	v_mfma_f32_16x16x32_bf16 v[28:31], v[158:161], v[198:201], 0
	v_mfma_f32_16x16x32_bf16 v[8:11], v[144:147], v[206:209], 0
	v_mfma_f32_16x16x32_bf16 v[12:15], v[158:161], v[206:209], 0
	v_mfma_f32_16x16x32_bf16 v[56:59], v[148:151], v[186:189], v[56:59]
	v_mfma_f32_16x16x32_bf16 v[60:63], v[162:165], v[186:189], v[60:63]
	v_mfma_f32_16x16x32_bf16 v[40:43], v[148:151], v[194:197], v[40:43]
	v_mfma_f32_16x16x32_bf16 v[44:47], v[162:165], v[194:197], v[44:47]
	v_mfma_f32_16x16x32_bf16 v[24:27], v[148:151], v[202:205], v[24:27]
	v_mfma_f32_16x16x32_bf16 v[28:31], v[162:165], v[202:205], v[28:31]
	v_mfma_f32_16x16x32_bf16 v[8:11], v[148:151], v[210:213], v[8:11]
	v_mfma_f32_16x16x32_bf16 v[12:15], v[162:165], v[210:213], v[12:15]
	s_setprio 0
	s_setprio 1
	v_mfma_f32_16x16x32_bf16 v[48:51], v[166:169], v[182:185], 0
	v_mfma_f32_16x16x32_bf16 v[52:55], v[174:177], v[182:185], 0
	v_mfma_f32_16x16x32_bf16 v[32:35], v[166:169], v[190:193], 0
	v_mfma_f32_16x16x32_bf16 v[36:39], v[174:177], v[190:193], 0
	v_mfma_f32_16x16x32_bf16 v[16:19], v[166:169], v[198:201], 0
	v_mfma_f32_16x16x32_bf16 v[20:23], v[174:177], v[198:201], 0
	v_mfma_f32_16x16x32_bf16 v[0:3], v[166:169], v[206:209], 0
	v_mfma_f32_16x16x32_bf16 v[4:7], v[174:177], v[206:209], 0
	v_mfma_f32_16x16x32_bf16 v[48:51], v[170:173], v[186:189], v[48:51]
	v_mfma_f32_16x16x32_bf16 v[52:55], v[178:181], v[186:189], v[52:55]
	v_mfma_f32_16x16x32_bf16 v[32:35], v[170:173], v[194:197], v[32:35]
	v_mfma_f32_16x16x32_bf16 v[36:39], v[178:181], v[194:197], v[36:39]
	v_mfma_f32_16x16x32_bf16 v[16:19], v[170:173], v[202:205], v[16:19]
	v_mfma_f32_16x16x32_bf16 v[20:23], v[178:181], v[202:205], v[20:23]
	v_mfma_f32_16x16x32_bf16 v[0:3], v[170:173], v[210:213], v[0:3]
	v_mfma_f32_16x16x32_bf16 v[4:7], v[178:181], v[210:213], v[4:7]
	s_setprio 0
	s_barrier
	s_add_i32 s44, 0, 0x18000
	s_add_i32 s45, 0, 0x1c000
	v_add_u32_e32 v162, s44, v153
	v_add_u32_e32 v178, s45, v153
	ds_read_b128 v[144:147], v162
	ds_read_b128 v[148:151], v162 offset:1024
	ds_read_b128 v[158:161], v162 offset:2048
	ds_read_b128 v[162:165], v162 offset:3072
	ds_read_b128 v[166:169], v178
	ds_read_b128 v[170:173], v178 offset:1024
	ds_read_b128 v[174:177], v178 offset:2048
	ds_read_b128 v[178:181], v178 offset:3072
	s_add_u32 s24, s24, 0x80000
	s_addc_u32 s25, s25, 0
	s_mov_b32 m0, s29
	v_lshl_add_u64 v[222:223], s[24:25], 0, v[128:129]
	ds_read_b128 v[182:185], v157 offset:32768
	ds_read_b128 v[186:189], v157 offset:33792
	ds_read_b128 v[190:193], v157 offset:34816
	ds_read_b128 v[194:197], v157 offset:35840
	ds_read_b128 v[198:201], v157 offset:36864
	ds_read_b128 v[202:205], v157 offset:37888
	ds_read_b128 v[206:209], v157 offset:38912
	ds_read_b128 v[210:213], v157 offset:39936
	global_load_lds_dwordx4 v[222:223], off
	v_lshl_add_u64 v[222:223], s[24:25], 0, v[132:133]
	s_mov_b32 m0, s30
	s_nop 0
	global_load_lds_dwordx4 v[222:223], off
	s_waitcnt vmcnt(8)
	s_waitcnt lgkmcnt(0)
	s_barrier
	s_setprio 1
	s_waitcnt lgkmcnt(0)
	v_mfma_f32_16x16x32_bf16 v[124:127], v[144:147], v[182:185], v[124:127]
	v_mfma_f32_16x16x32_bf16 v[120:123], v[158:161], v[182:185], v[120:123]
	v_mfma_f32_16x16x32_bf16 v[108:111], v[144:147], v[190:193], v[108:111]
	v_mfma_f32_16x16x32_bf16 v[104:107], v[158:161], v[190:193], v[104:107]
	v_mfma_f32_16x16x32_bf16 v[88:91], v[144:147], v[198:201], v[88:91]
	v_mfma_f32_16x16x32_bf16 v[92:95], v[158:161], v[198:201], v[92:95]
	v_mfma_f32_16x16x32_bf16 v[72:75], v[144:147], v[206:209], v[72:75]
	v_mfma_f32_16x16x32_bf16 v[76:79], v[158:161], v[206:209], v[76:79]
	v_mfma_f32_16x16x32_bf16 v[124:127], v[148:151], v[186:189], v[124:127]
	v_mfma_f32_16x16x32_bf16 v[120:123], v[162:165], v[186:189], v[120:123]
	v_mfma_f32_16x16x32_bf16 v[108:111], v[148:151], v[194:197], v[108:111]
	v_mfma_f32_16x16x32_bf16 v[104:107], v[162:165], v[194:197], v[104:107]
	v_mfma_f32_16x16x32_bf16 v[88:91], v[148:151], v[202:205], v[88:91]
	v_mfma_f32_16x16x32_bf16 v[92:95], v[162:165], v[202:205], v[92:95]
	v_mfma_f32_16x16x32_bf16 v[72:75], v[148:151], v[210:213], v[72:75]
	v_mfma_f32_16x16x32_bf16 v[76:79], v[162:165], v[210:213], v[76:79]
	s_setprio 0
	s_setprio 1
	v_mfma_f32_16x16x32_bf16 v[116:119], v[166:169], v[182:185], v[116:119]
	v_mfma_f32_16x16x32_bf16 v[112:115], v[174:177], v[182:185], v[112:115]
	v_mfma_f32_16x16x32_bf16 v[96:99], v[166:169], v[190:193], v[96:99]
	v_mfma_f32_16x16x32_bf16 v[100:103], v[174:177], v[190:193], v[100:103]
	v_mfma_f32_16x16x32_bf16 v[80:83], v[166:169], v[198:201], v[80:83]
	v_mfma_f32_16x16x32_bf16 v[84:87], v[174:177], v[198:201], v[84:87]
	v_mfma_f32_16x16x32_bf16 v[64:67], v[166:169], v[206:209], v[64:67]
	v_mfma_f32_16x16x32_bf16 v[68:71], v[174:177], v[206:209], v[68:71]
	v_mfma_f32_16x16x32_bf16 v[116:119], v[170:173], v[186:189], v[116:119]
	v_mfma_f32_16x16x32_bf16 v[112:115], v[178:181], v[186:189], v[112:115]
	v_mfma_f32_16x16x32_bf16 v[96:99], v[170:173], v[194:197], v[96:99]
	v_mfma_f32_16x16x32_bf16 v[100:103], v[178:181], v[194:197], v[100:103]
	v_mfma_f32_16x16x32_bf16 v[80:83], v[170:173], v[202:205], v[80:83]
	v_mfma_f32_16x16x32_bf16 v[84:87], v[178:181], v[202:205], v[84:87]
	v_mfma_f32_16x16x32_bf16 v[64:67], v[170:173], v[210:213], v[64:67]
	v_mfma_f32_16x16x32_bf16 v[68:71], v[178:181], v[210:213], v[68:71]
	s_setprio 0
	s_barrier
; #define PG8_STAGE(bufoff, gbase, voff) do { _Pragma("unroll") for (int _i = 0; _i < 2; ++_i) \
;         __builtin_amdgcn_global_load_lds((const unsigned*)((const char*)(gbase) + (voff)[_i]), (PG8_LAS unsigned*)(lds + (bufoff) + ldsw + _i * 8192), 16, 0, 0); } while (0)
; #define PG8_LDA(dst, b, h) do { _Pragma("unroll") for (int m = 0; m < 4; ++m) _Pragma("unroll") for (int k = 0; k < 2; ++k) dst[m][k] = *(const PG8_LAS bf16x8*)(lds + PG8_SA(b, h) + aoff + m * 2048 + k * 1024); } while (0)
; #define PG8_MMA(ai, bj, At, Bt) do { __builtin_amdgcn_s_setprio(1); _Pragma("unroll") for (int m = 0; m < 4; ++m) _Pragma("unroll") for (int n = 0; n < 2; ++n) _Pragma("unroll") for (int k = 0; k < 2; ++k) \
;         acc[ai][bj][m][n] = __builtin_amdgcn_mfma_f32_16x16x32_bf16(Bt[n][k], At[m][k], acc[ai][bj][m][n], 0, 0, 0); __builtin_amdgcn_s_setprio(0); } while (0)
; #define PG8_WAIT_V(n) asm volatile("s_waitcnt vmcnt(" #n ")" ::: "memory")
; #define PG8_WAIT_L(n) asm volatile("s_waitcnt lgkmcnt(" #n ")" ::: "memory")
; #define PG8_BAR __builtin_amdgcn_s_barrier()
; #define PG8_SCHED __builtin_amdgcn_sched_barrier(0)
; template <class Epi, class Sched, bool ALIGN_EPI = false, bool SP2 = false>
; __device__ __forceinline__ void gemm_phase(PG8_LAS unsigned char* lds, const Gemm g, const Sched& S, const Epi& E) {
;     ...
;             PG8_LDA(At, 1, 1); PG8_STAGE(PG8_SB(1, 0), b3, voffB); PG8_STAGE(PG8_SB(1, 1), b3 + hstep, voffB); PG8_STAGE(PG8_SA(1, 0), a3, voffA);
;             PG8_WAIT_V(8); PG8_WAIT_L(0); PG8_BAR; PG8_MMA(1, 0, At, B0); PG8_MMA(1, 1, At, B1); PG8_BAR; PG8_SCHED;
	s_add_i32 s24, s44, s27
	v_lshl_add_u64 v[214:215], v[214:215], 0, s[4:5]
	s_mov_b32 m0, s24
	ds_read_b128 v[182:185], v157 offset:49152
	ds_read_b128 v[186:189], v157 offset:50176
	ds_read_b128 v[190:193], v157 offset:51200
	ds_read_b128 v[194:197], v157 offset:52224
	ds_read_b128 v[198:201], v157 offset:53248
	ds_read_b128 v[202:205], v157 offset:54272
	ds_read_b128 v[206:209], v157 offset:55296
	ds_read_b128 v[210:213], v157 offset:56320
	global_load_lds_dwordx4 v[214:215], off
	s_add_i32 m0, s24, 0x2000
	s_add_u32 s22, s22, 0x80080
	v_lshl_add_u64 v[214:215], v[216:217], 0, s[4:5]
	s_addc_u32 s23, s23, 0
	s_add_i32 s24, s45, s27
	global_load_lds_dwordx4 v[214:215], off
	v_lshl_add_u64 v[214:215], s[22:23], 0, v[130:131]
	s_mov_b32 m0, s24
	s_nop 0
	global_load_lds_dwordx4 v[214:215], off
	v_lshl_add_u64 v[214:215], s[22:23], 0, v[134:135]
	s_add_i32 m0, s24, 0x2000
	s_nop 0
	global_load_lds_dwordx4 v[214:215], off
	v_lshl_add_u64 v[214:215], v[218:219], 0, s[4:5]
	s_mov_b32 m0, s33
	s_nop 0
	global_load_lds_dwordx4 v[214:215], off
	v_lshl_add_u64 v[214:215], v[220:221], 0, s[4:5]
	s_mov_b32 m0, s34
	s_nop 0
	global_load_lds_dwordx4 v[214:215], off
	s_waitcnt vmcnt(8)
	s_waitcnt lgkmcnt(0)
	s_barrier
	s_setprio 1
	s_waitcnt lgkmcnt(0)
	v_mfma_f32_16x16x32_bf16 v[56:59], v[144:147], v[182:185], v[56:59]
	v_mfma_f32_16x16x32_bf16 v[60:63], v[158:161], v[182:185], v[60:63]
	v_mfma_f32_16x16x32_bf16 v[40:43], v[144:147], v[190:193], v[40:43]
	v_mfma_f32_16x16x32_bf16 v[44:47], v[158:161], v[190:193], v[44:47]
	v_mfma_f32_16x16x32_bf16 v[24:27], v[144:147], v[198:201], v[24:27]
	v_mfma_f32_16x16x32_bf16 v[28:31], v[158:161], v[198:201], v[28:31]
	v_mfma_f32_16x16x32_bf16 v[8:11], v[144:147], v[206:209], v[8:11]
	v_mfma_f32_16x16x32_bf16 v[12:15], v[158:161], v[206:209], v[12:15]
	v_mfma_f32_16x16x32_bf16 v[56:59], v[148:151], v[186:189], v[56:59]
	v_mfma_f32_16x16x32_bf16 v[60:63], v[162:165], v[186:189], v[60:63]
	v_mfma_f32_16x16x32_bf16 v[40:43], v[148:151], v[194:197], v[40:43]
	v_mfma_f32_16x16x32_bf16 v[44:47], v[162:165], v[194:197], v[44:47]
	v_mfma_f32_16x16x32_bf16 v[24:27], v[148:151], v[202:205], v[24:27]
	v_mfma_f32_16x16x32_bf16 v[28:31], v[162:165], v[202:205], v[28:31]
	v_mfma_f32_16x16x32_bf16 v[8:11], v[148:151], v[210:213], v[8:11]
	v_mfma_f32_16x16x32_bf16 v[12:15], v[162:165], v[210:213], v[12:15]
	s_setprio 0
	s_setprio 1
	v_mfma_f32_16x16x32_bf16 v[48:51], v[166:169], v[182:185], v[48:51]
	v_mfma_f32_16x16x32_bf16 v[52:55], v[174:177], v[182:185], v[52:55]
	v_mfma_f32_16x16x32_bf16 v[32:35], v[166:169], v[190:193], v[32:35]
	v_mfma_f32_16x16x32_bf16 v[36:39], v[174:177], v[190:193], v[36:39]
	v_mfma_f32_16x16x32_bf16 v[16:19], v[166:169], v[198:201], v[16:19]
	v_mfma_f32_16x16x32_bf16 v[20:23], v[174:177], v[198:201], v[20:23]
	v_mfma_f32_16x16x32_bf16 v[0:3], v[166:169], v[206:209], v[0:3]
	v_mfma_f32_16x16x32_bf16 v[4:7], v[174:177], v[206:209], v[4:7]
	v_mfma_f32_16x16x32_bf16 v[48:51], v[170:173], v[186:189], v[48:51]
	v_mfma_f32_16x16x32_bf16 v[52:55], v[178:181], v[186:189], v[52:55]
	v_mfma_f32_16x16x32_bf16 v[32:35], v[170:173], v[194:197], v[32:35]
	v_mfma_f32_16x16x32_bf16 v[36:39], v[178:181], v[194:197], v[36:39]
	v_mfma_f32_16x16x32_bf16 v[16:19], v[170:173], v[202:205], v[16:19]
	v_mfma_f32_16x16x32_bf16 v[20:23], v[178:181], v[202:205], v[20:23]
	v_mfma_f32_16x16x32_bf16 v[0:3], v[170:173], v[210:213], v[0:3]
	v_mfma_f32_16x16x32_bf16 v[4:7], v[178:181], v[210:213], v[4:7]
	s_setprio 0
	s_barrier
	s_add_i32 s43, s43, 2
	s_add_u32 s20, s20, 0x100
	s_addc_u32 s21, s21, 0
	s_add_u32 s41, s41, 0x100
	s_addc_u32 s42, s42, 0
